# GEMM tile seams (tail end, cross-tile prefetch, rstd, epilogue stores, next prologue) run at raised wave priority; k-loop priorities unchanged
# speedup vs baseline: 1.0229x; 1.0074x over previous
; #define G_LOAD(kt_) do { \
;     if constexpr (AF32) { _Pragma("unroll") for (int i = 0; i < 4; ++i) ld16_sc1(ra[i], Af + (size_t)i * 32 * lda + (kt_) * 32); } \
;     else { _Pragma("unroll") for (int i = 0; i < 2; ++i) ld16_sc1(rab[i], Ab + (size_t)i * 64 * lda + (kt_) * 32); } \
;     _Pragma("unroll") for (int i = 0; i < 4; ++i) ld16_sc1(rb[i], Bp + (size_t)(kt_) * bstep + i * 2048); } while (0)
; template <bool AF32, class Epi>
; __device__ __forceinline__ void gemm_tile(unsigned char* smem, const void* Ap, int lda, const bf16_t* WT, int N, int K, const Epi& epi, int m0, int n0,
;                                           GPre& pr, bool preloaded, const void* nAp, int nn0, bool has_next) {
;     ...
;   if (!preloaded) G_LOAD(0);
;   G_STORE(0);
;   if (nk > 1) G_LOAD(1);
;   __syncthreads();
;   for (int kt = 0; kt < nk; ++kt) {
;     const int cur = kt & 1;
;     if (kt + 1 < nk) G_STORE(cur ^ 1);
;     if (kt + 2 < nk) G_LOAD(kt + 2);
;     const bf16_t* a_s = sbase + cur * G_STAGE + (wr * 64 + l15) * GLD + quad * 8;
;     const bf16_t* b_s = sbase + cur * G_STAGE + 128 * GLD + (wc * 128 + l15) * GLD + quad * 8;
;     __builtin_amdgcn_s_setprio(1);
;     bf16x8 af[4];
; #pragma unroll
;     for (int m = 0; m < 4; ++m) af[m] = *(const bf16x8*)(a_s + m * 16 * GLD);
; #pragma unroll
;     for (int nh = 0; nh < 4; ++nh) {
;       bf16x8 bfr[2];
; #pragma unroll
;       for (int n2 = 0; n2 < 2; ++n2) bfr[n2] = *(const bf16x8*)(b_s + (nh * 2 + n2) * 16 * GLD);
; #pragma unroll
;       for (int m = 0; m < 4; ++m)
; #pragma unroll
;         for (int n2 = 0; n2 < 2; ++n2) acc[m][nh * 2 + n2] = __builtin_amdgcn_mfma_f32_16x16x32_bf16(bfr[n2], af[m], acc[m][nh * 2 + n2], 0, 0, 0);
;     }
;     __builtin_amdgcn_s_setprio(0);
;     __syncthreads();
;   }
.LBB0_265:
	s_and_b32 s3, s54, 1
	s_waitcnt vmcnt(0)
	s_xor_b32 s55, s3, 1
	s_mulk_i32 s55, 0x7800
	v_add_u32_e32 v176, s55, v155
	ds_write_b128 v176, v[0:3]
	ds_write_b128 v176, v[4:7] offset:5120
	ds_write_b128 v176, v[8:11] offset:10240
	ds_write_b128 v176, v[12:15] offset:15360
	ds_write_b128 v176, v[16:19] offset:20480
	ds_write_b128 v176, v[20:23] offset:25600
	global_load_dwordx4 v[0:3], v[162:163], off sc1
	v_lshl_add_u64 v[168:169], v[162:163], 0, s[16:17]
	global_load_dwordx4 v[4:7], v[168:169], off sc1
	global_load_dwordx4 v[8:11], v[160:161], off sc1
	v_lshl_add_u64 v[170:171], v[160:161], 0, s[18:19]
	global_load_dwordx4 v[12:15], v[170:171], off sc1
	v_lshl_add_u64 v[172:173], v[160:161], 0, s[20:21]
	global_load_dwordx4 v[16:19], v[172:173], off sc1
	v_lshl_add_u64 v[174:175], v[160:161], 0, s[22:23]
	global_load_dwordx4 v[20:23], v[174:175], off sc1
	s_add_i32 s54, s54, 1
	s_mulk_i32 s3, 0x7800
	v_add3_u32 v188, s3, v166, v167
	s_setprio 1
	v_add3_u32 v192, s3, v165, v167
	ds_read_b128 v[168:171], v192 offset:10240
	ds_read_b128 v[172:175], v192 offset:11520
	ds_read_b128 v[176:179], v188
	ds_read_b128 v[180:183], v188 offset:1280
	ds_read_b128 v[184:187], v188 offset:2560
	ds_read_b128 v[188:191], v188 offset:3840
	s_waitcnt lgkmcnt(3)
	v_mfma_f32_16x16x32_bf16 v[148:151], v[168:171], v[176:179], v[148:151]
	v_mfma_f32_16x16x32_bf16 v[144:147], v[172:175], v[176:179], v[144:147]
	s_waitcnt lgkmcnt(2)
	v_mfma_f32_16x16x32_bf16 v[132:135], v[168:171], v[180:183], v[132:135]
	v_mfma_f32_16x16x32_bf16 v[128:131], v[172:175], v[180:183], v[128:131]
	s_waitcnt lgkmcnt(1)
	v_mfma_f32_16x16x32_bf16 v[100:103], v[168:171], v[184:187], v[100:103]
	v_mfma_f32_16x16x32_bf16 v[92:95], v[172:175], v[184:187], v[92:95]
	s_waitcnt lgkmcnt(0)
	v_mfma_f32_16x16x32_bf16 v[68:71], v[168:171], v[188:191], v[68:71]
	ds_read_b128 v[168:171], v192 offset:12800
	v_mfma_f32_16x16x32_bf16 v[60:63], v[172:175], v[188:191], v[60:63]
	ds_read_b128 v[172:175], v192 offset:14080
	s_waitcnt lgkmcnt(1)
	v_mfma_f32_16x16x32_bf16 v[140:143], v[168:171], v[176:179], v[140:143]
	s_waitcnt lgkmcnt(0)
	v_mfma_f32_16x16x32_bf16 v[136:139], v[172:175], v[176:179], v[136:139]
	v_mfma_f32_16x16x32_bf16 v[116:119], v[168:171], v[180:183], v[116:119]
	v_mfma_f32_16x16x32_bf16 v[108:111], v[172:175], v[180:183], v[108:111]
	v_mfma_f32_16x16x32_bf16 v[84:87], v[168:171], v[184:187], v[84:87]
	v_mfma_f32_16x16x32_bf16 v[76:79], v[172:175], v[184:187], v[76:79]
	v_mfma_f32_16x16x32_bf16 v[52:55], v[168:171], v[188:191], v[52:55]
	ds_read_b128 v[168:171], v192 offset:15360
	v_mfma_f32_16x16x32_bf16 v[44:47], v[172:175], v[188:191], v[44:47]
	ds_read_b128 v[172:175], v192 offset:16640
	s_waitcnt lgkmcnt(1)
	v_mfma_f32_16x16x32_bf16 v[124:127], v[168:171], v[176:179], v[124:127]
	s_waitcnt lgkmcnt(0)
	v_mfma_f32_16x16x32_bf16 v[120:123], v[172:175], v[176:179], v[120:123]
	v_mfma_f32_16x16x32_bf16 v[96:99], v[168:171], v[180:183], v[96:99]
	v_mfma_f32_16x16x32_bf16 v[88:91], v[172:175], v[180:183], v[88:91]
	v_mfma_f32_16x16x32_bf16 v[64:67], v[168:171], v[184:187], v[64:67]
	v_mfma_f32_16x16x32_bf16 v[56:59], v[172:175], v[184:187], v[56:59]
	v_mfma_f32_16x16x32_bf16 v[36:39], v[168:171], v[188:191], v[36:39]
	ds_read_b128 v[168:171], v192 offset:17920
	v_mfma_f32_16x16x32_bf16 v[32:35], v[172:175], v[188:191], v[32:35]
	ds_read_b128 v[172:175], v192 offset:19200
	s_waitcnt lgkmcnt(1)
	v_mfma_f32_16x16x32_bf16 v[112:115], v[168:171], v[176:179], v[112:115]
	s_waitcnt lgkmcnt(0)
	v_mfma_f32_16x16x32_bf16 v[104:107], v[172:175], v[176:179], v[104:107]
	v_mfma_f32_16x16x32_bf16 v[80:83], v[168:171], v[180:183], v[80:83]
	v_mfma_f32_16x16x32_bf16 v[72:75], v[172:175], v[180:183], v[72:75]
	v_mfma_f32_16x16x32_bf16 v[48:51], v[168:171], v[184:187], v[48:51]
	v_mfma_f32_16x16x32_bf16 v[40:43], v[172:175], v[184:187], v[40:43]
	v_mfma_f32_16x16x32_bf16 v[28:31], v[168:171], v[188:191], v[28:31]
	v_mfma_f32_16x16x32_bf16 v[24:27], v[172:175], v[188:191], v[24:27]
	s_setprio 0
	v_lshl_add_u64 v[160:161], v[160:161], 0, s[26:27]
	s_cmp_eq_u32 s54, 22
	v_lshl_add_u64 v[162:163], v[162:163], 0, 64
	s_barrier
	s_cbranch_scc0 .LBB0_265
	s_waitcnt vmcnt(0)
	ds_write_b128 v155, v[0:3] offset:30720
	ds_write_b128 v155, v[4:7] offset:35840
	ds_write_b128 v155, v[8:11] offset:40960
	ds_write_b128 v155, v[12:15] offset:46080
	ds_write_b128 v155, v[16:19] offset:51200
	ds_write_b128 v155, v[20:23] offset:56320
	v_add_u32_e32 v155, v166, v167
	s_setprio 1
	v_add_u32_e32 v165, v165, v167
	ds_read_b128 v[160:163], v165 offset:10240
	ds_read_b128 v[166:169], v165 offset:11520
	ds_read_b128 v[170:173], v155
	ds_read_b128 v[174:177], v155 offset:1280
	ds_read_b128 v[178:181], v155 offset:2560
	ds_read_b128 v[182:185], v155 offset:3840
	s_waitcnt lgkmcnt(3)
	v_mfma_f32_16x16x32_bf16 v[148:151], v[160:163], v[170:173], v[148:151]
	v_mfma_f32_16x16x32_bf16 v[144:147], v[166:169], v[170:173], v[144:147]
	s_waitcnt lgkmcnt(2)
	v_mfma_f32_16x16x32_bf16 v[132:135], v[160:163], v[174:177], v[132:135]
	v_mfma_f32_16x16x32_bf16 v[128:131], v[166:169], v[174:177], v[128:131]
	s_waitcnt lgkmcnt(1)
	v_mfma_f32_16x16x32_bf16 v[100:103], v[160:163], v[178:181], v[100:103]
	v_mfma_f32_16x16x32_bf16 v[92:95], v[166:169], v[178:181], v[92:95]
	s_waitcnt lgkmcnt(0)
	v_mfma_f32_16x16x32_bf16 v[68:71], v[160:163], v[182:185], v[68:71]
	ds_read_b128 v[160:163], v165 offset:12800
	v_mfma_f32_16x16x32_bf16 v[60:63], v[166:169], v[182:185], v[60:63]
	ds_read_b128 v[166:169], v165 offset:14080
	s_waitcnt lgkmcnt(1)
	v_mfma_f32_16x16x32_bf16 v[186:189], v[160:163], v[170:173], v[140:143]
	s_waitcnt lgkmcnt(0)
; #define G_LOAD(kt_) do { \
;     if constexpr (AF32) { _Pragma("unroll") for (int i = 0; i < 4; ++i) ld16_sc1(ra[i], Af + (size_t)i * 32 * lda + (kt_) * 32); } \
;     else { _Pragma("unroll") for (int i = 0; i < 2; ++i) ld16_sc1(rab[i], Ab + (size_t)i * 64 * lda + (kt_) * 32); } \
;     _Pragma("unroll") for (int i = 0; i < 4; ++i) ld16_sc1(rb[i], Bp + (size_t)(kt_) * bstep + i * 2048); } while (0)
; template <bool AF32, class Epi>
; __device__ __forceinline__ void gemm_tile(unsigned char* smem, const void* Ap, int lda, const bf16_t* WT, int N, int K, const Epi& epi, int m0, int n0,
;                                           GPre& pr, bool preloaded, const void* nAp, int nn0, bool has_next) {
;     ...
;     const bf16_t* a_s = sbase + cur * G_STAGE + (wr * 64 + l15) * GLD + quad * 8;
;     const bf16_t* b_s = sbase + cur * G_STAGE + 128 * GLD + (wc * 128 + l15) * GLD + quad * 8;
;     __builtin_amdgcn_s_setprio(1);
;     bf16x8 af[4];
; #pragma unroll
;     for (int m = 0; m < 4; ++m) af[m] = *(const bf16x8*)(a_s + m * 16 * GLD);
; #pragma unroll
;     for (int nh = 0; nh < 4; ++nh) {
;       bf16x8 bfr[2];
; #pragma unroll
;       for (int n2 = 0; n2 < 2; ++n2) bfr[n2] = *(const bf16x8*)(b_s + (nh * 2 + n2) * 16 * GLD);
; #pragma unroll
;       for (int m = 0; m < 4; ++m)
; #pragma unroll
;         for (int n2 = 0; n2 < 2; ++n2) acc[m][nh * 2 + n2] = __builtin_amdgcn_mfma_f32_16x16x32_bf16(bfr[n2], af[m], acc[m][nh * 2 + n2], 0, 0, 0);
;     }
;     __builtin_amdgcn_s_setprio(0);
;     __syncthreads();
;   }
;   if (has_next) {
;     const float* Af = (const float*)nAp + (size_t)(tid >> 3) * lda + (tid & 7) * 4;
;     const bf16_t* Ab = (const bf16_t*)nAp + (size_t)(tid >> 2) * lda + (tid & 3) * 8;
;     const bf16_t* Bp = WT + (size_t)nn0 * 32 + tid * 8;
;     G_LOAD(0);
;   }
	v_mfma_f32_16x16x32_bf16 v[136:139], v[166:169], v[170:173], v[136:139]
	v_mfma_f32_16x16x32_bf16 v[190:193], v[160:163], v[174:177], v[116:119]
	v_mfma_f32_16x16x32_bf16 v[194:197], v[166:169], v[174:177], v[108:111]
	v_mfma_f32_16x16x32_bf16 v[198:201], v[160:163], v[178:181], v[84:87]
	v_mfma_f32_16x16x32_bf16 v[202:205], v[166:169], v[178:181], v[76:79]
	v_mfma_f32_16x16x32_bf16 v[160:163], v[160:163], v[182:185], v[52:55]
	s_nop 2
	ds_read_b128 v[52:55], v165 offset:15360
	v_mfma_f32_16x16x32_bf16 v[166:169], v[166:169], v[182:185], v[44:47]
	s_nop 2
	ds_read_b128 v[44:47], v165 offset:16640
	s_waitcnt lgkmcnt(1)
	v_mfma_f32_16x16x32_bf16 v[124:127], v[52:55], v[170:173], v[124:127]
	s_waitcnt lgkmcnt(0)
	v_mfma_f32_16x16x32_bf16 v[120:123], v[44:47], v[170:173], v[120:123]
	v_mfma_f32_16x16x32_bf16 v[96:99], v[52:55], v[174:177], v[96:99]
	v_mfma_f32_16x16x32_bf16 v[88:91], v[44:47], v[174:177], v[88:91]
	v_mfma_f32_16x16x32_bf16 v[64:67], v[52:55], v[178:181], v[64:67]
	v_mfma_f32_16x16x32_bf16 v[56:59], v[44:47], v[178:181], v[56:59]
	v_mfma_f32_16x16x32_bf16 v[36:39], v[52:55], v[182:185], v[36:39]
	ds_read_b128 v[52:55], v165 offset:17920
	v_mfma_f32_16x16x32_bf16 v[32:35], v[44:47], v[182:185], v[32:35]
	ds_read_b128 v[44:47], v165 offset:19200
	s_waitcnt lgkmcnt(1)
	v_mfma_f32_16x16x32_bf16 v[28:31], v[52:55], v[182:185], v[28:31]
	s_waitcnt lgkmcnt(0)
	v_mfma_f32_16x16x32_bf16 v[24:27], v[44:47], v[182:185], v[24:27]
	v_mfma_f32_16x16x32_bf16 v[206:209], v[52:55], v[170:173], v[112:115]
	v_mfma_f32_16x16x32_bf16 v[170:173], v[44:47], v[170:173], v[104:107]
	v_mfma_f32_16x16x32_bf16 v[212:215], v[52:55], v[174:177], v[80:83]
	v_mfma_f32_16x16x32_bf16 v[174:177], v[44:47], v[174:177], v[72:75]
	v_mfma_f32_16x16x32_bf16 v[216:219], v[52:55], v[178:181], v[48:51]
	v_mfma_f32_16x16x32_bf16 v[178:181], v[44:47], v[178:181], v[40:43]
	s_setprio 0
	s_barrier
	s_setprio 1
	ds_read_b128 v[40:43], v165 offset:40960
	ds_read_b128 v[44:47], v165 offset:42240
	ds_read_b128 v[182:185], v155 offset:30720
	ds_read_b128 v[220:223], v155 offset:32000
	ds_read_b128 v[224:227], v155 offset:33280
	ds_read_b128 v[228:231], v155 offset:34560
	s_waitcnt lgkmcnt(3)
	v_mfma_f32_16x16x32_bf16 v[148:151], v[40:43], v[182:185], v[148:151]
	s_waitcnt lgkmcnt(2)
	v_mfma_f32_16x16x32_bf16 v[116:119], v[40:43], v[220:223], v[132:135]
	s_waitcnt lgkmcnt(1)
	v_mfma_f32_16x16x32_bf16 v[84:87], v[40:43], v[224:227], v[100:103]
	s_waitcnt lgkmcnt(0)
	v_mfma_f32_16x16x32_bf16 v[52:55], v[40:43], v[228:231], v[68:71]
	ds_read_b128 v[40:43], v165 offset:43520
	v_mfma_f32_16x16x32_bf16 v[48:51], v[44:47], v[228:231], v[60:63]
	s_nop 2
	ds_read_b128 v[60:63], v165 offset:44800
	v_mfma_f32_16x16x32_bf16 v[140:143], v[44:47], v[182:185], v[144:147]
	v_mfma_f32_16x16x32_bf16 v[108:111], v[44:47], v[220:223], v[128:131]
	v_mfma_f32_16x16x32_bf16 v[80:83], v[44:47], v[224:227], v[92:95]
	s_waitcnt lgkmcnt(1)
	v_mfma_f32_16x16x32_bf16 v[144:147], v[40:43], v[182:185], v[186:189]
	s_nop 0
	ds_read_b128 v[92:95], v165 offset:46080
	s_waitcnt lgkmcnt(1)
	v_mfma_f32_16x16x32_bf16 v[136:139], v[60:63], v[182:185], v[136:139]
	v_mfma_f32_16x16x32_bf16 v[112:115], v[40:43], v[220:223], v[190:193]
	v_mfma_f32_16x16x32_bf16 v[104:107], v[60:63], v[220:223], v[194:197]
	v_mfma_f32_16x16x32_bf16 v[76:79], v[40:43], v[224:227], v[198:201]
	v_mfma_f32_16x16x32_bf16 v[72:75], v[60:63], v[224:227], v[202:205]
	v_mfma_f32_16x16x32_bf16 v[44:47], v[40:43], v[228:231], v[160:163]
	v_mfma_f32_16x16x32_bf16 v[40:43], v[60:63], v[228:231], v[166:169]
	ds_read_b128 v[60:63], v165 offset:47360
	s_nop 0
	ds_read_b128 v[160:163], v165 offset:48640
	ds_read_b128 v[166:169], v165 offset:49920
	s_waitcnt lgkmcnt(3)
	v_mfma_f32_16x16x32_bf16 v[132:135], v[92:95], v[182:185], v[124:127]
	s_waitcnt lgkmcnt(2)
	v_mfma_f32_16x16x32_bf16 v[128:131], v[60:63], v[182:185], v[120:123]
	v_mfma_f32_16x16x32_bf16 v[100:103], v[92:95], v[220:223], v[96:99]
	v_mfma_f32_16x16x32_bf16 v[96:99], v[60:63], v[220:223], v[88:91]
	v_mfma_f32_16x16x32_bf16 v[68:71], v[92:95], v[224:227], v[64:67]
	v_mfma_f32_16x16x32_bf16 v[64:67], v[60:63], v[224:227], v[56:59]
	v_mfma_f32_16x16x32_bf16 v[36:39], v[92:95], v[228:231], v[36:39]
	v_mfma_f32_16x16x32_bf16 v[32:35], v[60:63], v[228:231], v[32:35]
	s_waitcnt lgkmcnt(1)
	v_mfma_f32_16x16x32_bf16 v[124:127], v[160:163], v[182:185], v[206:209]
	s_waitcnt lgkmcnt(0)
	v_mfma_f32_16x16x32_bf16 v[120:123], v[166:169], v[182:185], v[170:173]
	v_mfma_f32_16x16x32_bf16 v[92:95], v[160:163], v[220:223], v[212:215]
	v_mfma_f32_16x16x32_bf16 v[88:91], v[166:169], v[220:223], v[174:177]
	v_mfma_f32_16x16x32_bf16 v[60:63], v[160:163], v[224:227], v[216:219]
	v_mfma_f32_16x16x32_bf16 v[56:59], v[166:169], v[224:227], v[178:181]
	v_mfma_f32_16x16x32_bf16 v[28:31], v[160:163], v[228:231], v[28:31]
	v_mfma_f32_16x16x32_bf16 v[24:27], v[166:169], v[228:231], v[24:27]
	s_and_b64 vcc, exec, s[50:51]
	s_barrier
	s_cbranch_vccz .LBB0_253
	s_mul_i32 s50, s72, 0xc0000
	s_mul_hi_i32 s3, s72, 0xc0000
	s_add_u32 s50, s2, s50
	s_addc_u32 s51, s33, s3
	s_lshl_b32 s54, s71, 8
	s_ashr_i32 s55, s54, 31
	v_lshl_add_u64 v[0:1], v[158:159], 1, s[50:51]
	s_lshl_b64 s[50:51], s[54:55], 6
	v_lshl_add_u64 v[4:5], v[0:1], 0, v[152:153]
	s_add_u32 s50, s58, s50
	s_addc_u32 s51, s59, s51
	global_load_dwordx4 v[0:3], v[4:5], off sc1
	v_lshl_add_u64 v[4:5], v[4:5], 0, s[16:17]
	global_load_dwordx4 v[4:7], v[4:5], off sc1
	v_lshl_add_u64 v[20:21], v[156:157], 1, s[50:51]
	global_load_dwordx4 v[8:11], v[20:21], off sc1
	v_lshl_add_u64 v[12:13], v[20:21], 0, s[18:19]
	global_load_dwordx4 v[12:15], v[12:13], off sc1
	v_lshl_add_u64 v[16:17], v[20:21], 0, s[20:21]
	global_load_dwordx4 v[16:19], v[16:17], off sc1
	v_lshl_add_u64 v[20:21], v[20:21], 0, s[22:23]
	global_load_dwordx4 v[20:23], v[20:21], off sc1
	s_branch .LBB0_253

; __device__ __forceinline__ void run_phase(int ph, KParams kp, unsigned char* smem) {
;     ...
;       for (int t = blockIdx.x; t < 512 * 4; t += gridDim.x) {
;         int mt, nt; tile_map(t, 4, gridDim.x, mt, nt);
;         const bool hn = t + (int)gridDim.x < 512 * 4; int mtn = 0, ntn = 0; if (hn) tile_map(t + gridDim.x, 4, gridDim.x, mtn, ntn);
;         EpiResid e{ph == 4 ? xin_row(kp->x_prompt, kp->x_sample, mt * 128) : kp->out + (size_t)mt * 128 * 1024, kp->out};
;         gemm_tile<false>(smem, A + (size_t)mt * 128 * lda, lda, Bt, 1024, K, e, mt * 128, nt * 256, pr, pre, A + (size_t)mtn * 128 * lda, ntn * 256, hn); pre = hn;
;       }
.LBB0_269:
	s_setprio 0
	v_readlane_b32 s26, v248, 1
	v_readlane_b32 s27, v248, 2

; #define G_LOAD(kt_) do { \
;     if constexpr (AF32) { _Pragma("unroll") for (int i = 0; i < 4; ++i) ld16_sc1(ra[i], Af + (size_t)i * 32 * lda + (kt_) * 32); } \
;     else { _Pragma("unroll") for (int i = 0; i < 2; ++i) ld16_sc1(rab[i], Ab + (size_t)i * 64 * lda + (kt_) * 32); } \
;     _Pragma("unroll") for (int i = 0; i < 4; ++i) ld16_sc1(rb[i], Bp + (size_t)(kt_) * bstep + i * 2048); } while (0)
; template <bool AF32, class Epi>
; __device__ __forceinline__ void gemm_tile(unsigned char* smem, const void* Ap, int lda, const bf16_t* WT, int N, int K, const Epi& epi, int m0, int n0,
;                                           GPre& pr, bool preloaded, const void* nAp, int nn0, bool has_next) {
;     ...
;   if (!preloaded) G_LOAD(0);
;   G_STORE(0);
;   if (nk > 1) G_LOAD(1);
;   __syncthreads();
;   for (int kt = 0; kt < nk; ++kt) {
;     const int cur = kt & 1;
;     if (kt + 1 < nk) G_STORE(cur ^ 1);
;     if (kt + 2 < nk) G_LOAD(kt + 2);
;     const bf16_t* a_s = sbase + cur * G_STAGE + (wr * 64 + l15) * GLD + quad * 8;
;     const bf16_t* b_s = sbase + cur * G_STAGE + 128 * GLD + (wc * 128 + l15) * GLD + quad * 8;
;     __builtin_amdgcn_s_setprio(1);
;     bf16x8 af[4];
; #pragma unroll
;     for (int m = 0; m < 4; ++m) af[m] = *(const bf16x8*)(a_s + m * 16 * GLD);
; #pragma unroll
;     for (int nh = 0; nh < 4; ++nh) {
;       bf16x8 bfr[2];
; #pragma unroll
;       for (int n2 = 0; n2 < 2; ++n2) bfr[n2] = *(const bf16x8*)(b_s + (nh * 2 + n2) * 16 * GLD);
; #pragma unroll
;       for (int m = 0; m < 4; ++m)
; #pragma unroll
;         for (int n2 = 0; n2 < 2; ++n2) acc[m][nh * 2 + n2] = __builtin_amdgcn_mfma_f32_16x16x32_bf16(bfr[n2], af[m], acc[m][nh * 2 + n2], 0, 0, 0);
;     }
;     __builtin_amdgcn_s_setprio(0);
;     __syncthreads();
;   }
.LBB0_296:
	s_and_b32 s3, s49, 1
	s_waitcnt vmcnt(0)
	s_xor_b32 s51, s3, 1
	s_mulk_i32 s51, 0x7800
	v_cvt_pk_bf16_f32 v202, v28, v29
	v_mov_b32_e32 v205, v28
	v_mov_b32_e32 v28, v25
	v_lshl_add_u32 v171, v160, 1, s51
	v_cvt_pk_bf16_f32 v203, v30, v31
	v_mov_b32_e32 v204, v24
	v_mov_b32_e32 v206, v26
	v_mov_b32_e32 v207, v30
	v_mov_b32_e32 v30, v27
	v_cvt_pk_bf16_f32 v24, v24, v25
	v_cvt_pk_bf16_f32 v25, v26, v27
	v_cvt_pk_bf16_f32 v26, v20, v21
	v_cvt_pk_bf16_f32 v27, v22, v23
	v_mov_b32_e32 v208, v16
	v_mov_b32_e32 v209, v20
	v_mov_b32_e32 v20, v17
	v_mov_b32_e32 v212, v18
	v_mov_b32_e32 v213, v22
	v_mov_b32_e32 v22, v19
	v_cvt_pk_bf16_f32 v16, v16, v17
	v_cvt_pk_bf16_f32 v17, v18, v19
	v_pk_mul_f32 v[18:19], v[28:29], v[28:29]
	v_lshl_add_u32 v176, v162, 1, s51
	ds_write2st64_b64 v171, v[202:203], v[24:25] offset1:5
	ds_write2st64_b64 v171, v[26:27], v[16:17] offset0:10 offset1:15
	ds_write_b128 v176, v[0:3] offset:10240
	ds_write_b128 v176, v[4:7] offset:15360
	ds_write_b128 v176, v[8:11] offset:20480
	ds_write_b128 v176, v[12:15] offset:25600
	v_pk_fma_f32 v[0:1], v[204:205], v[204:205], v[18:19]
	v_pk_mul_f32 v[20:21], v[20:21], v[20:21]
	v_pk_fma_f32 v[0:1], v[206:207], v[206:207], v[0:1]
	v_pk_fma_f32 v[2:3], v[208:209], v[208:209], v[20:21]
	v_pk_fma_f32 v[202:203], v[30:31], v[30:31], v[0:1]
	global_load_dwordx4 v[28:31], v[166:167], off sc1
	v_lshl_add_u64 v[172:173], v[166:167], 0, s[14:15]
	v_pk_fma_f32 v[2:3], v[212:213], v[212:213], v[2:3]
	global_load_dwordx4 v[24:27], v[172:173], off sc1
	v_lshl_add_u64 v[174:175], v[166:167], 0, s[16:17]
	v_pk_fma_f32 v[204:205], v[22:23], v[22:23], v[2:3]
	global_load_dwordx4 v[20:23], v[174:175], off sc1
	v_lshl_add_u64 v[194:195], v[166:167], 0, s[18:19]
	global_load_dwordx4 v[16:19], v[194:195], off sc1
	global_load_dwordx4 v[0:3], v[164:165], off sc1
	v_lshl_add_u64 v[196:197], v[164:165], 0, s[20:21]
	global_load_dwordx4 v[4:7], v[196:197], off sc1
	v_lshl_add_u64 v[198:199], v[164:165], 0, s[22:23]
	global_load_dwordx4 v[8:11], v[198:199], off sc1
	v_lshl_add_u64 v[200:201], v[164:165], 0, s[24:25]
	global_load_dwordx4 v[12:15], v[200:201], off sc1
	s_add_i32 s49, s49, 1
	s_mulk_i32 s3, 0x7800
	v_pk_add_f32 v[186:187], v[186:187], v[202:203]
	v_pk_add_f32 v[182:183], v[182:183], v[204:205]
	v_add3_u32 v171, s3, v169, v170
	s_setprio 1
	v_add3_u32 v176, s3, v168, v170
	ds_read_b128 v[172:175], v176 offset:10240
	ds_read_b128 v[194:197], v176 offset:11520
	ds_read_b128 v[198:201], v171
	ds_read_b128 v[202:205], v171 offset:1280
	ds_read_b128 v[206:209], v171 offset:2560
	ds_read_b128 v[212:215], v171 offset:3840
	s_waitcnt lgkmcnt(3)
	v_mfma_f32_16x16x32_bf16 v[156:159], v[172:175], v[198:201], v[156:159]
	v_mfma_f32_16x16x32_bf16 v[152:155], v[194:197], v[198:201], v[152:155]
	s_waitcnt lgkmcnt(2)
	v_mfma_f32_16x16x32_bf16 v[140:143], v[172:175], v[202:205], v[140:143]
	v_mfma_f32_16x16x32_bf16 v[136:139], v[194:197], v[202:205], v[136:139]
	s_waitcnt lgkmcnt(1)
	v_mfma_f32_16x16x32_bf16 v[108:111], v[172:175], v[206:209], v[108:111]
	v_mfma_f32_16x16x32_bf16 v[100:103], v[194:197], v[206:209], v[100:103]
	s_waitcnt lgkmcnt(0)
	v_mfma_f32_16x16x32_bf16 v[76:79], v[172:175], v[212:215], v[76:79]
	ds_read_b128 v[172:175], v176 offset:12800
	v_mfma_f32_16x16x32_bf16 v[68:71], v[194:197], v[212:215], v[68:71]
	ds_read_b128 v[194:197], v176 offset:14080
	s_waitcnt lgkmcnt(1)
	v_mfma_f32_16x16x32_bf16 v[148:151], v[172:175], v[198:201], v[148:151]
	s_waitcnt lgkmcnt(0)
	v_mfma_f32_16x16x32_bf16 v[144:147], v[194:197], v[198:201], v[144:147]
	v_mfma_f32_16x16x32_bf16 v[124:127], v[172:175], v[202:205], v[124:127]
	v_mfma_f32_16x16x32_bf16 v[116:119], v[194:197], v[202:205], v[116:119]
	v_mfma_f32_16x16x32_bf16 v[92:95], v[172:175], v[206:209], v[92:95]
	v_mfma_f32_16x16x32_bf16 v[84:87], v[194:197], v[206:209], v[84:87]
	v_mfma_f32_16x16x32_bf16 v[60:63], v[172:175], v[212:215], v[60:63]
	ds_read_b128 v[172:175], v176 offset:15360
	v_mfma_f32_16x16x32_bf16 v[52:55], v[194:197], v[212:215], v[52:55]
	ds_read_b128 v[194:197], v176 offset:16640
	s_waitcnt lgkmcnt(1)
	v_mfma_f32_16x16x32_bf16 v[132:135], v[172:175], v[198:201], v[132:135]
	s_waitcnt lgkmcnt(0)
	v_mfma_f32_16x16x32_bf16 v[128:131], v[194:197], v[198:201], v[128:131]
	v_mfma_f32_16x16x32_bf16 v[104:107], v[172:175], v[202:205], v[104:107]
	v_mfma_f32_16x16x32_bf16 v[96:99], v[194:197], v[202:205], v[96:99]
	v_mfma_f32_16x16x32_bf16 v[72:75], v[172:175], v[206:209], v[72:75]
	v_mfma_f32_16x16x32_bf16 v[64:67], v[194:197], v[206:209], v[64:67]
	v_mfma_f32_16x16x32_bf16 v[44:47], v[172:175], v[212:215], v[44:47]
	ds_read_b128 v[172:175], v176 offset:17920
	v_mfma_f32_16x16x32_bf16 v[40:43], v[194:197], v[212:215], v[40:43]
	ds_read_b128 v[194:197], v176 offset:19200
	s_waitcnt lgkmcnt(1)
	v_mfma_f32_16x16x32_bf16 v[120:123], v[172:175], v[198:201], v[120:123]
	s_waitcnt lgkmcnt(0)
	v_mfma_f32_16x16x32_bf16 v[112:115], v[194:197], v[198:201], v[112:115]
	v_mfma_f32_16x16x32_bf16 v[88:91], v[172:175], v[202:205], v[88:91]
	v_mfma_f32_16x16x32_bf16 v[80:83], v[194:197], v[202:205], v[80:83]
	v_mfma_f32_16x16x32_bf16 v[56:59], v[172:175], v[206:209], v[56:59]
	v_mfma_f32_16x16x32_bf16 v[48:51], v[194:197], v[206:209], v[48:51]
	v_mfma_f32_16x16x32_bf16 v[36:39], v[172:175], v[212:215], v[36:39]
	v_mfma_f32_16x16x32_bf16 v[32:35], v[194:197], v[212:215], v[32:35]
	s_setprio 0
	v_lshl_add_u64 v[164:165], v[164:165], 0, s[36:37]
	s_cmp_eq_u32 s49, 30
	v_lshl_add_u64 v[166:167], v[166:167], 0, s[26:27]
	s_barrier
	s_cbranch_scc0 .LBB0_296
; #define G_LOAD(kt_) do { \
;     if constexpr (AF32) { _Pragma("unroll") for (int i = 0; i < 4; ++i) ld16_sc1(ra[i], Af + (size_t)i * 32 * lda + (kt_) * 32); } \
;     else { _Pragma("unroll") for (int i = 0; i < 2; ++i) ld16_sc1(rab[i], Ab + (size_t)i * 64 * lda + (kt_) * 32); } \
;     _Pragma("unroll") for (int i = 0; i < 4; ++i) ld16_sc1(rb[i], Bp + (size_t)(kt_) * bstep + i * 2048); } while (0)
; template <bool AF32, class Epi>
; __device__ __forceinline__ void gemm_tile(unsigned char* smem, const void* Ap, int lda, const bf16_t* WT, int N, int K, const Epi& epi, int m0, int n0,
;                                           GPre& pr, bool preloaded, const void* nAp, int nn0, bool has_next) {
;     ...
;   if (!preloaded) G_LOAD(0);
;   G_STORE(0);
;   if (nk > 1) G_LOAD(1);
;   __syncthreads();
;   for (int kt = 0; kt < nk; ++kt) {
;     const int cur = kt & 1;
;     if (kt + 1 < nk) G_STORE(cur ^ 1);
;     if (kt + 2 < nk) G_LOAD(kt + 2);
;     const bf16_t* a_s = sbase + cur * G_STAGE + (wr * 64 + l15) * GLD + quad * 8;
;     const bf16_t* b_s = sbase + cur * G_STAGE + 128 * GLD + (wc * 128 + l15) * GLD + quad * 8;
;     __builtin_amdgcn_s_setprio(1);
;     bf16x8 af[4];
; #pragma unroll
;     for (int m = 0; m < 4; ++m) af[m] = *(const bf16x8*)(a_s + m * 16 * GLD);
; #pragma unroll
;     for (int nh = 0; nh < 4; ++nh) {
;       bf16x8 bfr[2];
; #pragma unroll
;       for (int n2 = 0; n2 < 2; ++n2) bfr[n2] = *(const bf16x8*)(b_s + (nh * 2 + n2) * 16 * GLD);
; #pragma unroll
;       for (int m = 0; m < 4; ++m)
; #pragma unroll
;         for (int n2 = 0; n2 < 2; ++n2) acc[m][nh * 2 + n2] = __builtin_amdgcn_mfma_f32_16x16x32_bf16(bfr[n2], af[m], acc[m][nh * 2 + n2], 0, 0, 0);
;     }
;     __builtin_amdgcn_s_setprio(0);
;     __syncthreads();
	s_waitcnt vmcnt(0)
	v_add_u32_e32 v176, v169, v170
	v_cvt_pk_bf16_f32 v164, v28, v29
	v_cvt_pk_bf16_f32 v165, v30, v31
	v_cvt_pk_bf16_f32 v166, v24, v25
	v_cvt_pk_bf16_f32 v167, v26, v27
	ds_write2st64_b64 v161, v[164:165], v[166:167] offset0:60 offset1:65
	v_cvt_pk_bf16_f32 v164, v20, v21
	v_cvt_pk_bf16_f32 v165, v22, v23
	v_cvt_pk_bf16_f32 v166, v16, v17
	v_cvt_pk_bf16_f32 v167, v18, v19
	ds_write2st64_b64 v161, v[164:165], v[166:167] offset0:70 offset1:75
	ds_write_b128 v163, v[0:3] offset:40960
	ds_write_b128 v163, v[4:7] offset:46080
	ds_write_b128 v163, v[8:11] offset:51200
	ds_write_b128 v163, v[12:15] offset:56320
	s_setprio 1
	v_add_u32_e32 v193, v168, v170
	ds_read_b128 v[160:163], v193 offset:10240
	ds_read_b128 v[164:167], v193 offset:11520
	ds_read_b128 v[168:171], v176
	ds_read_b128 v[172:175], v176 offset:1280
	ds_read_b128 v[194:197], v176 offset:2560
	ds_read_b128 v[198:201], v176 offset:3840
	s_waitcnt lgkmcnt(3)
	v_mfma_f32_16x16x32_bf16 v[156:159], v[160:163], v[168:171], v[156:159]
	v_mfma_f32_16x16x32_bf16 v[152:155], v[164:167], v[168:171], v[152:155]
	s_waitcnt lgkmcnt(2)
	v_mfma_f32_16x16x32_bf16 v[140:143], v[160:163], v[172:175], v[140:143]
	v_mfma_f32_16x16x32_bf16 v[136:139], v[164:167], v[172:175], v[136:139]
	s_waitcnt lgkmcnt(1)
	v_mfma_f32_16x16x32_bf16 v[108:111], v[160:163], v[194:197], v[108:111]
	v_mfma_f32_16x16x32_bf16 v[100:103], v[164:167], v[194:197], v[100:103]
	s_waitcnt lgkmcnt(0)
	v_mfma_f32_16x16x32_bf16 v[76:79], v[160:163], v[198:201], v[76:79]
	ds_read_b128 v[160:163], v193 offset:12800
	v_mfma_f32_16x16x32_bf16 v[68:71], v[164:167], v[198:201], v[68:71]
	ds_read_b128 v[164:167], v193 offset:14080
	s_waitcnt lgkmcnt(1)
	v_mfma_f32_16x16x32_bf16 v[148:151], v[160:163], v[168:171], v[148:151]
	s_waitcnt lgkmcnt(0)
	v_mfma_f32_16x16x32_bf16 v[144:147], v[164:167], v[168:171], v[144:147]
	v_mfma_f32_16x16x32_bf16 v[124:127], v[160:163], v[172:175], v[124:127]
	v_mfma_f32_16x16x32_bf16 v[116:119], v[164:167], v[172:175], v[116:119]
	v_mfma_f32_16x16x32_bf16 v[92:95], v[160:163], v[194:197], v[92:95]
	v_mfma_f32_16x16x32_bf16 v[84:87], v[164:167], v[194:197], v[84:87]
	v_mfma_f32_16x16x32_bf16 v[60:63], v[160:163], v[198:201], v[60:63]
	ds_read_b128 v[160:163], v193 offset:15360
	v_mfma_f32_16x16x32_bf16 v[52:55], v[164:167], v[198:201], v[52:55]
	ds_read_b128 v[164:167], v193 offset:16640
	s_waitcnt lgkmcnt(1)
	v_mfma_f32_16x16x32_bf16 v[212:215], v[160:163], v[194:197], v[72:75]
	s_nop 2
	ds_read_b128 v[72:75], v193 offset:19200
	s_waitcnt lgkmcnt(1)
	v_mfma_f32_16x16x32_bf16 v[216:219], v[164:167], v[194:197], v[64:67]
	s_nop 2
	ds_read_b128 v[64:67], v193 offset:17920
	v_mfma_f32_16x16x32_bf16 v[128:131], v[164:167], v[168:171], v[128:131]
	v_mfma_f32_16x16x32_bf16 v[96:99], v[164:167], v[172:175], v[96:99]
	s_waitcnt lgkmcnt(0)
	v_mfma_f32_16x16x32_bf16 v[120:123], v[64:67], v[168:171], v[120:123]
	v_mfma_f32_16x16x32_bf16 v[112:115], v[72:75], v[168:171], v[112:115]
	v_mfma_f32_16x16x32_bf16 v[88:91], v[64:67], v[172:175], v[88:91]
	v_mfma_f32_16x16x32_bf16 v[80:83], v[72:75], v[172:175], v[80:83]
	v_mfma_f32_16x16x32_bf16 v[48:51], v[72:75], v[194:197], v[48:51]
	v_mfma_f32_16x16x32_bf16 v[202:205], v[160:163], v[168:171], v[132:135]
	v_mfma_f32_16x16x32_bf16 v[206:209], v[160:163], v[172:175], v[104:107]
	v_mfma_f32_16x16x32_bf16 v[44:47], v[160:163], v[198:201], v[44:47]
	v_mfma_f32_16x16x32_bf16 v[40:43], v[164:167], v[198:201], v[40:43]
	v_mfma_f32_16x16x32_bf16 v[220:223], v[64:67], v[194:197], v[56:59]
	v_mfma_f32_16x16x32_bf16 v[36:39], v[64:67], v[198:201], v[36:39]
	v_mfma_f32_16x16x32_bf16 v[32:35], v[72:75], v[198:201], v[32:35]
	s_setprio 0
	s_barrier
; #define G_LOAD(kt_) do { \
;     if constexpr (AF32) { _Pragma("unroll") for (int i = 0; i < 4; ++i) ld16_sc1(ra[i], Af + (size_t)i * 32 * lda + (kt_) * 32); } \
;     else { _Pragma("unroll") for (int i = 0; i < 2; ++i) ld16_sc1(rab[i], Ab + (size_t)i * 64 * lda + (kt_) * 32); } \
;     _Pragma("unroll") for (int i = 0; i < 4; ++i) ld16_sc1(rb[i], Bp + (size_t)(kt_) * bstep + i * 2048); } while (0)
; template <bool AF32, class Epi>
; __device__ __forceinline__ void gemm_tile(unsigned char* smem, const void* Ap, int lda, const bf16_t* WT, int N, int K, const Epi& epi, int m0, int n0,
;                                           GPre& pr, bool preloaded, const void* nAp, int nn0, bool has_next) {
;     ...
;     const bf16_t* a_s = sbase + cur * G_STAGE + (wr * 64 + l15) * GLD + quad * 8;
;     const bf16_t* b_s = sbase + cur * G_STAGE + 128 * GLD + (wc * 128 + l15) * GLD + quad * 8;
;     __builtin_amdgcn_s_setprio(1);
;     bf16x8 af[4];
; #pragma unroll
;     for (int m = 0; m < 4; ++m) af[m] = *(const bf16x8*)(a_s + m * 16 * GLD);
; #pragma unroll
;     for (int nh = 0; nh < 4; ++nh) {
;       bf16x8 bfr[2];
; #pragma unroll
;       for (int n2 = 0; n2 < 2; ++n2) bfr[n2] = *(const bf16x8*)(b_s + (nh * 2 + n2) * 16 * GLD);
; #pragma unroll
;       for (int m = 0; m < 4; ++m)
; #pragma unroll
;         for (int n2 = 0; n2 < 2; ++n2) acc[m][nh * 2 + n2] = __builtin_amdgcn_mfma_f32_16x16x32_bf16(bfr[n2], af[m], acc[m][nh * 2 + n2], 0, 0, 0);
;     }
;     __builtin_amdgcn_s_setprio(0);
;     __syncthreads();
;   }
;   if (has_next) {
;     const float* Af = (const float*)nAp + (size_t)(tid >> 3) * lda + (tid & 7) * 4;
;     const bf16_t* Ab = (const bf16_t*)nAp + (size_t)(tid >> 2) * lda + (tid & 3) * 8;
;     const bf16_t* Bp = WT + (size_t)nn0 * 32 + tid * 8;
;     G_LOAD(0);
;   }
	s_setprio 1
	ds_read_b128 v[56:59], v193 offset:40960
	ds_read_b128 v[64:67], v193 offset:42240
	ds_read_b128 v[194:197], v176 offset:30720
	ds_read_b128 v[198:201], v176 offset:32000
	ds_read_b128 v[224:227], v176 offset:33280
	ds_read_b128 v[228:231], v176 offset:34560
	s_waitcnt lgkmcnt(3)
	v_mfma_f32_16x16x32_bf16 v[172:175], v[56:59], v[194:197], v[156:159]
	v_mfma_f32_16x16x32_bf16 v[164:167], v[64:67], v[194:197], v[152:155]
	s_waitcnt lgkmcnt(2)
	v_mfma_f32_16x16x32_bf16 v[140:143], v[56:59], v[198:201], v[140:143]
	v_mfma_f32_16x16x32_bf16 v[132:135], v[64:67], v[198:201], v[136:139]
	s_waitcnt lgkmcnt(1)
	v_mfma_f32_16x16x32_bf16 v[108:111], v[56:59], v[224:227], v[108:111]
	v_mfma_f32_16x16x32_bf16 v[100:103], v[64:67], v[224:227], v[100:103]
	s_waitcnt lgkmcnt(0)
	v_mfma_f32_16x16x32_bf16 v[76:79], v[56:59], v[228:231], v[76:79]
	ds_read_b128 v[56:59], v193 offset:43520
	v_mfma_f32_16x16x32_bf16 v[72:75], v[64:67], v[228:231], v[68:71]
	ds_read_b128 v[64:67], v193 offset:44800
	s_waitcnt lgkmcnt(1)
	v_mfma_f32_16x16x32_bf16 v[168:171], v[56:59], v[194:197], v[148:151]
	s_waitcnt lgkmcnt(0)
	v_mfma_f32_16x16x32_bf16 v[156:159], v[64:67], v[194:197], v[144:147]
	v_mfma_f32_16x16x32_bf16 v[136:139], v[56:59], v[198:201], v[124:127]
	v_mfma_f32_16x16x32_bf16 v[124:127], v[64:67], v[198:201], v[116:119]
	v_mfma_f32_16x16x32_bf16 v[104:107], v[56:59], v[224:227], v[92:95]
	v_mfma_f32_16x16x32_bf16 v[92:95], v[64:67], v[224:227], v[84:87]
	v_mfma_f32_16x16x32_bf16 v[68:71], v[56:59], v[228:231], v[60:63]
	ds_read_b128 v[56:59], v193 offset:46080
	v_mfma_f32_16x16x32_bf16 v[64:67], v[64:67], v[228:231], v[52:55]
	s_nop 2
	ds_read_b128 v[52:55], v193 offset:47360
	s_waitcnt lgkmcnt(1)
	v_mfma_f32_16x16x32_bf16 v[160:163], v[56:59], v[194:197], v[202:205]
	s_waitcnt lgkmcnt(0)
	v_mfma_f32_16x16x32_bf16 v[148:151], v[52:55], v[194:197], v[128:131]
	v_mfma_f32_16x16x32_bf16 v[128:131], v[56:59], v[198:201], v[206:209]
	v_mfma_f32_16x16x32_bf16 v[116:119], v[52:55], v[198:201], v[96:99]
	v_mfma_f32_16x16x32_bf16 v[96:99], v[56:59], v[224:227], v[212:215]
	v_mfma_f32_16x16x32_bf16 v[60:63], v[56:59], v[228:231], v[44:47]
	s_nop 2
	ds_read_b128 v[44:47], v193 offset:48640
	v_mfma_f32_16x16x32_bf16 v[56:59], v[52:55], v[228:231], v[40:43]
	s_nop 2
	ds_read_b128 v[40:43], v193 offset:49920
	v_mfma_f32_16x16x32_bf16 v[84:87], v[52:55], v[224:227], v[216:219]
	s_waitcnt lgkmcnt(1)
	v_mfma_f32_16x16x32_bf16 v[152:155], v[44:47], v[194:197], v[120:123]
	s_waitcnt lgkmcnt(0)
	v_mfma_f32_16x16x32_bf16 v[144:147], v[40:43], v[194:197], v[112:115]
	v_mfma_f32_16x16x32_bf16 v[120:123], v[44:47], v[198:201], v[88:91]
	v_mfma_f32_16x16x32_bf16 v[112:115], v[40:43], v[198:201], v[80:83]
	v_mfma_f32_16x16x32_bf16 v[88:91], v[44:47], v[224:227], v[220:223]
	v_mfma_f32_16x16x32_bf16 v[80:83], v[40:43], v[224:227], v[48:51]
	v_mfma_f32_16x16x32_bf16 v[52:55], v[44:47], v[228:231], v[36:39]
	v_mfma_f32_16x16x32_bf16 v[48:51], v[40:43], v[228:231], v[32:35]
	s_and_b64 vcc, exec, s[6:7]
	s_barrier
	s_cbranch_vccz .LBB0_299
	s_ashr_i32 s51, s50, 31
	s_lshl_b64 s[6:7], s[50:51], 19
	s_add_u32 s6, s10, s6
	s_addc_u32 s7, s11, s7
	s_lshl_b32 s50, s65, 8
	v_lshl_add_u64 v[0:1], v[188:189], 2, s[6:7]
	v_lshlrev_b32_e32 v176, 2, v190
	s_ashr_i32 s51, s50, 31
	v_lshl_add_u64 v[0:1], v[0:1], 0, v[176:177]
	s_lshl_b64 s[6:7], s[50:51], 6
	global_load_dwordx4 v[40:43], v[0:1], off sc1
	s_add_u32 s6, s2, s6
	v_lshl_add_u64 v[2:3], v[0:1], 0, s[14:15]
	global_load_dwordx4 v[44:47], v[2:3], off sc1
	s_addc_u32 s7, s33, s7
	v_lshl_add_u64 v[2:3], v[0:1], 0, s[16:17]
	global_load_dwordx4 v[32:35], v[2:3], off sc1
	v_lshl_add_u64 v[0:1], v[0:1], 0, s[18:19]
	global_load_dwordx4 v[36:39], v[0:1], off sc1
	v_lshl_add_u64 v[12:13], v[184:185], 1, s[6:7]
	global_load_dwordx4 v[0:3], v[12:13], off sc1
	v_lshl_add_u64 v[4:5], v[12:13], 0, s[20:21]
	global_load_dwordx4 v[4:7], v[4:5], off sc1
	v_lshl_add_u64 v[8:9], v[12:13], 0, s[22:23]
	global_load_dwordx4 v[8:11], v[8:9], off sc1
	v_lshl_add_u64 v[12:13], v[12:13], 0, s[24:25]
	global_load_dwordx4 v[12:15], v[12:13], off sc1
	s_branch .LBB0_300

; #define G_LOAD(kt_) do { \
;     if constexpr (AF32) { _Pragma("unroll") for (int i = 0; i < 4; ++i) ld16_sc1(ra[i], Af + (size_t)i * 32 * lda + (kt_) * 32); } \
;     else { _Pragma("unroll") for (int i = 0; i < 2; ++i) ld16_sc1(rab[i], Ab + (size_t)i * 64 * lda + (kt_) * 32); } \
;     _Pragma("unroll") for (int i = 0; i < 4; ++i) ld16_sc1(rb[i], Bp + (size_t)(kt_) * bstep + i * 2048); } while (0)
; template <bool AF32, class Epi>
; __device__ __forceinline__ void gemm_tile(unsigned char* smem, const void* Ap, int lda, const bf16_t* WT, int N, int K, const Epi& epi, int m0, int n0,
;                                           GPre& pr, bool preloaded, const void* nAp, int nn0, bool has_next) {
;     ...
;   if (!preloaded) G_LOAD(0);
;   G_STORE(0);
;   if (nk > 1) G_LOAD(1);
;   __syncthreads();
;   for (int kt = 0; kt < nk; ++kt) {
;     const int cur = kt & 1;
;     if (kt + 1 < nk) G_STORE(cur ^ 1);
;     if (kt + 2 < nk) G_LOAD(kt + 2);
;     const bf16_t* a_s = sbase + cur * G_STAGE + (wr * 64 + l15) * GLD + quad * 8;
;     const bf16_t* b_s = sbase + cur * G_STAGE + 128 * GLD + (wc * 128 + l15) * GLD + quad * 8;
;     __builtin_amdgcn_s_setprio(1);
;     bf16x8 af[4];
; #pragma unroll
;     for (int m = 0; m < 4; ++m) af[m] = *(const bf16x8*)(a_s + m * 16 * GLD);
; #pragma unroll
;     for (int nh = 0; nh < 4; ++nh) {
;       bf16x8 bfr[2];
; #pragma unroll
;       for (int n2 = 0; n2 < 2; ++n2) bfr[n2] = *(const bf16x8*)(b_s + (nh * 2 + n2) * 16 * GLD);
; #pragma unroll
;       for (int m = 0; m < 4; ++m)
; #pragma unroll
;         for (int n2 = 0; n2 < 2; ++n2) acc[m][nh * 2 + n2] = __builtin_amdgcn_mfma_f32_16x16x32_bf16(bfr[n2], af[m], acc[m][nh * 2 + n2], 0, 0, 0);
;     }
;     __builtin_amdgcn_s_setprio(0);
;     __syncthreads();
;   }
.LBB0_358:
	s_and_b32 s3, s53, 1
	s_waitcnt vmcnt(0)
	s_xor_b32 s54, s3, 1
	s_mulk_i32 s54, 0x7800
	v_add_u32_e32 v176, s54, v155
	ds_write_b128 v176, v[0:3]
	ds_write_b128 v176, v[4:7] offset:5120
	ds_write_b128 v176, v[8:11] offset:10240
	ds_write_b128 v176, v[12:15] offset:15360
	ds_write_b128 v176, v[16:19] offset:20480
	ds_write_b128 v176, v[20:23] offset:25600
	global_load_dwordx4 v[0:3], v[162:163], off sc1
	v_lshl_add_u64 v[168:169], v[162:163], 0, s[12:13]
	global_load_dwordx4 v[4:7], v[168:169], off sc1
	global_load_dwordx4 v[8:11], v[160:161], off sc1
	v_lshl_add_u64 v[170:171], v[160:161], 0, s[14:15]
	global_load_dwordx4 v[12:15], v[170:171], off sc1
	v_lshl_add_u64 v[172:173], v[160:161], 0, s[16:17]
	global_load_dwordx4 v[16:19], v[172:173], off sc1
	v_lshl_add_u64 v[174:175], v[160:161], 0, s[18:19]
	global_load_dwordx4 v[20:23], v[174:175], off sc1
	s_add_i32 s53, s53, 1
	s_mulk_i32 s3, 0x7800
	v_add3_u32 v188, s3, v166, v167
	s_setprio 1
	v_add3_u32 v192, s3, v165, v167
	ds_read_b128 v[168:171], v192 offset:10240
	ds_read_b128 v[172:175], v192 offset:11520
	ds_read_b128 v[176:179], v188
	ds_read_b128 v[180:183], v188 offset:1280
	ds_read_b128 v[184:187], v188 offset:2560
	ds_read_b128 v[188:191], v188 offset:3840
	s_waitcnt lgkmcnt(3)
	v_mfma_f32_16x16x32_bf16 v[148:151], v[168:171], v[176:179], v[148:151]
	v_mfma_f32_16x16x32_bf16 v[144:147], v[172:175], v[176:179], v[144:147]
	s_waitcnt lgkmcnt(2)
	v_mfma_f32_16x16x32_bf16 v[132:135], v[168:171], v[180:183], v[132:135]
	v_mfma_f32_16x16x32_bf16 v[128:131], v[172:175], v[180:183], v[128:131]
	s_waitcnt lgkmcnt(1)
	v_mfma_f32_16x16x32_bf16 v[100:103], v[168:171], v[184:187], v[100:103]
	v_mfma_f32_16x16x32_bf16 v[92:95], v[172:175], v[184:187], v[92:95]
	s_waitcnt lgkmcnt(0)
	v_mfma_f32_16x16x32_bf16 v[68:71], v[168:171], v[188:191], v[68:71]
	ds_read_b128 v[168:171], v192 offset:12800
	v_mfma_f32_16x16x32_bf16 v[60:63], v[172:175], v[188:191], v[60:63]
	ds_read_b128 v[172:175], v192 offset:14080
	s_waitcnt lgkmcnt(1)
	v_mfma_f32_16x16x32_bf16 v[140:143], v[168:171], v[176:179], v[140:143]
	s_waitcnt lgkmcnt(0)
	v_mfma_f32_16x16x32_bf16 v[136:139], v[172:175], v[176:179], v[136:139]
	v_mfma_f32_16x16x32_bf16 v[116:119], v[168:171], v[180:183], v[116:119]
	v_mfma_f32_16x16x32_bf16 v[108:111], v[172:175], v[180:183], v[108:111]
	v_mfma_f32_16x16x32_bf16 v[84:87], v[168:171], v[184:187], v[84:87]
	v_mfma_f32_16x16x32_bf16 v[76:79], v[172:175], v[184:187], v[76:79]
	v_mfma_f32_16x16x32_bf16 v[52:55], v[168:171], v[188:191], v[52:55]
	ds_read_b128 v[168:171], v192 offset:15360
	v_mfma_f32_16x16x32_bf16 v[44:47], v[172:175], v[188:191], v[44:47]
	ds_read_b128 v[172:175], v192 offset:16640
	s_waitcnt lgkmcnt(1)
	v_mfma_f32_16x16x32_bf16 v[124:127], v[168:171], v[176:179], v[124:127]
	s_waitcnt lgkmcnt(0)
	v_mfma_f32_16x16x32_bf16 v[120:123], v[172:175], v[176:179], v[120:123]
	v_mfma_f32_16x16x32_bf16 v[96:99], v[168:171], v[180:183], v[96:99]
	v_mfma_f32_16x16x32_bf16 v[88:91], v[172:175], v[180:183], v[88:91]
	v_mfma_f32_16x16x32_bf16 v[64:67], v[168:171], v[184:187], v[64:67]
	v_mfma_f32_16x16x32_bf16 v[56:59], v[172:175], v[184:187], v[56:59]
	v_mfma_f32_16x16x32_bf16 v[36:39], v[168:171], v[188:191], v[36:39]
	ds_read_b128 v[168:171], v192 offset:17920
	v_mfma_f32_16x16x32_bf16 v[32:35], v[172:175], v[188:191], v[32:35]
	ds_read_b128 v[172:175], v192 offset:19200
	s_waitcnt lgkmcnt(1)
	v_mfma_f32_16x16x32_bf16 v[112:115], v[168:171], v[176:179], v[112:115]
	s_waitcnt lgkmcnt(0)
	v_mfma_f32_16x16x32_bf16 v[104:107], v[172:175], v[176:179], v[104:107]
	v_mfma_f32_16x16x32_bf16 v[80:83], v[168:171], v[180:183], v[80:83]
	v_mfma_f32_16x16x32_bf16 v[72:75], v[172:175], v[180:183], v[72:75]
	v_mfma_f32_16x16x32_bf16 v[48:51], v[168:171], v[184:187], v[48:51]
	v_mfma_f32_16x16x32_bf16 v[40:43], v[172:175], v[184:187], v[40:43]
	v_mfma_f32_16x16x32_bf16 v[28:31], v[168:171], v[188:191], v[28:31]
	v_mfma_f32_16x16x32_bf16 v[24:27], v[172:175], v[188:191], v[24:27]
	s_setprio 0
	v_lshl_add_u64 v[160:161], v[160:161], 0, s[22:23]
	s_cmp_eq_u32 s53, 30
	v_lshl_add_u64 v[162:163], v[162:163], 0, 64
	s_barrier
	s_cbranch_scc0 .LBB0_358
	s_waitcnt vmcnt(0)
	ds_write_b128 v155, v[0:3] offset:30720
	ds_write_b128 v155, v[4:7] offset:35840
	ds_write_b128 v155, v[8:11] offset:40960
	ds_write_b128 v155, v[12:15] offset:46080
	ds_write_b128 v155, v[16:19] offset:51200
	ds_write_b128 v155, v[20:23] offset:56320
	v_add_u32_e32 v155, v166, v167
	s_setprio 1
	v_add_u32_e32 v165, v165, v167
	ds_read_b128 v[160:163], v165 offset:10240
	ds_read_b128 v[166:169], v165 offset:11520
	ds_read_b128 v[170:173], v155
	ds_read_b128 v[174:177], v155 offset:1280
	ds_read_b128 v[178:181], v155 offset:2560
	ds_read_b128 v[182:185], v155 offset:3840
	s_waitcnt lgkmcnt(3)
	v_mfma_f32_16x16x32_bf16 v[148:151], v[160:163], v[170:173], v[148:151]
	v_mfma_f32_16x16x32_bf16 v[144:147], v[166:169], v[170:173], v[144:147]
	s_waitcnt lgkmcnt(2)
	v_mfma_f32_16x16x32_bf16 v[132:135], v[160:163], v[174:177], v[132:135]
	v_mfma_f32_16x16x32_bf16 v[128:131], v[166:169], v[174:177], v[128:131]
	s_waitcnt lgkmcnt(1)
	v_mfma_f32_16x16x32_bf16 v[100:103], v[160:163], v[178:181], v[100:103]
	v_mfma_f32_16x16x32_bf16 v[92:95], v[166:169], v[178:181], v[92:95]
	s_waitcnt lgkmcnt(0)
	v_mfma_f32_16x16x32_bf16 v[68:71], v[160:163], v[182:185], v[68:71]
	ds_read_b128 v[160:163], v165 offset:12800
	v_mfma_f32_16x16x32_bf16 v[60:63], v[166:169], v[182:185], v[60:63]
	ds_read_b128 v[166:169], v165 offset:14080
	s_waitcnt lgkmcnt(1)
	v_mfma_f32_16x16x32_bf16 v[186:189], v[160:163], v[170:173], v[140:143]
	s_waitcnt lgkmcnt(0)
; #define G_LOAD(kt_) do { \
;     if constexpr (AF32) { _Pragma("unroll") for (int i = 0; i < 4; ++i) ld16_sc1(ra[i], Af + (size_t)i * 32 * lda + (kt_) * 32); } \
;     else { _Pragma("unroll") for (int i = 0; i < 2; ++i) ld16_sc1(rab[i], Ab + (size_t)i * 64 * lda + (kt_) * 32); } \
;     _Pragma("unroll") for (int i = 0; i < 4; ++i) ld16_sc1(rb[i], Bp + (size_t)(kt_) * bstep + i * 2048); } while (0)
; template <bool AF32, class Epi>
; __device__ __forceinline__ void gemm_tile(unsigned char* smem, const void* Ap, int lda, const bf16_t* WT, int N, int K, const Epi& epi, int m0, int n0,
;                                           GPre& pr, bool preloaded, const void* nAp, int nn0, bool has_next) {
;     ...
;     const bf16_t* a_s = sbase + cur * G_STAGE + (wr * 64 + l15) * GLD + quad * 8;
;     const bf16_t* b_s = sbase + cur * G_STAGE + 128 * GLD + (wc * 128 + l15) * GLD + quad * 8;
;     __builtin_amdgcn_s_setprio(1);
;     bf16x8 af[4];
; #pragma unroll
;     for (int m = 0; m < 4; ++m) af[m] = *(const bf16x8*)(a_s + m * 16 * GLD);
; #pragma unroll
;     for (int nh = 0; nh < 4; ++nh) {
;       bf16x8 bfr[2];
; #pragma unroll
;       for (int n2 = 0; n2 < 2; ++n2) bfr[n2] = *(const bf16x8*)(b_s + (nh * 2 + n2) * 16 * GLD);
; #pragma unroll
;       for (int m = 0; m < 4; ++m)
; #pragma unroll
;         for (int n2 = 0; n2 < 2; ++n2) acc[m][nh * 2 + n2] = __builtin_amdgcn_mfma_f32_16x16x32_bf16(bfr[n2], af[m], acc[m][nh * 2 + n2], 0, 0, 0);
;     }
;     __builtin_amdgcn_s_setprio(0);
;     __syncthreads();
;   }
;   if (has_next) {
;     const float* Af = (const float*)nAp + (size_t)(tid >> 3) * lda + (tid & 7) * 4;
;     const bf16_t* Ab = (const bf16_t*)nAp + (size_t)(tid >> 2) * lda + (tid & 3) * 8;
;     const bf16_t* Bp = WT + (size_t)nn0 * 32 + tid * 8;
;     G_LOAD(0);
;   }
	v_mfma_f32_16x16x32_bf16 v[136:139], v[166:169], v[170:173], v[136:139]
	v_mfma_f32_16x16x32_bf16 v[190:193], v[160:163], v[174:177], v[116:119]
	v_mfma_f32_16x16x32_bf16 v[194:197], v[166:169], v[174:177], v[108:111]
	v_mfma_f32_16x16x32_bf16 v[198:201], v[160:163], v[178:181], v[84:87]
	v_mfma_f32_16x16x32_bf16 v[202:205], v[166:169], v[178:181], v[76:79]
	v_mfma_f32_16x16x32_bf16 v[160:163], v[160:163], v[182:185], v[52:55]
	s_nop 2
	ds_read_b128 v[52:55], v165 offset:15360
	v_mfma_f32_16x16x32_bf16 v[166:169], v[166:169], v[182:185], v[44:47]
	s_nop 2
	ds_read_b128 v[44:47], v165 offset:16640
	s_waitcnt lgkmcnt(1)
	v_mfma_f32_16x16x32_bf16 v[124:127], v[52:55], v[170:173], v[124:127]
	s_waitcnt lgkmcnt(0)
	v_mfma_f32_16x16x32_bf16 v[120:123], v[44:47], v[170:173], v[120:123]
	v_mfma_f32_16x16x32_bf16 v[96:99], v[52:55], v[174:177], v[96:99]
	v_mfma_f32_16x16x32_bf16 v[88:91], v[44:47], v[174:177], v[88:91]
	v_mfma_f32_16x16x32_bf16 v[64:67], v[52:55], v[178:181], v[64:67]
	v_mfma_f32_16x16x32_bf16 v[56:59], v[44:47], v[178:181], v[56:59]
	v_mfma_f32_16x16x32_bf16 v[36:39], v[52:55], v[182:185], v[36:39]
	ds_read_b128 v[52:55], v165 offset:17920
	v_mfma_f32_16x16x32_bf16 v[32:35], v[44:47], v[182:185], v[32:35]
	ds_read_b128 v[44:47], v165 offset:19200
	s_waitcnt lgkmcnt(1)
	v_mfma_f32_16x16x32_bf16 v[28:31], v[52:55], v[182:185], v[28:31]
	s_waitcnt lgkmcnt(0)
	v_mfma_f32_16x16x32_bf16 v[24:27], v[44:47], v[182:185], v[24:27]
	v_mfma_f32_16x16x32_bf16 v[206:209], v[52:55], v[170:173], v[112:115]
	v_mfma_f32_16x16x32_bf16 v[170:173], v[44:47], v[170:173], v[104:107]
	v_mfma_f32_16x16x32_bf16 v[212:215], v[52:55], v[174:177], v[80:83]
	v_mfma_f32_16x16x32_bf16 v[174:177], v[44:47], v[174:177], v[72:75]
	v_mfma_f32_16x16x32_bf16 v[216:219], v[52:55], v[178:181], v[48:51]
	v_mfma_f32_16x16x32_bf16 v[178:181], v[44:47], v[178:181], v[40:43]
	s_setprio 0
	s_barrier
	s_setprio 1
	ds_read_b128 v[40:43], v165 offset:40960
	ds_read_b128 v[44:47], v165 offset:42240
	ds_read_b128 v[182:185], v155 offset:30720
	ds_read_b128 v[220:223], v155 offset:32000
	ds_read_b128 v[224:227], v155 offset:33280
	ds_read_b128 v[228:231], v155 offset:34560
	s_waitcnt lgkmcnt(3)
	v_mfma_f32_16x16x32_bf16 v[148:151], v[40:43], v[182:185], v[148:151]
	s_waitcnt lgkmcnt(2)
	v_mfma_f32_16x16x32_bf16 v[116:119], v[40:43], v[220:223], v[132:135]
	s_waitcnt lgkmcnt(1)
	v_mfma_f32_16x16x32_bf16 v[84:87], v[40:43], v[224:227], v[100:103]
	s_waitcnt lgkmcnt(0)
	v_mfma_f32_16x16x32_bf16 v[52:55], v[40:43], v[228:231], v[68:71]
	ds_read_b128 v[40:43], v165 offset:43520
	v_mfma_f32_16x16x32_bf16 v[48:51], v[44:47], v[228:231], v[60:63]
	s_nop 2
	ds_read_b128 v[60:63], v165 offset:44800
	v_mfma_f32_16x16x32_bf16 v[140:143], v[44:47], v[182:185], v[144:147]
	v_mfma_f32_16x16x32_bf16 v[108:111], v[44:47], v[220:223], v[128:131]
	v_mfma_f32_16x16x32_bf16 v[80:83], v[44:47], v[224:227], v[92:95]
	s_waitcnt lgkmcnt(1)
	v_mfma_f32_16x16x32_bf16 v[144:147], v[40:43], v[182:185], v[186:189]
	s_nop 0
	ds_read_b128 v[92:95], v165 offset:46080
	s_waitcnt lgkmcnt(1)
	v_mfma_f32_16x16x32_bf16 v[136:139], v[60:63], v[182:185], v[136:139]
	v_mfma_f32_16x16x32_bf16 v[112:115], v[40:43], v[220:223], v[190:193]
	v_mfma_f32_16x16x32_bf16 v[104:107], v[60:63], v[220:223], v[194:197]
	v_mfma_f32_16x16x32_bf16 v[76:79], v[40:43], v[224:227], v[198:201]
	v_mfma_f32_16x16x32_bf16 v[72:75], v[60:63], v[224:227], v[202:205]
	v_mfma_f32_16x16x32_bf16 v[44:47], v[40:43], v[228:231], v[160:163]
	v_mfma_f32_16x16x32_bf16 v[40:43], v[60:63], v[228:231], v[166:169]
	ds_read_b128 v[60:63], v165 offset:47360
	s_nop 0
	ds_read_b128 v[160:163], v165 offset:48640
	ds_read_b128 v[166:169], v165 offset:49920
	s_waitcnt lgkmcnt(3)
	v_mfma_f32_16x16x32_bf16 v[132:135], v[92:95], v[182:185], v[124:127]
	s_waitcnt lgkmcnt(2)
	v_mfma_f32_16x16x32_bf16 v[128:131], v[60:63], v[182:185], v[120:123]
	v_mfma_f32_16x16x32_bf16 v[100:103], v[92:95], v[220:223], v[96:99]
	v_mfma_f32_16x16x32_bf16 v[96:99], v[60:63], v[220:223], v[88:91]
	v_mfma_f32_16x16x32_bf16 v[68:71], v[92:95], v[224:227], v[64:67]
	v_mfma_f32_16x16x32_bf16 v[64:67], v[60:63], v[224:227], v[56:59]
	v_mfma_f32_16x16x32_bf16 v[36:39], v[92:95], v[228:231], v[36:39]
	v_mfma_f32_16x16x32_bf16 v[32:35], v[60:63], v[228:231], v[32:35]
	s_waitcnt lgkmcnt(1)
	v_mfma_f32_16x16x32_bf16 v[124:127], v[160:163], v[182:185], v[206:209]
	s_waitcnt lgkmcnt(0)
	v_mfma_f32_16x16x32_bf16 v[120:123], v[166:169], v[182:185], v[170:173]
	v_mfma_f32_16x16x32_bf16 v[92:95], v[160:163], v[220:223], v[212:215]
	v_mfma_f32_16x16x32_bf16 v[88:91], v[166:169], v[220:223], v[174:177]
	v_mfma_f32_16x16x32_bf16 v[60:63], v[160:163], v[224:227], v[216:219]
	v_mfma_f32_16x16x32_bf16 v[56:59], v[166:169], v[224:227], v[178:181]
	v_mfma_f32_16x16x32_bf16 v[28:31], v[160:163], v[228:231], v[28:31]
	v_mfma_f32_16x16x32_bf16 v[24:27], v[166:169], v[228:231], v[24:27]
	s_and_b64 vcc, exec, s[48:49]
	s_barrier
	s_cbranch_vccz .LBB0_346
	s_ashr_i32 s53, s52, 31
	s_lshl_b64 s[48:49], s[52:53], 18
	s_add_u32 s48, s2, s48
	s_addc_u32 s49, s33, s49
	s_lshl_b32 s52, s68, 8
	s_ashr_i32 s53, s52, 31
	v_lshl_add_u64 v[0:1], v[158:159], 1, s[48:49]
	s_lshl_b64 s[48:49], s[52:53], 6
	v_lshl_add_u64 v[4:5], v[0:1], 0, v[152:153]
	s_add_u32 s48, s58, s48
	s_addc_u32 s49, s59, s49
	global_load_dwordx4 v[0:3], v[4:5], off sc1
	v_lshl_add_u64 v[4:5], v[4:5], 0, s[12:13]
	global_load_dwordx4 v[4:7], v[4:5], off sc1
	v_lshl_add_u64 v[20:21], v[156:157], 1, s[48:49]
	global_load_dwordx4 v[8:11], v[20:21], off sc1
	v_lshl_add_u64 v[12:13], v[20:21], 0, s[14:15]
	global_load_dwordx4 v[12:15], v[12:13], off sc1
	v_lshl_add_u64 v[16:17], v[20:21], 0, s[16:17]
	global_load_dwordx4 v[16:19], v[16:17], off sc1
	v_lshl_add_u64 v[20:21], v[20:21], 0, s[18:19]
	global_load_dwordx4 v[20:23], v[20:21], off sc1
	s_branch .LBB0_346

; #define G_LOAD(kt_) do { \
;     if constexpr (AF32) { _Pragma("unroll") for (int i = 0; i < 4; ++i) ld16_sc1(ra[i], Af + (size_t)i * 32 * lda + (kt_) * 32); } \
;     else { _Pragma("unroll") for (int i = 0; i < 2; ++i) ld16_sc1(rab[i], Ab + (size_t)i * 64 * lda + (kt_) * 32); } \
;     _Pragma("unroll") for (int i = 0; i < 4; ++i) ld16_sc1(rb[i], Bp + (size_t)(kt_) * bstep + i * 2048); } while (0)
; template <bool AF32, class Epi>
; __device__ __forceinline__ void gemm_tile(unsigned char* smem, const void* Ap, int lda, const bf16_t* WT, int N, int K, const Epi& epi, int m0, int n0,
;                                           GPre& pr, bool preloaded, const void* nAp, int nn0, bool has_next) {
;     ...
;   if (!preloaded) G_LOAD(0);
;   G_STORE(0);
;   if (nk > 1) G_LOAD(1);
;   __syncthreads();
;   for (int kt = 0; kt < nk; ++kt) {
;     const int cur = kt & 1;
;     if (kt + 1 < nk) G_STORE(cur ^ 1);
;     if (kt + 2 < nk) G_LOAD(kt + 2);
;     const bf16_t* a_s = sbase + cur * G_STAGE + (wr * 64 + l15) * GLD + quad * 8;
;     const bf16_t* b_s = sbase + cur * G_STAGE + 128 * GLD + (wc * 128 + l15) * GLD + quad * 8;
;     __builtin_amdgcn_s_setprio(1);
;     bf16x8 af[4];
; #pragma unroll
;     for (int m = 0; m < 4; ++m) af[m] = *(const bf16x8*)(a_s + m * 16 * GLD);
; #pragma unroll
;     for (int nh = 0; nh < 4; ++nh) {
;       bf16x8 bfr[2];
; #pragma unroll
;       for (int n2 = 0; n2 < 2; ++n2) bfr[n2] = *(const bf16x8*)(b_s + (nh * 2 + n2) * 16 * GLD);
; #pragma unroll
;       for (int m = 0; m < 4; ++m)
; #pragma unroll
;         for (int n2 = 0; n2 < 2; ++n2) acc[m][nh * 2 + n2] = __builtin_amdgcn_mfma_f32_16x16x32_bf16(bfr[n2], af[m], acc[m][nh * 2 + n2], 0, 0, 0);
;     }
;     __builtin_amdgcn_s_setprio(0);
;     __syncthreads();
;   }
.LBB0_389:
	s_and_b32 s3, s51, 1
	s_waitcnt vmcnt(0)
	s_xor_b32 s52, s3, 1
	s_mulk_i32 s52, 0x7800
	v_cvt_pk_bf16_f32 v202, v44, v45
	v_mov_b32_e32 v205, v44
	v_mov_b32_e32 v44, v41
	v_lshl_add_u32 v171, v160, 1, s52
	v_cvt_pk_bf16_f32 v203, v46, v47
	v_mov_b32_e32 v204, v40
	v_mov_b32_e32 v206, v42
	v_mov_b32_e32 v207, v46
	v_mov_b32_e32 v46, v43
	v_cvt_pk_bf16_f32 v40, v40, v41
	v_cvt_pk_bf16_f32 v41, v42, v43
	v_cvt_pk_bf16_f32 v42, v36, v37
	v_cvt_pk_bf16_f32 v43, v38, v39
	v_mov_b32_e32 v208, v32
	v_mov_b32_e32 v209, v36
	v_mov_b32_e32 v36, v33
	v_mov_b32_e32 v212, v34
	v_mov_b32_e32 v213, v38
	v_mov_b32_e32 v38, v35
	v_cvt_pk_bf16_f32 v32, v32, v33
	v_cvt_pk_bf16_f32 v33, v34, v35
	v_pk_mul_f32 v[34:35], v[44:45], v[44:45]
	v_lshl_add_u32 v176, v162, 1, s52
	ds_write2st64_b64 v171, v[202:203], v[40:41] offset1:5
	ds_write2st64_b64 v171, v[42:43], v[32:33] offset0:10 offset1:15
	ds_write_b128 v176, v[0:3] offset:10240
	ds_write_b128 v176, v[4:7] offset:15360
	ds_write_b128 v176, v[8:11] offset:20480
	ds_write_b128 v176, v[12:15] offset:25600
	v_pk_fma_f32 v[0:1], v[204:205], v[204:205], v[34:35]
	v_pk_mul_f32 v[36:37], v[36:37], v[36:37]
	v_pk_fma_f32 v[0:1], v[206:207], v[206:207], v[0:1]
	v_pk_fma_f32 v[2:3], v[208:209], v[208:209], v[36:37]
	v_pk_fma_f32 v[202:203], v[46:47], v[46:47], v[0:1]
	global_load_dwordx4 v[44:47], v[166:167], off sc1
	v_lshl_add_u64 v[172:173], v[166:167], 0, s[16:17]
	v_pk_fma_f32 v[2:3], v[212:213], v[212:213], v[2:3]
	global_load_dwordx4 v[40:43], v[172:173], off sc1
	v_lshl_add_u64 v[174:175], v[166:167], 0, s[18:19]
	v_pk_fma_f32 v[204:205], v[38:39], v[38:39], v[2:3]
	global_load_dwordx4 v[36:39], v[174:175], off sc1
	v_lshl_add_u64 v[194:195], v[166:167], 0, s[20:21]
	global_load_dwordx4 v[32:35], v[194:195], off sc1
	global_load_dwordx4 v[0:3], v[164:165], off sc1
	v_lshl_add_u64 v[196:197], v[164:165], 0, s[22:23]
	global_load_dwordx4 v[4:7], v[196:197], off sc1
	v_lshl_add_u64 v[198:199], v[164:165], 0, s[24:25]
	global_load_dwordx4 v[8:11], v[198:199], off sc1
	v_lshl_add_u64 v[200:201], v[164:165], 0, s[26:27]
	global_load_dwordx4 v[12:15], v[200:201], off sc1
	s_add_i32 s51, s51, 1
	s_mulk_i32 s3, 0x7800
	v_pk_add_f32 v[184:185], v[184:185], v[202:203]
	v_pk_add_f32 v[180:181], v[180:181], v[204:205]
	v_add3_u32 v171, s3, v169, v170
	s_setprio 1
	v_add3_u32 v176, s3, v168, v170
	ds_read_b128 v[172:175], v176 offset:10240
	ds_read_b128 v[194:197], v176 offset:11520
	ds_read_b128 v[198:201], v171
	ds_read_b128 v[202:205], v171 offset:1280
	ds_read_b128 v[206:209], v171 offset:2560
	ds_read_b128 v[212:215], v171 offset:3840
	s_waitcnt lgkmcnt(3)
	v_mfma_f32_16x16x32_bf16 v[156:159], v[172:175], v[198:201], v[156:159]
	v_mfma_f32_16x16x32_bf16 v[152:155], v[194:197], v[198:201], v[152:155]
	s_waitcnt lgkmcnt(2)
	v_mfma_f32_16x16x32_bf16 v[140:143], v[172:175], v[202:205], v[140:143]
	v_mfma_f32_16x16x32_bf16 v[136:139], v[194:197], v[202:205], v[136:139]
	s_waitcnt lgkmcnt(1)
	v_mfma_f32_16x16x32_bf16 v[108:111], v[172:175], v[206:209], v[108:111]
	v_mfma_f32_16x16x32_bf16 v[100:103], v[194:197], v[206:209], v[100:103]
	s_waitcnt lgkmcnt(0)
	v_mfma_f32_16x16x32_bf16 v[76:79], v[172:175], v[212:215], v[76:79]
	ds_read_b128 v[172:175], v176 offset:12800
	v_mfma_f32_16x16x32_bf16 v[68:71], v[194:197], v[212:215], v[68:71]
	ds_read_b128 v[194:197], v176 offset:14080
	s_waitcnt lgkmcnt(1)
	v_mfma_f32_16x16x32_bf16 v[148:151], v[172:175], v[198:201], v[148:151]
	s_waitcnt lgkmcnt(0)
	v_mfma_f32_16x16x32_bf16 v[144:147], v[194:197], v[198:201], v[144:147]
	v_mfma_f32_16x16x32_bf16 v[124:127], v[172:175], v[202:205], v[124:127]
	v_mfma_f32_16x16x32_bf16 v[116:119], v[194:197], v[202:205], v[116:119]
	v_mfma_f32_16x16x32_bf16 v[92:95], v[172:175], v[206:209], v[92:95]
	v_mfma_f32_16x16x32_bf16 v[84:87], v[194:197], v[206:209], v[84:87]
	v_mfma_f32_16x16x32_bf16 v[60:63], v[172:175], v[212:215], v[60:63]
	ds_read_b128 v[172:175], v176 offset:15360
	v_mfma_f32_16x16x32_bf16 v[52:55], v[194:197], v[212:215], v[52:55]
	ds_read_b128 v[194:197], v176 offset:16640
	s_waitcnt lgkmcnt(1)
	v_mfma_f32_16x16x32_bf16 v[132:135], v[172:175], v[198:201], v[132:135]
	s_waitcnt lgkmcnt(0)
	v_mfma_f32_16x16x32_bf16 v[128:131], v[194:197], v[198:201], v[128:131]
	v_mfma_f32_16x16x32_bf16 v[104:107], v[172:175], v[202:205], v[104:107]
	v_mfma_f32_16x16x32_bf16 v[96:99], v[194:197], v[202:205], v[96:99]
	v_mfma_f32_16x16x32_bf16 v[72:75], v[172:175], v[206:209], v[72:75]
	v_mfma_f32_16x16x32_bf16 v[64:67], v[194:197], v[206:209], v[64:67]
	v_mfma_f32_16x16x32_bf16 v[28:31], v[172:175], v[212:215], v[28:31]
	ds_read_b128 v[172:175], v176 offset:17920
	v_mfma_f32_16x16x32_bf16 v[24:27], v[194:197], v[212:215], v[24:27]
	ds_read_b128 v[194:197], v176 offset:19200
	s_waitcnt lgkmcnt(1)
	v_mfma_f32_16x16x32_bf16 v[120:123], v[172:175], v[198:201], v[120:123]
	s_waitcnt lgkmcnt(0)
	v_mfma_f32_16x16x32_bf16 v[112:115], v[194:197], v[198:201], v[112:115]
	v_mfma_f32_16x16x32_bf16 v[88:91], v[172:175], v[202:205], v[88:91]
	v_mfma_f32_16x16x32_bf16 v[80:83], v[194:197], v[202:205], v[80:83]
	v_mfma_f32_16x16x32_bf16 v[56:59], v[172:175], v[206:209], v[56:59]
	v_mfma_f32_16x16x32_bf16 v[48:51], v[194:197], v[206:209], v[48:51]
	v_mfma_f32_16x16x32_bf16 v[20:23], v[172:175], v[212:215], v[20:23]
	v_mfma_f32_16x16x32_bf16 v[16:19], v[194:197], v[212:215], v[16:19]
	s_setprio 0
	v_lshl_add_u64 v[164:165], v[164:165], 0, s[38:39]
	s_cmp_eq_u32 s51, 30
	v_lshl_add_u64 v[166:167], v[166:167], 0, s[28:29]
	s_barrier
	s_cbranch_scc0 .LBB0_389
; #define G_LOAD(kt_) do { \
;     if constexpr (AF32) { _Pragma("unroll") for (int i = 0; i < 4; ++i) ld16_sc1(ra[i], Af + (size_t)i * 32 * lda + (kt_) * 32); } \
;     else { _Pragma("unroll") for (int i = 0; i < 2; ++i) ld16_sc1(rab[i], Ab + (size_t)i * 64 * lda + (kt_) * 32); } \
;     _Pragma("unroll") for (int i = 0; i < 4; ++i) ld16_sc1(rb[i], Bp + (size_t)(kt_) * bstep + i * 2048); } while (0)
; template <bool AF32, class Epi>
; __device__ __forceinline__ void gemm_tile(unsigned char* smem, const void* Ap, int lda, const bf16_t* WT, int N, int K, const Epi& epi, int m0, int n0,
;                                           GPre& pr, bool preloaded, const void* nAp, int nn0, bool has_next) {
;     ...
;   if (!preloaded) G_LOAD(0);
;   G_STORE(0);
;   if (nk > 1) G_LOAD(1);
;   __syncthreads();
;   for (int kt = 0; kt < nk; ++kt) {
;     const int cur = kt & 1;
;     if (kt + 1 < nk) G_STORE(cur ^ 1);
;     if (kt + 2 < nk) G_LOAD(kt + 2);
;     const bf16_t* a_s = sbase + cur * G_STAGE + (wr * 64 + l15) * GLD + quad * 8;
;     const bf16_t* b_s = sbase + cur * G_STAGE + 128 * GLD + (wc * 128 + l15) * GLD + quad * 8;
;     __builtin_amdgcn_s_setprio(1);
;     bf16x8 af[4];
; #pragma unroll
;     for (int m = 0; m < 4; ++m) af[m] = *(const bf16x8*)(a_s + m * 16 * GLD);
; #pragma unroll
;     for (int nh = 0; nh < 4; ++nh) {
;       bf16x8 bfr[2];
; #pragma unroll
;       for (int n2 = 0; n2 < 2; ++n2) bfr[n2] = *(const bf16x8*)(b_s + (nh * 2 + n2) * 16 * GLD);
; #pragma unroll
;       for (int m = 0; m < 4; ++m)
; #pragma unroll
;         for (int n2 = 0; n2 < 2; ++n2) acc[m][nh * 2 + n2] = __builtin_amdgcn_mfma_f32_16x16x32_bf16(bfr[n2], af[m], acc[m][nh * 2 + n2], 0, 0, 0);
;     }
;     __builtin_amdgcn_s_setprio(0);
;     __syncthreads();
	s_waitcnt vmcnt(0)
	v_add_u32_e32 v176, v169, v170
	v_cvt_pk_bf16_f32 v164, v44, v45
	v_cvt_pk_bf16_f32 v165, v46, v47
	v_cvt_pk_bf16_f32 v166, v40, v41
	v_cvt_pk_bf16_f32 v167, v42, v43
	ds_write2st64_b64 v161, v[164:165], v[166:167] offset0:60 offset1:65
	v_cvt_pk_bf16_f32 v164, v36, v37
	v_cvt_pk_bf16_f32 v165, v38, v39
	v_cvt_pk_bf16_f32 v166, v32, v33
	v_cvt_pk_bf16_f32 v167, v34, v35
	ds_write2st64_b64 v161, v[164:165], v[166:167] offset0:70 offset1:75
	ds_write_b128 v163, v[0:3] offset:40960
	ds_write_b128 v163, v[4:7] offset:46080
	ds_write_b128 v163, v[8:11] offset:51200
	ds_write_b128 v163, v[12:15] offset:56320
	s_setprio 1
	v_add_u32_e32 v193, v168, v170
	ds_read_b128 v[160:163], v193 offset:10240
	ds_read_b128 v[164:167], v193 offset:11520
	ds_read_b128 v[168:171], v176
	ds_read_b128 v[172:175], v176 offset:1280
	ds_read_b128 v[194:197], v176 offset:2560
	ds_read_b128 v[198:201], v176 offset:3840
	s_waitcnt lgkmcnt(3)
	v_mfma_f32_16x16x32_bf16 v[156:159], v[160:163], v[168:171], v[156:159]
	v_mfma_f32_16x16x32_bf16 v[152:155], v[164:167], v[168:171], v[152:155]
	s_waitcnt lgkmcnt(2)
	v_mfma_f32_16x16x32_bf16 v[140:143], v[160:163], v[172:175], v[140:143]
	v_mfma_f32_16x16x32_bf16 v[136:139], v[164:167], v[172:175], v[136:139]
	s_waitcnt lgkmcnt(1)
	v_mfma_f32_16x16x32_bf16 v[108:111], v[160:163], v[194:197], v[108:111]
	v_mfma_f32_16x16x32_bf16 v[100:103], v[164:167], v[194:197], v[100:103]
	s_waitcnt lgkmcnt(0)
	v_mfma_f32_16x16x32_bf16 v[76:79], v[160:163], v[198:201], v[76:79]
	ds_read_b128 v[160:163], v193 offset:12800
	v_mfma_f32_16x16x32_bf16 v[68:71], v[164:167], v[198:201], v[68:71]
	ds_read_b128 v[164:167], v193 offset:14080
	s_waitcnt lgkmcnt(1)
	v_mfma_f32_16x16x32_bf16 v[148:151], v[160:163], v[168:171], v[148:151]
	s_waitcnt lgkmcnt(0)
	v_mfma_f32_16x16x32_bf16 v[144:147], v[164:167], v[168:171], v[144:147]
	v_mfma_f32_16x16x32_bf16 v[124:127], v[160:163], v[172:175], v[124:127]
	v_mfma_f32_16x16x32_bf16 v[116:119], v[164:167], v[172:175], v[116:119]
	v_mfma_f32_16x16x32_bf16 v[92:95], v[160:163], v[194:197], v[92:95]
	v_mfma_f32_16x16x32_bf16 v[84:87], v[164:167], v[194:197], v[84:87]
	v_mfma_f32_16x16x32_bf16 v[60:63], v[160:163], v[198:201], v[60:63]
	ds_read_b128 v[160:163], v193 offset:15360
	v_mfma_f32_16x16x32_bf16 v[52:55], v[164:167], v[198:201], v[52:55]
	ds_read_b128 v[164:167], v193 offset:16640
	s_waitcnt lgkmcnt(1)
	v_mfma_f32_16x16x32_bf16 v[220:223], v[160:163], v[194:197], v[72:75]
	s_nop 2
	ds_read_b128 v[72:75], v193 offset:19200
	s_waitcnt lgkmcnt(1)
	v_mfma_f32_16x16x32_bf16 v[224:227], v[164:167], v[194:197], v[64:67]
	s_nop 2
	ds_read_b128 v[64:67], v193 offset:17920
	s_waitcnt lgkmcnt(1)
	v_mfma_f32_16x16x32_bf16 v[112:115], v[72:75], v[168:171], v[112:115]
	v_mfma_f32_16x16x32_bf16 v[80:83], v[72:75], v[172:175], v[80:83]
	v_mfma_f32_16x16x32_bf16 v[48:51], v[72:75], v[194:197], v[48:51]
	v_mfma_f32_16x16x32_bf16 v[202:205], v[160:163], v[168:171], v[132:135]
	v_mfma_f32_16x16x32_bf16 v[206:209], v[164:167], v[168:171], v[128:131]
	v_mfma_f32_16x16x32_bf16 v[212:215], v[160:163], v[172:175], v[104:107]
	v_mfma_f32_16x16x32_bf16 v[216:219], v[164:167], v[172:175], v[96:99]
	v_mfma_f32_16x16x32_bf16 v[28:31], v[160:163], v[198:201], v[28:31]
	v_mfma_f32_16x16x32_bf16 v[24:27], v[164:167], v[198:201], v[24:27]
	s_waitcnt lgkmcnt(0)
	v_mfma_f32_16x16x32_bf16 v[228:231], v[64:67], v[168:171], v[120:123]
	v_mfma_f32_16x16x32_bf16 v[232:235], v[64:67], v[172:175], v[88:91]
	v_mfma_f32_16x16x32_bf16 v[236:239], v[64:67], v[194:197], v[56:59]
	v_mfma_f32_16x16x32_bf16 v[20:23], v[64:67], v[198:201], v[20:23]
	v_mfma_f32_16x16x32_bf16 v[16:19], v[72:75], v[198:201], v[16:19]
	s_setprio 0
	s_barrier
; #define G_LOAD(kt_) do { \
;     if constexpr (AF32) { _Pragma("unroll") for (int i = 0; i < 4; ++i) ld16_sc1(ra[i], Af + (size_t)i * 32 * lda + (kt_) * 32); } \
;     else { _Pragma("unroll") for (int i = 0; i < 2; ++i) ld16_sc1(rab[i], Ab + (size_t)i * 64 * lda + (kt_) * 32); } \
;     _Pragma("unroll") for (int i = 0; i < 4; ++i) ld16_sc1(rb[i], Bp + (size_t)(kt_) * bstep + i * 2048); } while (0)
; template <bool AF32, class Epi>
; __device__ __forceinline__ void gemm_tile(unsigned char* smem, const void* Ap, int lda, const bf16_t* WT, int N, int K, const Epi& epi, int m0, int n0,
;                                           GPre& pr, bool preloaded, const void* nAp, int nn0, bool has_next) {
;     ...
;     const bf16_t* a_s = sbase + cur * G_STAGE + (wr * 64 + l15) * GLD + quad * 8;
;     const bf16_t* b_s = sbase + cur * G_STAGE + 128 * GLD + (wc * 128 + l15) * GLD + quad * 8;
;     __builtin_amdgcn_s_setprio(1);
;     bf16x8 af[4];
; #pragma unroll
;     for (int m = 0; m < 4; ++m) af[m] = *(const bf16x8*)(a_s + m * 16 * GLD);
; #pragma unroll
;     for (int nh = 0; nh < 4; ++nh) {
;       bf16x8 bfr[2];
; #pragma unroll
;       for (int n2 = 0; n2 < 2; ++n2) bfr[n2] = *(const bf16x8*)(b_s + (nh * 2 + n2) * 16 * GLD);
; #pragma unroll
;       for (int m = 0; m < 4; ++m)
; #pragma unroll
;         for (int n2 = 0; n2 < 2; ++n2) acc[m][nh * 2 + n2] = __builtin_amdgcn_mfma_f32_16x16x32_bf16(bfr[n2], af[m], acc[m][nh * 2 + n2], 0, 0, 0);
;     }
;     __builtin_amdgcn_s_setprio(0);
;     __syncthreads();
;   }
;   if (has_next) {
;     const float* Af = (const float*)nAp + (size_t)(tid >> 3) * lda + (tid & 7) * 4;
;     const bf16_t* Ab = (const bf16_t*)nAp + (size_t)(tid >> 2) * lda + (tid & 3) * 8;
;     const bf16_t* Bp = WT + (size_t)nn0 * 32 + tid * 8;
;     G_LOAD(0);
;   }
	s_setprio 1
	ds_read_b128 v[56:59], v193 offset:40960
	ds_read_b128 v[64:67], v193 offset:42240
	ds_read_b128 v[194:197], v176 offset:30720
	ds_read_b128 v[198:201], v176 offset:32000
	ds_read_b128 v[240:243], v176 offset:33280
	ds_read_b128 v[244:247], v176 offset:34560
	s_waitcnt lgkmcnt(3)
	v_mfma_f32_16x16x32_bf16 v[172:175], v[56:59], v[194:197], v[156:159]
	v_mfma_f32_16x16x32_bf16 v[168:171], v[64:67], v[194:197], v[152:155]
	s_waitcnt lgkmcnt(2)
	v_mfma_f32_16x16x32_bf16 v[140:143], v[56:59], v[198:201], v[140:143]
	v_mfma_f32_16x16x32_bf16 v[136:139], v[64:67], v[198:201], v[136:139]
	s_waitcnt lgkmcnt(1)
	v_mfma_f32_16x16x32_bf16 v[108:111], v[56:59], v[240:243], v[108:111]
	v_mfma_f32_16x16x32_bf16 v[104:107], v[64:67], v[240:243], v[100:103]
	s_waitcnt lgkmcnt(0)
	v_mfma_f32_16x16x32_bf16 v[76:79], v[56:59], v[244:247], v[76:79]
	ds_read_b128 v[56:59], v193 offset:43520
	v_mfma_f32_16x16x32_bf16 v[72:75], v[64:67], v[244:247], v[68:71]
	ds_read_b128 v[64:67], v193 offset:44800
	s_waitcnt lgkmcnt(1)
	v_mfma_f32_16x16x32_bf16 v[164:167], v[56:59], v[194:197], v[148:151]
	s_waitcnt lgkmcnt(0)
	v_mfma_f32_16x16x32_bf16 v[160:163], v[64:67], v[194:197], v[144:147]
	v_mfma_f32_16x16x32_bf16 v[132:135], v[56:59], v[198:201], v[124:127]
	v_mfma_f32_16x16x32_bf16 v[128:131], v[64:67], v[198:201], v[116:119]
	v_mfma_f32_16x16x32_bf16 v[100:103], v[56:59], v[240:243], v[92:95]
	v_mfma_f32_16x16x32_bf16 v[96:99], v[64:67], v[240:243], v[84:87]
	v_mfma_f32_16x16x32_bf16 v[68:71], v[56:59], v[244:247], v[60:63]
	ds_read_b128 v[56:59], v193 offset:46080
	v_mfma_f32_16x16x32_bf16 v[64:67], v[64:67], v[244:247], v[52:55]
	s_nop 2
	ds_read_b128 v[52:55], v193 offset:47360
	s_waitcnt lgkmcnt(1)
	v_mfma_f32_16x16x32_bf16 v[156:159], v[56:59], v[194:197], v[202:205]
	v_mfma_f32_16x16x32_bf16 v[124:127], v[56:59], v[198:201], v[212:215]
	v_mfma_f32_16x16x32_bf16 v[92:95], v[56:59], v[240:243], v[220:223]
	v_mfma_f32_16x16x32_bf16 v[60:63], v[56:59], v[244:247], v[28:31]
	s_nop 2
	ds_read_b128 v[28:31], v193 offset:48640
	s_waitcnt lgkmcnt(1)
	v_mfma_f32_16x16x32_bf16 v[56:59], v[52:55], v[244:247], v[24:27]
	s_nop 2
	ds_read_b128 v[24:27], v193 offset:49920
	v_mfma_f32_16x16x32_bf16 v[152:155], v[52:55], v[194:197], v[206:209]
	v_mfma_f32_16x16x32_bf16 v[120:123], v[52:55], v[198:201], v[216:219]
	v_mfma_f32_16x16x32_bf16 v[88:91], v[52:55], v[240:243], v[224:227]
	s_waitcnt lgkmcnt(1)
	v_mfma_f32_16x16x32_bf16 v[148:151], v[28:31], v[194:197], v[228:231]
	s_waitcnt lgkmcnt(0)
	v_mfma_f32_16x16x32_bf16 v[144:147], v[24:27], v[194:197], v[112:115]
	v_mfma_f32_16x16x32_bf16 v[116:119], v[28:31], v[198:201], v[232:235]
	v_mfma_f32_16x16x32_bf16 v[112:115], v[24:27], v[198:201], v[80:83]
	v_mfma_f32_16x16x32_bf16 v[84:87], v[28:31], v[240:243], v[236:239]
	v_mfma_f32_16x16x32_bf16 v[80:83], v[24:27], v[240:243], v[48:51]
	v_mfma_f32_16x16x32_bf16 v[52:55], v[28:31], v[244:247], v[20:23]
	v_mfma_f32_16x16x32_bf16 v[48:51], v[24:27], v[244:247], v[16:19]
	s_and_b64 vcc, exec, s[6:7]
	s_barrier
	s_cbranch_vccz .LBB0_392
	s_ashr_i32 s51, s50, 31
	s_lshl_b64 s[6:7], s[50:51], 19
	s_add_u32 s6, s12, s6
	s_addc_u32 s7, s13, s7
	s_lshl_b32 s50, s67, 8
	v_lshl_add_u64 v[0:1], v[186:187], 2, s[6:7]
	v_lshlrev_b32_e32 v176, 2, v188
	s_ashr_i32 s51, s50, 31
	v_lshl_add_u64 v[0:1], v[0:1], 0, v[176:177]
	s_lshl_b64 s[6:7], s[50:51], 6
	global_load_dwordx4 v[24:27], v[0:1], off sc1
	s_add_u32 s6, s2, s6
	v_lshl_add_u64 v[2:3], v[0:1], 0, s[16:17]
	global_load_dwordx4 v[28:31], v[2:3], off sc1
	s_addc_u32 s7, s33, s7
	v_lshl_add_u64 v[2:3], v[0:1], 0, s[18:19]
	global_load_dwordx4 v[16:19], v[2:3], off sc1
	v_lshl_add_u64 v[0:1], v[0:1], 0, s[20:21]
	global_load_dwordx4 v[20:23], v[0:1], off sc1
	v_lshl_add_u64 v[12:13], v[182:183], 1, s[6:7]
	global_load_dwordx4 v[0:3], v[12:13], off sc1
	v_lshl_add_u64 v[4:5], v[12:13], 0, s[22:23]
	global_load_dwordx4 v[4:7], v[4:5], off sc1
	v_lshl_add_u64 v[8:9], v[12:13], 0, s[24:25]
	global_load_dwordx4 v[8:11], v[8:9], off sc1
	v_lshl_add_u64 v[12:13], v[12:13], 0, s[26:27]
	global_load_dwordx4 v[12:15], v[12:13], off sc1
	s_branch .LBB0_393

; #define G_LOAD(kt_) do { \
;     if constexpr (AF32) { _Pragma("unroll") for (int i = 0; i < 4; ++i) ld16_sc1(ra[i], Af + (size_t)i * 32 * lda + (kt_) * 32); } \
;     else { _Pragma("unroll") for (int i = 0; i < 2; ++i) ld16_sc1(rab[i], Ab + (size_t)i * 64 * lda + (kt_) * 32); } \
;     _Pragma("unroll") for (int i = 0; i < 4; ++i) ld16_sc1(rb[i], Bp + (size_t)(kt_) * bstep + i * 2048); } while (0)
; template <bool AF32, class Epi>
; __device__ __forceinline__ void gemm_tile(unsigned char* smem, const void* Ap, int lda, const bf16_t* WT, int N, int K, const Epi& epi, int m0, int n0,
;                                           GPre& pr, bool preloaded, const void* nAp, int nn0, bool has_next) {
;     ...
;   if (!preloaded) G_LOAD(0);
;   G_STORE(0);
;   if (nk > 1) G_LOAD(1);
;   __syncthreads();
;   for (int kt = 0; kt < nk; ++kt) {
;     const int cur = kt & 1;
;     if (kt + 1 < nk) G_STORE(cur ^ 1);
;     if (kt + 2 < nk) G_LOAD(kt + 2);
;     const bf16_t* a_s = sbase + cur * G_STAGE + (wr * 64 + l15) * GLD + quad * 8;
;     const bf16_t* b_s = sbase + cur * G_STAGE + 128 * GLD + (wc * 128 + l15) * GLD + quad * 8;
;     __builtin_amdgcn_s_setprio(1);
;     bf16x8 af[4];
; #pragma unroll
;     for (int m = 0; m < 4; ++m) af[m] = *(const bf16x8*)(a_s + m * 16 * GLD);
; #pragma unroll
;     for (int nh = 0; nh < 4; ++nh) {
;       bf16x8 bfr[2];
; #pragma unroll
;       for (int n2 = 0; n2 < 2; ++n2) bfr[n2] = *(const bf16x8*)(b_s + (nh * 2 + n2) * 16 * GLD);
; #pragma unroll
;       for (int m = 0; m < 4; ++m)
; #pragma unroll
;         for (int n2 = 0; n2 < 2; ++n2) acc[m][nh * 2 + n2] = __builtin_amdgcn_mfma_f32_16x16x32_bf16(bfr[n2], af[m], acc[m][nh * 2 + n2], 0, 0, 0);
;     }
;     __builtin_amdgcn_s_setprio(0);
;     __syncthreads();
;   }
.LBB0_429:
	s_and_b32 s3, s52, 1
	s_waitcnt vmcnt(0)
	s_xor_b32 s53, s3, 1
	s_mulk_i32 s53, 0x7800
	v_add_u32_e32 v176, s53, v155
	ds_write_b128 v176, v[0:3]
	ds_write_b128 v176, v[4:7] offset:5120
	ds_write_b128 v176, v[8:11] offset:10240
	ds_write_b128 v176, v[12:15] offset:15360
	ds_write_b128 v176, v[16:19] offset:20480
	ds_write_b128 v176, v[20:23] offset:25600
	global_load_dwordx4 v[0:3], v[162:163], off sc1
	v_lshl_add_u64 v[168:169], v[162:163], 0, s[12:13]
	global_load_dwordx4 v[4:7], v[168:169], off sc1
	global_load_dwordx4 v[8:11], v[160:161], off sc1
	v_lshl_add_u64 v[170:171], v[160:161], 0, s[14:15]
	global_load_dwordx4 v[12:15], v[170:171], off sc1
	v_lshl_add_u64 v[172:173], v[160:161], 0, s[16:17]
	global_load_dwordx4 v[16:19], v[172:173], off sc1
	v_lshl_add_u64 v[174:175], v[160:161], 0, s[18:19]
	global_load_dwordx4 v[20:23], v[174:175], off sc1
	s_add_i32 s52, s52, 1
	s_mulk_i32 s3, 0x7800
	v_add3_u32 v188, s3, v166, v167
	s_setprio 1
	v_add3_u32 v192, s3, v165, v167
	ds_read_b128 v[168:171], v192 offset:10240
	ds_read_b128 v[172:175], v192 offset:11520
	ds_read_b128 v[176:179], v188
	ds_read_b128 v[180:183], v188 offset:1280
	ds_read_b128 v[184:187], v188 offset:2560
	ds_read_b128 v[188:191], v188 offset:3840
	s_waitcnt lgkmcnt(3)
	v_mfma_f32_16x16x32_bf16 v[148:151], v[168:171], v[176:179], v[148:151]
	v_mfma_f32_16x16x32_bf16 v[144:147], v[172:175], v[176:179], v[144:147]
	s_waitcnt lgkmcnt(2)
	v_mfma_f32_16x16x32_bf16 v[132:135], v[168:171], v[180:183], v[132:135]
	v_mfma_f32_16x16x32_bf16 v[128:131], v[172:175], v[180:183], v[128:131]
	s_waitcnt lgkmcnt(1)
	v_mfma_f32_16x16x32_bf16 v[100:103], v[168:171], v[184:187], v[100:103]
	v_mfma_f32_16x16x32_bf16 v[92:95], v[172:175], v[184:187], v[92:95]
	s_waitcnt lgkmcnt(0)
	v_mfma_f32_16x16x32_bf16 v[68:71], v[168:171], v[188:191], v[68:71]
	ds_read_b128 v[168:171], v192 offset:12800
	v_mfma_f32_16x16x32_bf16 v[60:63], v[172:175], v[188:191], v[60:63]
	ds_read_b128 v[172:175], v192 offset:14080
	s_waitcnt lgkmcnt(1)
	v_mfma_f32_16x16x32_bf16 v[140:143], v[168:171], v[176:179], v[140:143]
	s_waitcnt lgkmcnt(0)
	v_mfma_f32_16x16x32_bf16 v[136:139], v[172:175], v[176:179], v[136:139]
	v_mfma_f32_16x16x32_bf16 v[116:119], v[168:171], v[180:183], v[116:119]
	v_mfma_f32_16x16x32_bf16 v[108:111], v[172:175], v[180:183], v[108:111]
	v_mfma_f32_16x16x32_bf16 v[84:87], v[168:171], v[184:187], v[84:87]
	v_mfma_f32_16x16x32_bf16 v[76:79], v[172:175], v[184:187], v[76:79]
	v_mfma_f32_16x16x32_bf16 v[52:55], v[168:171], v[188:191], v[52:55]
	ds_read_b128 v[168:171], v192 offset:15360
	v_mfma_f32_16x16x32_bf16 v[44:47], v[172:175], v[188:191], v[44:47]
	ds_read_b128 v[172:175], v192 offset:16640
	s_waitcnt lgkmcnt(1)
	v_mfma_f32_16x16x32_bf16 v[124:127], v[168:171], v[176:179], v[124:127]
	s_waitcnt lgkmcnt(0)
	v_mfma_f32_16x16x32_bf16 v[120:123], v[172:175], v[176:179], v[120:123]
	v_mfma_f32_16x16x32_bf16 v[96:99], v[168:171], v[180:183], v[96:99]
	v_mfma_f32_16x16x32_bf16 v[88:91], v[172:175], v[180:183], v[88:91]
	v_mfma_f32_16x16x32_bf16 v[64:67], v[168:171], v[184:187], v[64:67]
	v_mfma_f32_16x16x32_bf16 v[56:59], v[172:175], v[184:187], v[56:59]
	v_mfma_f32_16x16x32_bf16 v[36:39], v[168:171], v[188:191], v[36:39]
	ds_read_b128 v[168:171], v192 offset:17920
	v_mfma_f32_16x16x32_bf16 v[32:35], v[172:175], v[188:191], v[32:35]
	ds_read_b128 v[172:175], v192 offset:19200
	s_waitcnt lgkmcnt(1)
	v_mfma_f32_16x16x32_bf16 v[112:115], v[168:171], v[176:179], v[112:115]
	s_waitcnt lgkmcnt(0)
	v_mfma_f32_16x16x32_bf16 v[104:107], v[172:175], v[176:179], v[104:107]
	v_mfma_f32_16x16x32_bf16 v[80:83], v[168:171], v[180:183], v[80:83]
	v_mfma_f32_16x16x32_bf16 v[72:75], v[172:175], v[180:183], v[72:75]
	v_mfma_f32_16x16x32_bf16 v[48:51], v[168:171], v[184:187], v[48:51]
	v_mfma_f32_16x16x32_bf16 v[40:43], v[172:175], v[184:187], v[40:43]
	v_mfma_f32_16x16x32_bf16 v[28:31], v[168:171], v[188:191], v[28:31]
	v_mfma_f32_16x16x32_bf16 v[24:27], v[172:175], v[188:191], v[24:27]
	s_setprio 0
	v_lshl_add_u64 v[160:161], v[160:161], 0, s[22:23]
	s_cmpk_eq_i32 s52, 0x56
	v_lshl_add_u64 v[162:163], v[162:163], 0, 64
	s_barrier
	s_cbranch_scc0 .LBB0_429
	s_waitcnt vmcnt(0)
	ds_write_b128 v155, v[0:3] offset:30720
	ds_write_b128 v155, v[4:7] offset:35840
	ds_write_b128 v155, v[8:11] offset:40960
	ds_write_b128 v155, v[12:15] offset:46080
	ds_write_b128 v155, v[16:19] offset:51200
	ds_write_b128 v155, v[20:23] offset:56320
	v_add_u32_e32 v155, v166, v167
	s_setprio 1
	v_add_u32_e32 v165, v165, v167
	ds_read_b128 v[160:163], v165 offset:10240
	ds_read_b128 v[166:169], v165 offset:11520
	ds_read_b128 v[170:173], v155
	ds_read_b128 v[174:177], v155 offset:1280
	ds_read_b128 v[178:181], v155 offset:2560
	ds_read_b128 v[182:185], v155 offset:3840
	s_waitcnt lgkmcnt(3)
	v_mfma_f32_16x16x32_bf16 v[148:151], v[160:163], v[170:173], v[148:151]
	v_mfma_f32_16x16x32_bf16 v[144:147], v[166:169], v[170:173], v[144:147]
	s_waitcnt lgkmcnt(2)
	v_mfma_f32_16x16x32_bf16 v[132:135], v[160:163], v[174:177], v[132:135]
	v_mfma_f32_16x16x32_bf16 v[128:131], v[166:169], v[174:177], v[128:131]
	s_waitcnt lgkmcnt(1)
	v_mfma_f32_16x16x32_bf16 v[100:103], v[160:163], v[178:181], v[100:103]
	v_mfma_f32_16x16x32_bf16 v[92:95], v[166:169], v[178:181], v[92:95]
	s_waitcnt lgkmcnt(0)
	v_mfma_f32_16x16x32_bf16 v[68:71], v[160:163], v[182:185], v[68:71]
	ds_read_b128 v[160:163], v165 offset:12800
	v_mfma_f32_16x16x32_bf16 v[60:63], v[166:169], v[182:185], v[60:63]
	ds_read_b128 v[166:169], v165 offset:14080
	s_waitcnt lgkmcnt(1)
	v_mfma_f32_16x16x32_bf16 v[186:189], v[160:163], v[170:173], v[140:143]
	s_waitcnt lgkmcnt(0)
; #define G_LOAD(kt_) do { \
;     if constexpr (AF32) { _Pragma("unroll") for (int i = 0; i < 4; ++i) ld16_sc1(ra[i], Af + (size_t)i * 32 * lda + (kt_) * 32); } \
;     else { _Pragma("unroll") for (int i = 0; i < 2; ++i) ld16_sc1(rab[i], Ab + (size_t)i * 64 * lda + (kt_) * 32); } \
;     _Pragma("unroll") for (int i = 0; i < 4; ++i) ld16_sc1(rb[i], Bp + (size_t)(kt_) * bstep + i * 2048); } while (0)
; template <bool AF32, class Epi>
; __device__ __forceinline__ void gemm_tile(unsigned char* smem, const void* Ap, int lda, const bf16_t* WT, int N, int K, const Epi& epi, int m0, int n0,
;                                           GPre& pr, bool preloaded, const void* nAp, int nn0, bool has_next) {
;     ...
;     const bf16_t* a_s = sbase + cur * G_STAGE + (wr * 64 + l15) * GLD + quad * 8;
;     const bf16_t* b_s = sbase + cur * G_STAGE + 128 * GLD + (wc * 128 + l15) * GLD + quad * 8;
;     __builtin_amdgcn_s_setprio(1);
;     bf16x8 af[4];
; #pragma unroll
;     for (int m = 0; m < 4; ++m) af[m] = *(const bf16x8*)(a_s + m * 16 * GLD);
; #pragma unroll
;     for (int nh = 0; nh < 4; ++nh) {
;       bf16x8 bfr[2];
; #pragma unroll
;       for (int n2 = 0; n2 < 2; ++n2) bfr[n2] = *(const bf16x8*)(b_s + (nh * 2 + n2) * 16 * GLD);
; #pragma unroll
;       for (int m = 0; m < 4; ++m)
; #pragma unroll
;         for (int n2 = 0; n2 < 2; ++n2) acc[m][nh * 2 + n2] = __builtin_amdgcn_mfma_f32_16x16x32_bf16(bfr[n2], af[m], acc[m][nh * 2 + n2], 0, 0, 0);
;     }
;     __builtin_amdgcn_s_setprio(0);
;     __syncthreads();
;   }
;   if (has_next) {
;     const float* Af = (const float*)nAp + (size_t)(tid >> 3) * lda + (tid & 7) * 4;
;     const bf16_t* Ab = (const bf16_t*)nAp + (size_t)(tid >> 2) * lda + (tid & 3) * 8;
;     const bf16_t* Bp = WT + (size_t)nn0 * 32 + tid * 8;
;     G_LOAD(0);
;   }
	v_mfma_f32_16x16x32_bf16 v[136:139], v[166:169], v[170:173], v[136:139]
	v_mfma_f32_16x16x32_bf16 v[190:193], v[160:163], v[174:177], v[116:119]
	v_mfma_f32_16x16x32_bf16 v[194:197], v[166:169], v[174:177], v[108:111]
	v_mfma_f32_16x16x32_bf16 v[198:201], v[160:163], v[178:181], v[84:87]
	v_mfma_f32_16x16x32_bf16 v[202:205], v[166:169], v[178:181], v[76:79]
	v_mfma_f32_16x16x32_bf16 v[160:163], v[160:163], v[182:185], v[52:55]
	s_nop 2
	ds_read_b128 v[52:55], v165 offset:15360
	v_mfma_f32_16x16x32_bf16 v[166:169], v[166:169], v[182:185], v[44:47]
	s_nop 2
	ds_read_b128 v[44:47], v165 offset:16640
	s_waitcnt lgkmcnt(1)
	v_mfma_f32_16x16x32_bf16 v[124:127], v[52:55], v[170:173], v[124:127]
	s_waitcnt lgkmcnt(0)
	v_mfma_f32_16x16x32_bf16 v[120:123], v[44:47], v[170:173], v[120:123]
	v_mfma_f32_16x16x32_bf16 v[96:99], v[52:55], v[174:177], v[96:99]
	v_mfma_f32_16x16x32_bf16 v[88:91], v[44:47], v[174:177], v[88:91]
	v_mfma_f32_16x16x32_bf16 v[64:67], v[52:55], v[178:181], v[64:67]
	v_mfma_f32_16x16x32_bf16 v[56:59], v[44:47], v[178:181], v[56:59]
	v_mfma_f32_16x16x32_bf16 v[36:39], v[52:55], v[182:185], v[36:39]
	ds_read_b128 v[52:55], v165 offset:17920
	v_mfma_f32_16x16x32_bf16 v[32:35], v[44:47], v[182:185], v[32:35]
	ds_read_b128 v[44:47], v165 offset:19200
	s_waitcnt lgkmcnt(1)
	v_mfma_f32_16x16x32_bf16 v[28:31], v[52:55], v[182:185], v[28:31]
	s_waitcnt lgkmcnt(0)
	v_mfma_f32_16x16x32_bf16 v[24:27], v[44:47], v[182:185], v[24:27]
	v_mfma_f32_16x16x32_bf16 v[206:209], v[52:55], v[170:173], v[112:115]
	v_mfma_f32_16x16x32_bf16 v[170:173], v[44:47], v[170:173], v[104:107]
	v_mfma_f32_16x16x32_bf16 v[212:215], v[52:55], v[174:177], v[80:83]
	v_mfma_f32_16x16x32_bf16 v[174:177], v[44:47], v[174:177], v[72:75]
	v_mfma_f32_16x16x32_bf16 v[216:219], v[52:55], v[178:181], v[48:51]
	v_mfma_f32_16x16x32_bf16 v[178:181], v[44:47], v[178:181], v[40:43]
	s_setprio 0
	s_barrier
	s_setprio 1
	ds_read_b128 v[40:43], v165 offset:40960
	ds_read_b128 v[44:47], v165 offset:42240
	ds_read_b128 v[182:185], v155 offset:30720
	ds_read_b128 v[220:223], v155 offset:32000
	ds_read_b128 v[224:227], v155 offset:33280
	ds_read_b128 v[228:231], v155 offset:34560
	s_waitcnt lgkmcnt(3)
	v_mfma_f32_16x16x32_bf16 v[148:151], v[40:43], v[182:185], v[148:151]
	s_waitcnt lgkmcnt(2)
	v_mfma_f32_16x16x32_bf16 v[116:119], v[40:43], v[220:223], v[132:135]
	s_waitcnt lgkmcnt(1)
	v_mfma_f32_16x16x32_bf16 v[84:87], v[40:43], v[224:227], v[100:103]
	s_waitcnt lgkmcnt(0)
	v_mfma_f32_16x16x32_bf16 v[52:55], v[40:43], v[228:231], v[68:71]
	ds_read_b128 v[40:43], v165 offset:43520
	v_mfma_f32_16x16x32_bf16 v[48:51], v[44:47], v[228:231], v[60:63]
	s_nop 2
	ds_read_b128 v[60:63], v165 offset:44800
	v_mfma_f32_16x16x32_bf16 v[140:143], v[44:47], v[182:185], v[144:147]
	v_mfma_f32_16x16x32_bf16 v[108:111], v[44:47], v[220:223], v[128:131]
	v_mfma_f32_16x16x32_bf16 v[80:83], v[44:47], v[224:227], v[92:95]
	s_waitcnt lgkmcnt(1)
	v_mfma_f32_16x16x32_bf16 v[144:147], v[40:43], v[182:185], v[186:189]
	s_nop 0
	ds_read_b128 v[92:95], v165 offset:46080
	s_waitcnt lgkmcnt(1)
	v_mfma_f32_16x16x32_bf16 v[136:139], v[60:63], v[182:185], v[136:139]
	v_mfma_f32_16x16x32_bf16 v[112:115], v[40:43], v[220:223], v[190:193]
	v_mfma_f32_16x16x32_bf16 v[104:107], v[60:63], v[220:223], v[194:197]
	v_mfma_f32_16x16x32_bf16 v[76:79], v[40:43], v[224:227], v[198:201]
	v_mfma_f32_16x16x32_bf16 v[72:75], v[60:63], v[224:227], v[202:205]
	v_mfma_f32_16x16x32_bf16 v[44:47], v[40:43], v[228:231], v[160:163]
	v_mfma_f32_16x16x32_bf16 v[40:43], v[60:63], v[228:231], v[166:169]
	ds_read_b128 v[60:63], v165 offset:47360
	s_nop 0
	ds_read_b128 v[160:163], v165 offset:48640
	ds_read_b128 v[166:169], v165 offset:49920
	s_waitcnt lgkmcnt(3)
	v_mfma_f32_16x16x32_bf16 v[132:135], v[92:95], v[182:185], v[124:127]
	s_waitcnt lgkmcnt(2)
	v_mfma_f32_16x16x32_bf16 v[128:131], v[60:63], v[182:185], v[120:123]
	v_mfma_f32_16x16x32_bf16 v[100:103], v[92:95], v[220:223], v[96:99]
	v_mfma_f32_16x16x32_bf16 v[96:99], v[60:63], v[220:223], v[88:91]
	v_mfma_f32_16x16x32_bf16 v[68:71], v[92:95], v[224:227], v[64:67]
	v_mfma_f32_16x16x32_bf16 v[64:67], v[60:63], v[224:227], v[56:59]
	v_mfma_f32_16x16x32_bf16 v[36:39], v[92:95], v[228:231], v[36:39]
	v_mfma_f32_16x16x32_bf16 v[32:35], v[60:63], v[228:231], v[32:35]
	s_waitcnt lgkmcnt(1)
	v_mfma_f32_16x16x32_bf16 v[124:127], v[160:163], v[182:185], v[206:209]
	s_waitcnt lgkmcnt(0)
	v_mfma_f32_16x16x32_bf16 v[120:123], v[166:169], v[182:185], v[170:173]
	v_mfma_f32_16x16x32_bf16 v[92:95], v[160:163], v[220:223], v[212:215]
	v_mfma_f32_16x16x32_bf16 v[88:91], v[166:169], v[220:223], v[174:177]
	v_mfma_f32_16x16x32_bf16 v[60:63], v[160:163], v[224:227], v[216:219]
	v_mfma_f32_16x16x32_bf16 v[56:59], v[166:169], v[224:227], v[178:181]
	v_mfma_f32_16x16x32_bf16 v[28:31], v[160:163], v[228:231], v[28:31]
	v_mfma_f32_16x16x32_bf16 v[24:27], v[166:169], v[228:231], v[24:27]
	s_and_b64 vcc, exec, s[48:49]
	s_barrier
	s_cbranch_vccz .LBB0_417
	s_mul_i32 s48, s69, 0xb0000
	s_mul_hi_i32 s3, s69, 0xb0000
	s_add_u32 s48, s2, s48
	s_addc_u32 s49, s33, s3
	s_lshl_b32 s52, s68, 8
	s_ashr_i32 s53, s52, 31
	v_lshl_add_u64 v[0:1], v[158:159], 1, s[48:49]
	s_lshl_b64 s[48:49], s[52:53], 6
	v_lshl_add_u64 v[4:5], v[0:1], 0, v[152:153]
	s_add_u32 s48, s56, s48
	s_addc_u32 s49, s57, s49
	global_load_dwordx4 v[0:3], v[4:5], off sc1
	v_lshl_add_u64 v[4:5], v[4:5], 0, s[12:13]
	global_load_dwordx4 v[4:7], v[4:5], off sc1
	v_lshl_add_u64 v[20:21], v[156:157], 1, s[48:49]
	global_load_dwordx4 v[8:11], v[20:21], off sc1
	v_lshl_add_u64 v[12:13], v[20:21], 0, s[14:15]
	global_load_dwordx4 v[12:15], v[12:13], off sc1
	v_lshl_add_u64 v[16:17], v[20:21], 0, s[16:17]
	global_load_dwordx4 v[16:19], v[16:17], off sc1
	v_lshl_add_u64 v[20:21], v[20:21], 0, s[18:19]
	global_load_dwordx4 v[20:23], v[20:21], off sc1
	s_branch .LBB0_417

; #define G_LOAD(kt_) do { \
;     if constexpr (AF32) { _Pragma("unroll") for (int i = 0; i < 4; ++i) ld16_sc1(ra[i], Af + (size_t)i * 32 * lda + (kt_) * 32); } \
;     else { _Pragma("unroll") for (int i = 0; i < 2; ++i) ld16_sc1(rab[i], Ab + (size_t)i * 64 * lda + (kt_) * 32); } \
;     _Pragma("unroll") for (int i = 0; i < 4; ++i) ld16_sc1(rb[i], Bp + (size_t)(kt_) * bstep + i * 2048); } while (0)
; template <bool AF32, class Epi>
; __device__ __forceinline__ void gemm_tile(unsigned char* smem, const void* Ap, int lda, const bf16_t* WT, int N, int K, const Epi& epi, int m0, int n0,
;                                           GPre& pr, bool preloaded, const void* nAp, int nn0, bool has_next) {
;     ...
;   if (!preloaded) G_LOAD(0);
;   G_STORE(0);
;   if (nk > 1) G_LOAD(1);
;   __syncthreads();
;   for (int kt = 0; kt < nk; ++kt) {
;     const int cur = kt & 1;
;     if (kt + 1 < nk) G_STORE(cur ^ 1);
;     if (kt + 2 < nk) G_LOAD(kt + 2);
;     const bf16_t* a_s = sbase + cur * G_STAGE + (wr * 64 + l15) * GLD + quad * 8;
;     const bf16_t* b_s = sbase + cur * G_STAGE + 128 * GLD + (wc * 128 + l15) * GLD + quad * 8;
;     __builtin_amdgcn_s_setprio(1);
;     bf16x8 af[4];
; #pragma unroll
;     for (int m = 0; m < 4; ++m) af[m] = *(const bf16x8*)(a_s + m * 16 * GLD);
; #pragma unroll
;     for (int nh = 0; nh < 4; ++nh) {
;       bf16x8 bfr[2];
; #pragma unroll
;       for (int n2 = 0; n2 < 2; ++n2) bfr[n2] = *(const bf16x8*)(b_s + (nh * 2 + n2) * 16 * GLD);
; #pragma unroll
;       for (int m = 0; m < 4; ++m)
; #pragma unroll
;         for (int n2 = 0; n2 < 2; ++n2) acc[m][nh * 2 + n2] = __builtin_amdgcn_mfma_f32_16x16x32_bf16(bfr[n2], af[m], acc[m][nh * 2 + n2], 0, 0, 0);
;     }
;     __builtin_amdgcn_s_setprio(0);
;     __syncthreads();
;   }
.LBB0_460:
	s_and_b32 s3, s51, 1
	s_waitcnt vmcnt(0)
	s_xor_b32 s53, s3, 1
	s_mulk_i32 s53, 0x7800
	v_cvt_pk_bf16_f32 v202, v28, v29
	v_mov_b32_e32 v205, v28
	v_mov_b32_e32 v28, v25
	v_lshl_add_u32 v171, v160, 1, s53
	v_cvt_pk_bf16_f32 v203, v30, v31
	v_mov_b32_e32 v204, v24
	v_mov_b32_e32 v206, v26
	v_mov_b32_e32 v207, v30
	v_mov_b32_e32 v30, v27
	v_cvt_pk_bf16_f32 v24, v24, v25
	v_cvt_pk_bf16_f32 v25, v26, v27
	v_cvt_pk_bf16_f32 v26, v20, v21
	v_cvt_pk_bf16_f32 v27, v22, v23
	v_mov_b32_e32 v208, v16
	v_mov_b32_e32 v209, v20
	v_mov_b32_e32 v20, v17
	v_mov_b32_e32 v212, v18
	v_mov_b32_e32 v213, v22
	v_mov_b32_e32 v22, v19
	v_cvt_pk_bf16_f32 v16, v16, v17
	v_cvt_pk_bf16_f32 v17, v18, v19
	v_pk_mul_f32 v[18:19], v[28:29], v[28:29]
	v_lshl_add_u32 v176, v162, 1, s53
	ds_write2st64_b64 v171, v[202:203], v[24:25] offset1:5
	ds_write2st64_b64 v171, v[26:27], v[16:17] offset0:10 offset1:15
	ds_write_b128 v176, v[0:3] offset:10240
	ds_write_b128 v176, v[4:7] offset:15360
	ds_write_b128 v176, v[8:11] offset:20480
	ds_write_b128 v176, v[12:15] offset:25600
	v_pk_fma_f32 v[0:1], v[204:205], v[204:205], v[18:19]
	v_pk_mul_f32 v[20:21], v[20:21], v[20:21]
	v_pk_fma_f32 v[0:1], v[206:207], v[206:207], v[0:1]
	v_pk_fma_f32 v[2:3], v[208:209], v[208:209], v[20:21]
	v_pk_fma_f32 v[202:203], v[30:31], v[30:31], v[0:1]
	global_load_dwordx4 v[28:31], v[166:167], off sc1
	v_lshl_add_u64 v[172:173], v[166:167], 0, s[16:17]
	v_pk_fma_f32 v[2:3], v[212:213], v[212:213], v[2:3]
	global_load_dwordx4 v[24:27], v[172:173], off sc1
	v_lshl_add_u64 v[174:175], v[166:167], 0, s[18:19]
	v_pk_fma_f32 v[204:205], v[22:23], v[22:23], v[2:3]
	global_load_dwordx4 v[20:23], v[174:175], off sc1
	v_lshl_add_u64 v[194:195], v[166:167], 0, s[20:21]
	global_load_dwordx4 v[16:19], v[194:195], off sc1
	global_load_dwordx4 v[0:3], v[164:165], off sc1
	v_lshl_add_u64 v[196:197], v[164:165], 0, s[22:23]
	global_load_dwordx4 v[4:7], v[196:197], off sc1
	v_lshl_add_u64 v[198:199], v[164:165], 0, s[24:25]
	global_load_dwordx4 v[8:11], v[198:199], off sc1
	v_lshl_add_u64 v[200:201], v[164:165], 0, s[26:27]
	global_load_dwordx4 v[12:15], v[200:201], off sc1
	s_add_i32 s51, s51, 1
	s_mulk_i32 s3, 0x7800
	v_pk_add_f32 v[186:187], v[186:187], v[202:203]
	v_pk_add_f32 v[182:183], v[182:183], v[204:205]
	v_add3_u32 v171, s3, v169, v170
	s_setprio 1
	v_add3_u32 v176, s3, v168, v170
	ds_read_b128 v[172:175], v176 offset:10240
	ds_read_b128 v[194:197], v176 offset:11520
	ds_read_b128 v[198:201], v171
	ds_read_b128 v[202:205], v171 offset:1280
	ds_read_b128 v[206:209], v171 offset:2560
	ds_read_b128 v[212:215], v171 offset:3840
	s_waitcnt lgkmcnt(3)
	v_mfma_f32_16x16x32_bf16 v[156:159], v[172:175], v[198:201], v[156:159]
	v_mfma_f32_16x16x32_bf16 v[152:155], v[194:197], v[198:201], v[152:155]
	s_waitcnt lgkmcnt(2)
	v_mfma_f32_16x16x32_bf16 v[140:143], v[172:175], v[202:205], v[140:143]
	v_mfma_f32_16x16x32_bf16 v[136:139], v[194:197], v[202:205], v[136:139]
	s_waitcnt lgkmcnt(1)
	v_mfma_f32_16x16x32_bf16 v[108:111], v[172:175], v[206:209], v[108:111]
	v_mfma_f32_16x16x32_bf16 v[100:103], v[194:197], v[206:209], v[100:103]
	s_waitcnt lgkmcnt(0)
	v_mfma_f32_16x16x32_bf16 v[76:79], v[172:175], v[212:215], v[76:79]
	ds_read_b128 v[172:175], v176 offset:12800
	v_mfma_f32_16x16x32_bf16 v[68:71], v[194:197], v[212:215], v[68:71]
	ds_read_b128 v[194:197], v176 offset:14080
	s_waitcnt lgkmcnt(1)
	v_mfma_f32_16x16x32_bf16 v[148:151], v[172:175], v[198:201], v[148:151]
	s_waitcnt lgkmcnt(0)
	v_mfma_f32_16x16x32_bf16 v[144:147], v[194:197], v[198:201], v[144:147]
	v_mfma_f32_16x16x32_bf16 v[124:127], v[172:175], v[202:205], v[124:127]
	v_mfma_f32_16x16x32_bf16 v[116:119], v[194:197], v[202:205], v[116:119]
	v_mfma_f32_16x16x32_bf16 v[92:95], v[172:175], v[206:209], v[92:95]
	v_mfma_f32_16x16x32_bf16 v[84:87], v[194:197], v[206:209], v[84:87]
	v_mfma_f32_16x16x32_bf16 v[60:63], v[172:175], v[212:215], v[60:63]
	ds_read_b128 v[172:175], v176 offset:15360
	v_mfma_f32_16x16x32_bf16 v[52:55], v[194:197], v[212:215], v[52:55]
	ds_read_b128 v[194:197], v176 offset:16640
	s_waitcnt lgkmcnt(1)
	v_mfma_f32_16x16x32_bf16 v[132:135], v[172:175], v[198:201], v[132:135]
	s_waitcnt lgkmcnt(0)
	v_mfma_f32_16x16x32_bf16 v[128:131], v[194:197], v[198:201], v[128:131]
	v_mfma_f32_16x16x32_bf16 v[104:107], v[172:175], v[202:205], v[104:107]
	v_mfma_f32_16x16x32_bf16 v[96:99], v[194:197], v[202:205], v[96:99]
	v_mfma_f32_16x16x32_bf16 v[72:75], v[172:175], v[206:209], v[72:75]
	v_mfma_f32_16x16x32_bf16 v[64:67], v[194:197], v[206:209], v[64:67]
	v_mfma_f32_16x16x32_bf16 v[44:47], v[172:175], v[212:215], v[44:47]
	ds_read_b128 v[172:175], v176 offset:17920
	v_mfma_f32_16x16x32_bf16 v[40:43], v[194:197], v[212:215], v[40:43]
	ds_read_b128 v[194:197], v176 offset:19200
	s_waitcnt lgkmcnt(1)
	v_mfma_f32_16x16x32_bf16 v[120:123], v[172:175], v[198:201], v[120:123]
	s_waitcnt lgkmcnt(0)
	v_mfma_f32_16x16x32_bf16 v[112:115], v[194:197], v[198:201], v[112:115]
	v_mfma_f32_16x16x32_bf16 v[88:91], v[172:175], v[202:205], v[88:91]
	v_mfma_f32_16x16x32_bf16 v[80:83], v[194:197], v[202:205], v[80:83]
	v_mfma_f32_16x16x32_bf16 v[56:59], v[172:175], v[206:209], v[56:59]
	v_mfma_f32_16x16x32_bf16 v[48:51], v[194:197], v[206:209], v[48:51]
	v_mfma_f32_16x16x32_bf16 v[36:39], v[172:175], v[212:215], v[36:39]
	v_mfma_f32_16x16x32_bf16 v[32:35], v[194:197], v[212:215], v[32:35]
	s_setprio 0
	v_lshl_add_u64 v[164:165], v[164:165], 0, s[38:39]
	s_cmp_eq_u32 s51, 30
	v_lshl_add_u64 v[166:167], v[166:167], 0, s[28:29]
	s_barrier
	s_cbranch_scc0 .LBB0_460
; #define G_LOAD(kt_) do { \
;     if constexpr (AF32) { _Pragma("unroll") for (int i = 0; i < 4; ++i) ld16_sc1(ra[i], Af + (size_t)i * 32 * lda + (kt_) * 32); } \
;     else { _Pragma("unroll") for (int i = 0; i < 2; ++i) ld16_sc1(rab[i], Ab + (size_t)i * 64 * lda + (kt_) * 32); } \
;     _Pragma("unroll") for (int i = 0; i < 4; ++i) ld16_sc1(rb[i], Bp + (size_t)(kt_) * bstep + i * 2048); } while (0)
; template <bool AF32, class Epi>
; __device__ __forceinline__ void gemm_tile(unsigned char* smem, const void* Ap, int lda, const bf16_t* WT, int N, int K, const Epi& epi, int m0, int n0,
;                                           GPre& pr, bool preloaded, const void* nAp, int nn0, bool has_next) {
;     ...
;   if (!preloaded) G_LOAD(0);
;   G_STORE(0);
;   if (nk > 1) G_LOAD(1);
;   __syncthreads();
;   for (int kt = 0; kt < nk; ++kt) {
;     const int cur = kt & 1;
;     if (kt + 1 < nk) G_STORE(cur ^ 1);
;     if (kt + 2 < nk) G_LOAD(kt + 2);
;     const bf16_t* a_s = sbase + cur * G_STAGE + (wr * 64 + l15) * GLD + quad * 8;
;     const bf16_t* b_s = sbase + cur * G_STAGE + 128 * GLD + (wc * 128 + l15) * GLD + quad * 8;
;     __builtin_amdgcn_s_setprio(1);
;     bf16x8 af[4];
; #pragma unroll
;     for (int m = 0; m < 4; ++m) af[m] = *(const bf16x8*)(a_s + m * 16 * GLD);
; #pragma unroll
;     for (int nh = 0; nh < 4; ++nh) {
;       bf16x8 bfr[2];
; #pragma unroll
;       for (int n2 = 0; n2 < 2; ++n2) bfr[n2] = *(const bf16x8*)(b_s + (nh * 2 + n2) * 16 * GLD);
; #pragma unroll
;       for (int m = 0; m < 4; ++m)
; #pragma unroll
;         for (int n2 = 0; n2 < 2; ++n2) acc[m][nh * 2 + n2] = __builtin_amdgcn_mfma_f32_16x16x32_bf16(bfr[n2], af[m], acc[m][nh * 2 + n2], 0, 0, 0);
;     }
;     __builtin_amdgcn_s_setprio(0);
;     __syncthreads();
	s_waitcnt vmcnt(0)
	v_add_u32_e32 v176, v169, v170
	v_cvt_pk_bf16_f32 v164, v28, v29
	v_cvt_pk_bf16_f32 v165, v30, v31
	v_cvt_pk_bf16_f32 v166, v24, v25
	v_cvt_pk_bf16_f32 v167, v26, v27
	ds_write2st64_b64 v161, v[164:165], v[166:167] offset0:60 offset1:65
	v_cvt_pk_bf16_f32 v164, v20, v21
	v_cvt_pk_bf16_f32 v165, v22, v23
	v_cvt_pk_bf16_f32 v166, v16, v17
	v_cvt_pk_bf16_f32 v167, v18, v19
	ds_write2st64_b64 v161, v[164:165], v[166:167] offset0:70 offset1:75
	ds_write_b128 v163, v[0:3] offset:40960
	ds_write_b128 v163, v[4:7] offset:46080
	ds_write_b128 v163, v[8:11] offset:51200
	ds_write_b128 v163, v[12:15] offset:56320
	s_setprio 1
	v_add_u32_e32 v193, v168, v170
	ds_read_b128 v[160:163], v193 offset:10240
	ds_read_b128 v[164:167], v193 offset:11520
	ds_read_b128 v[168:171], v176
	ds_read_b128 v[172:175], v176 offset:1280
	ds_read_b128 v[194:197], v176 offset:2560
	ds_read_b128 v[198:201], v176 offset:3840
	s_waitcnt lgkmcnt(3)
	v_mfma_f32_16x16x32_bf16 v[156:159], v[160:163], v[168:171], v[156:159]
	v_mfma_f32_16x16x32_bf16 v[152:155], v[164:167], v[168:171], v[152:155]
	s_waitcnt lgkmcnt(2)
	v_mfma_f32_16x16x32_bf16 v[140:143], v[160:163], v[172:175], v[140:143]
	v_mfma_f32_16x16x32_bf16 v[136:139], v[164:167], v[172:175], v[136:139]
	s_waitcnt lgkmcnt(1)
	v_mfma_f32_16x16x32_bf16 v[108:111], v[160:163], v[194:197], v[108:111]
	v_mfma_f32_16x16x32_bf16 v[100:103], v[164:167], v[194:197], v[100:103]
	s_waitcnt lgkmcnt(0)
	v_mfma_f32_16x16x32_bf16 v[76:79], v[160:163], v[198:201], v[76:79]
	ds_read_b128 v[160:163], v193 offset:12800
	v_mfma_f32_16x16x32_bf16 v[68:71], v[164:167], v[198:201], v[68:71]
	ds_read_b128 v[164:167], v193 offset:14080
	s_waitcnt lgkmcnt(1)
	v_mfma_f32_16x16x32_bf16 v[148:151], v[160:163], v[168:171], v[148:151]
	s_waitcnt lgkmcnt(0)
	v_mfma_f32_16x16x32_bf16 v[144:147], v[164:167], v[168:171], v[144:147]
	v_mfma_f32_16x16x32_bf16 v[124:127], v[160:163], v[172:175], v[124:127]
	v_mfma_f32_16x16x32_bf16 v[116:119], v[164:167], v[172:175], v[116:119]
	v_mfma_f32_16x16x32_bf16 v[92:95], v[160:163], v[194:197], v[92:95]
	v_mfma_f32_16x16x32_bf16 v[84:87], v[164:167], v[194:197], v[84:87]
	v_mfma_f32_16x16x32_bf16 v[60:63], v[160:163], v[198:201], v[60:63]
	ds_read_b128 v[160:163], v193 offset:15360
	v_mfma_f32_16x16x32_bf16 v[52:55], v[164:167], v[198:201], v[52:55]
	ds_read_b128 v[164:167], v193 offset:16640
	s_waitcnt lgkmcnt(1)
	v_mfma_f32_16x16x32_bf16 v[212:215], v[160:163], v[194:197], v[72:75]
	s_nop 2
	ds_read_b128 v[72:75], v193 offset:19200
	s_waitcnt lgkmcnt(1)
	v_mfma_f32_16x16x32_bf16 v[216:219], v[164:167], v[194:197], v[64:67]
	s_nop 2
	ds_read_b128 v[64:67], v193 offset:17920
	v_mfma_f32_16x16x32_bf16 v[128:131], v[164:167], v[168:171], v[128:131]
	v_mfma_f32_16x16x32_bf16 v[96:99], v[164:167], v[172:175], v[96:99]
	s_waitcnt lgkmcnt(0)
	v_mfma_f32_16x16x32_bf16 v[120:123], v[64:67], v[168:171], v[120:123]
	v_mfma_f32_16x16x32_bf16 v[112:115], v[72:75], v[168:171], v[112:115]
	v_mfma_f32_16x16x32_bf16 v[88:91], v[64:67], v[172:175], v[88:91]
	v_mfma_f32_16x16x32_bf16 v[80:83], v[72:75], v[172:175], v[80:83]
	v_mfma_f32_16x16x32_bf16 v[48:51], v[72:75], v[194:197], v[48:51]
	v_mfma_f32_16x16x32_bf16 v[202:205], v[160:163], v[168:171], v[132:135]
	v_mfma_f32_16x16x32_bf16 v[206:209], v[160:163], v[172:175], v[104:107]
	v_mfma_f32_16x16x32_bf16 v[44:47], v[160:163], v[198:201], v[44:47]
	v_mfma_f32_16x16x32_bf16 v[40:43], v[164:167], v[198:201], v[40:43]
	v_mfma_f32_16x16x32_bf16 v[220:223], v[64:67], v[194:197], v[56:59]
	v_mfma_f32_16x16x32_bf16 v[36:39], v[64:67], v[198:201], v[36:39]
	v_mfma_f32_16x16x32_bf16 v[32:35], v[72:75], v[198:201], v[32:35]
	s_setprio 0
	s_barrier
; #define G_LOAD(kt_) do { \
;     if constexpr (AF32) { _Pragma("unroll") for (int i = 0; i < 4; ++i) ld16_sc1(ra[i], Af + (size_t)i * 32 * lda + (kt_) * 32); } \
;     else { _Pragma("unroll") for (int i = 0; i < 2; ++i) ld16_sc1(rab[i], Ab + (size_t)i * 64 * lda + (kt_) * 32); } \
;     _Pragma("unroll") for (int i = 0; i < 4; ++i) ld16_sc1(rb[i], Bp + (size_t)(kt_) * bstep + i * 2048); } while (0)
; template <bool AF32, class Epi>
; __device__ __forceinline__ void gemm_tile(unsigned char* smem, const void* Ap, int lda, const bf16_t* WT, int N, int K, const Epi& epi, int m0, int n0,
;                                           GPre& pr, bool preloaded, const void* nAp, int nn0, bool has_next) {
;     ...
;     const bf16_t* a_s = sbase + cur * G_STAGE + (wr * 64 + l15) * GLD + quad * 8;
;     const bf16_t* b_s = sbase + cur * G_STAGE + 128 * GLD + (wc * 128 + l15) * GLD + quad * 8;
;     __builtin_amdgcn_s_setprio(1);
;     bf16x8 af[4];
; #pragma unroll
;     for (int m = 0; m < 4; ++m) af[m] = *(const bf16x8*)(a_s + m * 16 * GLD);
; #pragma unroll
;     for (int nh = 0; nh < 4; ++nh) {
;       bf16x8 bfr[2];
; #pragma unroll
;       for (int n2 = 0; n2 < 2; ++n2) bfr[n2] = *(const bf16x8*)(b_s + (nh * 2 + n2) * 16 * GLD);
; #pragma unroll
;       for (int m = 0; m < 4; ++m)
; #pragma unroll
;         for (int n2 = 0; n2 < 2; ++n2) acc[m][nh * 2 + n2] = __builtin_amdgcn_mfma_f32_16x16x32_bf16(bfr[n2], af[m], acc[m][nh * 2 + n2], 0, 0, 0);
;     }
;     __builtin_amdgcn_s_setprio(0);
;     __syncthreads();
;   }
;   if (has_next) {
;     const float* Af = (const float*)nAp + (size_t)(tid >> 3) * lda + (tid & 7) * 4;
;     const bf16_t* Ab = (const bf16_t*)nAp + (size_t)(tid >> 2) * lda + (tid & 3) * 8;
;     const bf16_t* Bp = WT + (size_t)nn0 * 32 + tid * 8;
;     G_LOAD(0);
;   }
	s_setprio 1
	ds_read_b128 v[56:59], v193 offset:40960
	ds_read_b128 v[64:67], v193 offset:42240
	ds_read_b128 v[194:197], v176 offset:30720
	ds_read_b128 v[198:201], v176 offset:32000
	ds_read_b128 v[224:227], v176 offset:33280
	ds_read_b128 v[228:231], v176 offset:34560
	s_waitcnt lgkmcnt(3)
	v_mfma_f32_16x16x32_bf16 v[172:175], v[56:59], v[194:197], v[156:159]
	v_mfma_f32_16x16x32_bf16 v[164:167], v[64:67], v[194:197], v[152:155]
	s_waitcnt lgkmcnt(2)
	v_mfma_f32_16x16x32_bf16 v[140:143], v[56:59], v[198:201], v[140:143]
	v_mfma_f32_16x16x32_bf16 v[132:135], v[64:67], v[198:201], v[136:139]
	s_waitcnt lgkmcnt(1)
	v_mfma_f32_16x16x32_bf16 v[108:111], v[56:59], v[224:227], v[108:111]
	v_mfma_f32_16x16x32_bf16 v[100:103], v[64:67], v[224:227], v[100:103]
	s_waitcnt lgkmcnt(0)
	v_mfma_f32_16x16x32_bf16 v[76:79], v[56:59], v[228:231], v[76:79]
	ds_read_b128 v[56:59], v193 offset:43520
	v_mfma_f32_16x16x32_bf16 v[72:75], v[64:67], v[228:231], v[68:71]
	ds_read_b128 v[64:67], v193 offset:44800
	s_waitcnt lgkmcnt(1)
	v_mfma_f32_16x16x32_bf16 v[168:171], v[56:59], v[194:197], v[148:151]
	s_waitcnt lgkmcnt(0)
	v_mfma_f32_16x16x32_bf16 v[156:159], v[64:67], v[194:197], v[144:147]
	v_mfma_f32_16x16x32_bf16 v[136:139], v[56:59], v[198:201], v[124:127]
	v_mfma_f32_16x16x32_bf16 v[124:127], v[64:67], v[198:201], v[116:119]
	v_mfma_f32_16x16x32_bf16 v[104:107], v[56:59], v[224:227], v[92:95]
	v_mfma_f32_16x16x32_bf16 v[92:95], v[64:67], v[224:227], v[84:87]
	v_mfma_f32_16x16x32_bf16 v[68:71], v[56:59], v[228:231], v[60:63]
	ds_read_b128 v[56:59], v193 offset:46080
	v_mfma_f32_16x16x32_bf16 v[64:67], v[64:67], v[228:231], v[52:55]
	s_nop 2
	ds_read_b128 v[52:55], v193 offset:47360
	s_waitcnt lgkmcnt(1)
	v_mfma_f32_16x16x32_bf16 v[160:163], v[56:59], v[194:197], v[202:205]
	s_waitcnt lgkmcnt(0)
	v_mfma_f32_16x16x32_bf16 v[148:151], v[52:55], v[194:197], v[128:131]
	v_mfma_f32_16x16x32_bf16 v[128:131], v[56:59], v[198:201], v[206:209]
	v_mfma_f32_16x16x32_bf16 v[116:119], v[52:55], v[198:201], v[96:99]
	v_mfma_f32_16x16x32_bf16 v[96:99], v[56:59], v[224:227], v[212:215]
	v_mfma_f32_16x16x32_bf16 v[60:63], v[56:59], v[228:231], v[44:47]
	s_nop 2
	ds_read_b128 v[44:47], v193 offset:48640
	v_mfma_f32_16x16x32_bf16 v[56:59], v[52:55], v[228:231], v[40:43]
	s_nop 2
	ds_read_b128 v[40:43], v193 offset:49920
	v_mfma_f32_16x16x32_bf16 v[84:87], v[52:55], v[224:227], v[216:219]
	s_waitcnt lgkmcnt(1)
	v_mfma_f32_16x16x32_bf16 v[152:155], v[44:47], v[194:197], v[120:123]
	s_waitcnt lgkmcnt(0)
	v_mfma_f32_16x16x32_bf16 v[144:147], v[40:43], v[194:197], v[112:115]
	v_mfma_f32_16x16x32_bf16 v[120:123], v[44:47], v[198:201], v[88:91]
	v_mfma_f32_16x16x32_bf16 v[112:115], v[40:43], v[198:201], v[80:83]
	v_mfma_f32_16x16x32_bf16 v[88:91], v[44:47], v[224:227], v[220:223]
	v_mfma_f32_16x16x32_bf16 v[80:83], v[40:43], v[224:227], v[48:51]
	v_mfma_f32_16x16x32_bf16 v[52:55], v[44:47], v[228:231], v[36:39]
	v_mfma_f32_16x16x32_bf16 v[48:51], v[40:43], v[228:231], v[32:35]
	s_and_b64 vcc, exec, s[6:7]
	s_barrier
	s_cbranch_vccz .LBB0_463
	s_ashr_i32 s53, s52, 31
	s_lshl_b64 s[6:7], s[52:53], 19
	s_add_u32 s6, s12, s6
	s_addc_u32 s7, s13, s7
	s_lshl_b32 s52, s68, 8
	v_lshl_add_u64 v[0:1], v[188:189], 2, s[6:7]
	v_lshlrev_b32_e32 v176, 2, v190
	s_ashr_i32 s53, s52, 31
	v_lshl_add_u64 v[0:1], v[0:1], 0, v[176:177]
	s_lshl_b64 s[6:7], s[52:53], 6
	global_load_dwordx4 v[40:43], v[0:1], off sc1
	s_add_u32 s6, s2, s6
	v_lshl_add_u64 v[2:3], v[0:1], 0, s[16:17]
	global_load_dwordx4 v[44:47], v[2:3], off sc1
	s_addc_u32 s7, s33, s7
	v_lshl_add_u64 v[2:3], v[0:1], 0, s[18:19]
	global_load_dwordx4 v[32:35], v[2:3], off sc1
	v_lshl_add_u64 v[0:1], v[0:1], 0, s[20:21]
	global_load_dwordx4 v[36:39], v[0:1], off sc1
	v_lshl_add_u64 v[12:13], v[184:185], 1, s[6:7]
	global_load_dwordx4 v[0:3], v[12:13], off sc1
	v_lshl_add_u64 v[4:5], v[12:13], 0, s[22:23]
	global_load_dwordx4 v[4:7], v[4:5], off sc1
	v_lshl_add_u64 v[8:9], v[12:13], 0, s[24:25]
	global_load_dwordx4 v[8:11], v[8:9], off sc1
	v_lshl_add_u64 v[12:13], v[12:13], 0, s[26:27]
	global_load_dwordx4 v[12:15], v[12:13], off sc1
	s_branch .LBB0_464

; #define G_LOAD(kt_) do { \
;     if constexpr (AF32) { _Pragma("unroll") for (int i = 0; i < 4; ++i) ld16_sc1(ra[i], Af + (size_t)i * 32 * lda + (kt_) * 32); } \
;     else { _Pragma("unroll") for (int i = 0; i < 2; ++i) ld16_sc1(rab[i], Ab + (size_t)i * 64 * lda + (kt_) * 32); } \
;     _Pragma("unroll") for (int i = 0; i < 4; ++i) ld16_sc1(rb[i], Bp + (size_t)(kt_) * bstep + i * 2048); } while (0)
; template <bool AF32, class Epi>
; __device__ __forceinline__ void gemm_tile(unsigned char* smem, const void* Ap, int lda, const bf16_t* WT, int N, int K, const Epi& epi, int m0, int n0,
;                                           GPre& pr, bool preloaded, const void* nAp, int nn0, bool has_next) {
;     ...
;   if (!preloaded) G_LOAD(0);
;   G_STORE(0);
;   if (nk > 1) G_LOAD(1);
;   __syncthreads();
;   for (int kt = 0; kt < nk; ++kt) {
;     const int cur = kt & 1;
;     if (kt + 1 < nk) G_STORE(cur ^ 1);
;     if (kt + 2 < nk) G_LOAD(kt + 2);
;     const bf16_t* a_s = sbase + cur * G_STAGE + (wr * 64 + l15) * GLD + quad * 8;
;     const bf16_t* b_s = sbase + cur * G_STAGE + 128 * GLD + (wc * 128 + l15) * GLD + quad * 8;
;     __builtin_amdgcn_s_setprio(1);
;     bf16x8 af[4];
; #pragma unroll
;     for (int m = 0; m < 4; ++m) af[m] = *(const bf16x8*)(a_s + m * 16 * GLD);
; #pragma unroll
;     for (int nh = 0; nh < 4; ++nh) {
;       bf16x8 bfr[2];
; #pragma unroll
;       for (int n2 = 0; n2 < 2; ++n2) bfr[n2] = *(const bf16x8*)(b_s + (nh * 2 + n2) * 16 * GLD);
; #pragma unroll
;       for (int m = 0; m < 4; ++m)
; #pragma unroll
;         for (int n2 = 0; n2 < 2; ++n2) acc[m][nh * 2 + n2] = __builtin_amdgcn_mfma_f32_16x16x32_bf16(bfr[n2], af[m], acc[m][nh * 2 + n2], 0, 0, 0);
;     }
;     __builtin_amdgcn_s_setprio(0);
;     __syncthreads();
;   }
.LBB0_555:
	s_and_b32 s3, s50, 1
	s_waitcnt vmcnt(0)
	s_xor_b32 s51, s3, 1
	s_mulk_i32 s51, 0x7800
	v_add_u32_e32 v176, s51, v155
	ds_write_b128 v176, v[0:3]
	ds_write_b128 v176, v[4:7] offset:5120
	ds_write_b128 v176, v[8:11] offset:10240
	ds_write_b128 v176, v[12:15] offset:15360
	ds_write_b128 v176, v[16:19] offset:20480
	ds_write_b128 v176, v[20:23] offset:25600
	global_load_dwordx4 v[0:3], v[162:163], off sc1
	v_lshl_add_u64 v[168:169], v[162:163], 0, s[10:11]
	global_load_dwordx4 v[4:7], v[168:169], off sc1
	global_load_dwordx4 v[8:11], v[160:161], off sc1
	v_lshl_add_u64 v[170:171], v[160:161], 0, s[12:13]
	global_load_dwordx4 v[12:15], v[170:171], off sc1
	v_lshl_add_u64 v[172:173], v[160:161], 0, s[14:15]
	global_load_dwordx4 v[16:19], v[172:173], off sc1
	v_lshl_add_u64 v[174:175], v[160:161], 0, s[16:17]
	global_load_dwordx4 v[20:23], v[174:175], off sc1
	s_add_i32 s50, s50, 1
	s_mulk_i32 s3, 0x7800
	v_add3_u32 v188, s3, v166, v167
	s_setprio 1
	v_add3_u32 v192, s3, v165, v167
	ds_read_b128 v[168:171], v192 offset:10240
	ds_read_b128 v[172:175], v192 offset:11520
	ds_read_b128 v[176:179], v188
	ds_read_b128 v[180:183], v188 offset:1280
	ds_read_b128 v[184:187], v188 offset:2560
	ds_read_b128 v[188:191], v188 offset:3840
	s_waitcnt lgkmcnt(3)
	v_mfma_f32_16x16x32_bf16 v[148:151], v[168:171], v[176:179], v[148:151]
	v_mfma_f32_16x16x32_bf16 v[144:147], v[172:175], v[176:179], v[144:147]
	s_waitcnt lgkmcnt(2)
	v_mfma_f32_16x16x32_bf16 v[132:135], v[168:171], v[180:183], v[132:135]
	v_mfma_f32_16x16x32_bf16 v[128:131], v[172:175], v[180:183], v[128:131]
	s_waitcnt lgkmcnt(1)
	v_mfma_f32_16x16x32_bf16 v[100:103], v[168:171], v[184:187], v[100:103]
	v_mfma_f32_16x16x32_bf16 v[92:95], v[172:175], v[184:187], v[92:95]
	s_waitcnt lgkmcnt(0)
	v_mfma_f32_16x16x32_bf16 v[68:71], v[168:171], v[188:191], v[68:71]
	ds_read_b128 v[168:171], v192 offset:12800
	v_mfma_f32_16x16x32_bf16 v[60:63], v[172:175], v[188:191], v[60:63]
	ds_read_b128 v[172:175], v192 offset:14080
	s_waitcnt lgkmcnt(1)
	v_mfma_f32_16x16x32_bf16 v[140:143], v[168:171], v[176:179], v[140:143]
	s_waitcnt lgkmcnt(0)
	v_mfma_f32_16x16x32_bf16 v[136:139], v[172:175], v[176:179], v[136:139]
	v_mfma_f32_16x16x32_bf16 v[116:119], v[168:171], v[180:183], v[116:119]
	v_mfma_f32_16x16x32_bf16 v[108:111], v[172:175], v[180:183], v[108:111]
	v_mfma_f32_16x16x32_bf16 v[84:87], v[168:171], v[184:187], v[84:87]
	v_mfma_f32_16x16x32_bf16 v[76:79], v[172:175], v[184:187], v[76:79]
	v_mfma_f32_16x16x32_bf16 v[52:55], v[168:171], v[188:191], v[52:55]
	ds_read_b128 v[168:171], v192 offset:15360
	v_mfma_f32_16x16x32_bf16 v[44:47], v[172:175], v[188:191], v[44:47]
	ds_read_b128 v[172:175], v192 offset:16640
	s_waitcnt lgkmcnt(1)
	v_mfma_f32_16x16x32_bf16 v[124:127], v[168:171], v[176:179], v[124:127]
	s_waitcnt lgkmcnt(0)
	v_mfma_f32_16x16x32_bf16 v[120:123], v[172:175], v[176:179], v[120:123]
	v_mfma_f32_16x16x32_bf16 v[96:99], v[168:171], v[180:183], v[96:99]
	v_mfma_f32_16x16x32_bf16 v[88:91], v[172:175], v[180:183], v[88:91]
	v_mfma_f32_16x16x32_bf16 v[64:67], v[168:171], v[184:187], v[64:67]
	v_mfma_f32_16x16x32_bf16 v[56:59], v[172:175], v[184:187], v[56:59]
	v_mfma_f32_16x16x32_bf16 v[36:39], v[168:171], v[188:191], v[36:39]
	ds_read_b128 v[168:171], v192 offset:17920
	v_mfma_f32_16x16x32_bf16 v[32:35], v[172:175], v[188:191], v[32:35]
	ds_read_b128 v[172:175], v192 offset:19200
	s_waitcnt lgkmcnt(1)
	v_mfma_f32_16x16x32_bf16 v[112:115], v[168:171], v[176:179], v[112:115]
	s_waitcnt lgkmcnt(0)
	v_mfma_f32_16x16x32_bf16 v[104:107], v[172:175], v[176:179], v[104:107]
	v_mfma_f32_16x16x32_bf16 v[80:83], v[168:171], v[180:183], v[80:83]
	v_mfma_f32_16x16x32_bf16 v[72:75], v[172:175], v[180:183], v[72:75]
	v_mfma_f32_16x16x32_bf16 v[48:51], v[168:171], v[184:187], v[48:51]
	v_mfma_f32_16x16x32_bf16 v[40:43], v[172:175], v[184:187], v[40:43]
	v_mfma_f32_16x16x32_bf16 v[28:31], v[168:171], v[188:191], v[28:31]
	v_mfma_f32_16x16x32_bf16 v[24:27], v[172:175], v[188:191], v[24:27]
	s_setprio 0
	v_lshl_add_u64 v[160:161], v[160:161], 0, s[20:21]
	s_cmp_eq_u32 s50, 30
	v_lshl_add_u64 v[162:163], v[162:163], 0, 64
	s_barrier
	s_cbranch_scc0 .LBB0_555
	s_waitcnt vmcnt(0)
	ds_write_b128 v155, v[0:3] offset:30720
	ds_write_b128 v155, v[4:7] offset:35840
	ds_write_b128 v155, v[8:11] offset:40960
	ds_write_b128 v155, v[12:15] offset:46080
	ds_write_b128 v155, v[16:19] offset:51200
	ds_write_b128 v155, v[20:23] offset:56320
	v_add_u32_e32 v155, v166, v167
	s_setprio 1
	v_add_u32_e32 v165, v165, v167
	ds_read_b128 v[160:163], v165 offset:10240
	ds_read_b128 v[166:169], v165 offset:11520
	ds_read_b128 v[170:173], v155
	ds_read_b128 v[174:177], v155 offset:1280
	ds_read_b128 v[178:181], v155 offset:2560
	ds_read_b128 v[182:185], v155 offset:3840
	s_waitcnt lgkmcnt(3)
	v_mfma_f32_16x16x32_bf16 v[148:151], v[160:163], v[170:173], v[148:151]
	v_mfma_f32_16x16x32_bf16 v[144:147], v[166:169], v[170:173], v[144:147]
	s_waitcnt lgkmcnt(2)
	v_mfma_f32_16x16x32_bf16 v[132:135], v[160:163], v[174:177], v[132:135]
	v_mfma_f32_16x16x32_bf16 v[128:131], v[166:169], v[174:177], v[128:131]
	s_waitcnt lgkmcnt(1)
	v_mfma_f32_16x16x32_bf16 v[100:103], v[160:163], v[178:181], v[100:103]
	v_mfma_f32_16x16x32_bf16 v[92:95], v[166:169], v[178:181], v[92:95]
	s_waitcnt lgkmcnt(0)
	v_mfma_f32_16x16x32_bf16 v[68:71], v[160:163], v[182:185], v[68:71]
	ds_read_b128 v[160:163], v165 offset:12800
	v_mfma_f32_16x16x32_bf16 v[60:63], v[166:169], v[182:185], v[60:63]
	ds_read_b128 v[166:169], v165 offset:14080
	s_waitcnt lgkmcnt(1)
	v_mfma_f32_16x16x32_bf16 v[186:189], v[160:163], v[170:173], v[140:143]
	s_waitcnt lgkmcnt(0)
; #define G_LOAD(kt_) do { \
;     if constexpr (AF32) { _Pragma("unroll") for (int i = 0; i < 4; ++i) ld16_sc1(ra[i], Af + (size_t)i * 32 * lda + (kt_) * 32); } \
;     else { _Pragma("unroll") for (int i = 0; i < 2; ++i) ld16_sc1(rab[i], Ab + (size_t)i * 64 * lda + (kt_) * 32); } \
;     _Pragma("unroll") for (int i = 0; i < 4; ++i) ld16_sc1(rb[i], Bp + (size_t)(kt_) * bstep + i * 2048); } while (0)
; template <bool AF32, class Epi>
; __device__ __forceinline__ void gemm_tile(unsigned char* smem, const void* Ap, int lda, const bf16_t* WT, int N, int K, const Epi& epi, int m0, int n0,
;                                           GPre& pr, bool preloaded, const void* nAp, int nn0, bool has_next) {
;     ...
;   for (int kt = 0; kt < nk; ++kt) {
;     const int cur = kt & 1;
;     if (kt + 1 < nk) G_STORE(cur ^ 1);
;     if (kt + 2 < nk) G_LOAD(kt + 2);
;     const bf16_t* a_s = sbase + cur * G_STAGE + (wr * 64 + l15) * GLD + quad * 8;
;     const bf16_t* b_s = sbase + cur * G_STAGE + 128 * GLD + (wc * 128 + l15) * GLD + quad * 8;
;     __builtin_amdgcn_s_setprio(1);
;     bf16x8 af[4];
; #pragma unroll
;     for (int m = 0; m < 4; ++m) af[m] = *(const bf16x8*)(a_s + m * 16 * GLD);
; #pragma unroll
;     for (int nh = 0; nh < 4; ++nh) {
;       bf16x8 bfr[2];
; #pragma unroll
;       for (int n2 = 0; n2 < 2; ++n2) bfr[n2] = *(const bf16x8*)(b_s + (nh * 2 + n2) * 16 * GLD);
; #pragma unroll
;       for (int m = 0; m < 4; ++m)
; #pragma unroll
;         for (int n2 = 0; n2 < 2; ++n2) acc[m][nh * 2 + n2] = __builtin_amdgcn_mfma_f32_16x16x32_bf16(bfr[n2], af[m], acc[m][nh * 2 + n2], 0, 0, 0);
;     }
;     __builtin_amdgcn_s_setprio(0);
;     __syncthreads();
;   }
;   if (has_next) {
;     const float* Af = (const float*)nAp + (size_t)(tid >> 3) * lda + (tid & 7) * 4;
;     const bf16_t* Ab = (const bf16_t*)nAp + (size_t)(tid >> 2) * lda + (tid & 3) * 8;
;     const bf16_t* Bp = WT + (size_t)nn0 * 32 + tid * 8;
;     G_LOAD(0);
;   }
	v_mfma_f32_16x16x32_bf16 v[136:139], v[166:169], v[170:173], v[136:139]
	v_mfma_f32_16x16x32_bf16 v[190:193], v[160:163], v[174:177], v[116:119]
	v_mfma_f32_16x16x32_bf16 v[194:197], v[166:169], v[174:177], v[108:111]
	v_mfma_f32_16x16x32_bf16 v[198:201], v[160:163], v[178:181], v[84:87]
	v_mfma_f32_16x16x32_bf16 v[202:205], v[166:169], v[178:181], v[76:79]
	v_mfma_f32_16x16x32_bf16 v[160:163], v[160:163], v[182:185], v[52:55]
	s_nop 2
	ds_read_b128 v[52:55], v165 offset:15360
	v_mfma_f32_16x16x32_bf16 v[166:169], v[166:169], v[182:185], v[44:47]
	s_nop 2
	ds_read_b128 v[44:47], v165 offset:16640
	s_waitcnt lgkmcnt(1)
	v_mfma_f32_16x16x32_bf16 v[124:127], v[52:55], v[170:173], v[124:127]
	s_waitcnt lgkmcnt(0)
	v_mfma_f32_16x16x32_bf16 v[120:123], v[44:47], v[170:173], v[120:123]
	v_mfma_f32_16x16x32_bf16 v[96:99], v[52:55], v[174:177], v[96:99]
	v_mfma_f32_16x16x32_bf16 v[88:91], v[44:47], v[174:177], v[88:91]
	v_mfma_f32_16x16x32_bf16 v[64:67], v[52:55], v[178:181], v[64:67]
	v_mfma_f32_16x16x32_bf16 v[56:59], v[44:47], v[178:181], v[56:59]
	v_mfma_f32_16x16x32_bf16 v[36:39], v[52:55], v[182:185], v[36:39]
	ds_read_b128 v[52:55], v165 offset:17920
	v_mfma_f32_16x16x32_bf16 v[32:35], v[44:47], v[182:185], v[32:35]
	ds_read_b128 v[44:47], v165 offset:19200
	s_waitcnt lgkmcnt(1)
	v_mfma_f32_16x16x32_bf16 v[28:31], v[52:55], v[182:185], v[28:31]
	s_waitcnt lgkmcnt(0)
	v_mfma_f32_16x16x32_bf16 v[24:27], v[44:47], v[182:185], v[24:27]
	v_mfma_f32_16x16x32_bf16 v[206:209], v[52:55], v[170:173], v[112:115]
	v_mfma_f32_16x16x32_bf16 v[170:173], v[44:47], v[170:173], v[104:107]
	v_mfma_f32_16x16x32_bf16 v[212:215], v[52:55], v[174:177], v[80:83]
	v_mfma_f32_16x16x32_bf16 v[174:177], v[44:47], v[174:177], v[72:75]
	v_mfma_f32_16x16x32_bf16 v[216:219], v[52:55], v[178:181], v[48:51]
	v_mfma_f32_16x16x32_bf16 v[178:181], v[44:47], v[178:181], v[40:43]
	s_setprio 0
	s_barrier
	s_setprio 1
	ds_read_b128 v[40:43], v165 offset:40960
	ds_read_b128 v[44:47], v165 offset:42240
	ds_read_b128 v[182:185], v155 offset:30720
	ds_read_b128 v[220:223], v155 offset:32000
	ds_read_b128 v[224:227], v155 offset:33280
	ds_read_b128 v[228:231], v155 offset:34560
	s_waitcnt lgkmcnt(3)
	v_mfma_f32_16x16x32_bf16 v[148:151], v[40:43], v[182:185], v[148:151]
	s_waitcnt lgkmcnt(2)
	v_mfma_f32_16x16x32_bf16 v[116:119], v[40:43], v[220:223], v[132:135]
	s_waitcnt lgkmcnt(1)
	v_mfma_f32_16x16x32_bf16 v[84:87], v[40:43], v[224:227], v[100:103]
	s_waitcnt lgkmcnt(0)
	v_mfma_f32_16x16x32_bf16 v[52:55], v[40:43], v[228:231], v[68:71]
	ds_read_b128 v[40:43], v165 offset:43520
	v_mfma_f32_16x16x32_bf16 v[48:51], v[44:47], v[228:231], v[60:63]
	s_nop 2
	ds_read_b128 v[60:63], v165 offset:44800
	v_mfma_f32_16x16x32_bf16 v[140:143], v[44:47], v[182:185], v[144:147]
	v_mfma_f32_16x16x32_bf16 v[108:111], v[44:47], v[220:223], v[128:131]
	v_mfma_f32_16x16x32_bf16 v[80:83], v[44:47], v[224:227], v[92:95]
	s_waitcnt lgkmcnt(1)
	v_mfma_f32_16x16x32_bf16 v[144:147], v[40:43], v[182:185], v[186:189]
	s_nop 0
	ds_read_b128 v[92:95], v165 offset:46080
	s_waitcnt lgkmcnt(1)
	v_mfma_f32_16x16x32_bf16 v[136:139], v[60:63], v[182:185], v[136:139]
	v_mfma_f32_16x16x32_bf16 v[112:115], v[40:43], v[220:223], v[190:193]
	v_mfma_f32_16x16x32_bf16 v[104:107], v[60:63], v[220:223], v[194:197]
	v_mfma_f32_16x16x32_bf16 v[76:79], v[40:43], v[224:227], v[198:201]
	v_mfma_f32_16x16x32_bf16 v[72:75], v[60:63], v[224:227], v[202:205]
	v_mfma_f32_16x16x32_bf16 v[44:47], v[40:43], v[228:231], v[160:163]
	v_mfma_f32_16x16x32_bf16 v[40:43], v[60:63], v[228:231], v[166:169]
	ds_read_b128 v[60:63], v165 offset:47360
	s_nop 0
	ds_read_b128 v[160:163], v165 offset:48640
	ds_read_b128 v[166:169], v165 offset:49920
	s_waitcnt lgkmcnt(3)
	v_mfma_f32_16x16x32_bf16 v[132:135], v[92:95], v[182:185], v[124:127]
	s_waitcnt lgkmcnt(2)
	v_mfma_f32_16x16x32_bf16 v[128:131], v[60:63], v[182:185], v[120:123]
	v_mfma_f32_16x16x32_bf16 v[100:103], v[92:95], v[220:223], v[96:99]
	v_mfma_f32_16x16x32_bf16 v[96:99], v[60:63], v[220:223], v[88:91]
	v_mfma_f32_16x16x32_bf16 v[68:71], v[92:95], v[224:227], v[64:67]
	v_mfma_f32_16x16x32_bf16 v[64:67], v[60:63], v[224:227], v[56:59]
	v_mfma_f32_16x16x32_bf16 v[36:39], v[92:95], v[228:231], v[36:39]
	v_mfma_f32_16x16x32_bf16 v[32:35], v[60:63], v[228:231], v[32:35]
	s_waitcnt lgkmcnt(1)
	v_mfma_f32_16x16x32_bf16 v[124:127], v[160:163], v[182:185], v[206:209]
	s_waitcnt lgkmcnt(0)
	v_mfma_f32_16x16x32_bf16 v[120:123], v[166:169], v[182:185], v[170:173]
	v_mfma_f32_16x16x32_bf16 v[92:95], v[160:163], v[220:223], v[212:215]
	v_mfma_f32_16x16x32_bf16 v[88:91], v[166:169], v[220:223], v[174:177]
	v_mfma_f32_16x16x32_bf16 v[60:63], v[160:163], v[224:227], v[216:219]
	v_mfma_f32_16x16x32_bf16 v[56:59], v[166:169], v[224:227], v[178:181]
	v_mfma_f32_16x16x32_bf16 v[28:31], v[160:163], v[228:231], v[28:31]
	v_mfma_f32_16x16x32_bf16 v[24:27], v[166:169], v[228:231], v[24:27]
	s_and_b64 vcc, exec, s[46:47]
	s_barrier
	s_cbranch_vccz .LBB0_543
	s_mul_i32 s46, s67, 0xc0000
	s_mul_hi_i32 s3, s67, 0xc0000
	s_add_u32 s46, s2, s46
	s_addc_u32 s47, s33, s3
	s_lshl_b32 s50, s66, 8
	s_ashr_i32 s51, s50, 31
	v_lshl_add_u64 v[0:1], v[158:159], 1, s[46:47]
	s_lshl_b64 s[46:47], s[50:51], 6
	v_lshl_add_u64 v[4:5], v[0:1], 0, v[152:153]
	s_add_u32 s46, s54, s46
	s_addc_u32 s47, s55, s47
	global_load_dwordx4 v[0:3], v[4:5], off sc1
	v_lshl_add_u64 v[4:5], v[4:5], 0, s[10:11]
	global_load_dwordx4 v[4:7], v[4:5], off sc1
	v_lshl_add_u64 v[20:21], v[156:157], 1, s[46:47]
	global_load_dwordx4 v[8:11], v[20:21], off sc1
	v_lshl_add_u64 v[12:13], v[20:21], 0, s[12:13]
	global_load_dwordx4 v[12:15], v[12:13], off sc1
	v_lshl_add_u64 v[16:17], v[20:21], 0, s[14:15]
	global_load_dwordx4 v[16:19], v[16:17], off sc1
	v_lshl_add_u64 v[20:21], v[20:21], 0, s[16:17]
	global_load_dwordx4 v[20:23], v[20:21], off sc1
	s_branch .LBB0_543

; #define G_LOAD(kt_) do { \
;     if constexpr (AF32) { _Pragma("unroll") for (int i = 0; i < 4; ++i) ld16_sc1(ra[i], Af + (size_t)i * 32 * lda + (kt_) * 32); } \
;     else { _Pragma("unroll") for (int i = 0; i < 2; ++i) ld16_sc1(rab[i], Ab + (size_t)i * 64 * lda + (kt_) * 32); } \
;     _Pragma("unroll") for (int i = 0; i < 4; ++i) ld16_sc1(rb[i], Bp + (size_t)(kt_) * bstep + i * 2048); } while (0)
; template <bool AF32, class Epi>
; __device__ __forceinline__ void gemm_tile(unsigned char* smem, const void* Ap, int lda, const bf16_t* WT, int N, int K, const Epi& epi, int m0, int n0,
;                                           GPre& pr, bool preloaded, const void* nAp, int nn0, bool has_next) {
;     ...
;   if (!preloaded) G_LOAD(0);
;   G_STORE(0);
;   if (nk > 1) G_LOAD(1);
;   __syncthreads();
;   for (int kt = 0; kt < nk; ++kt) {
;     const int cur = kt & 1;
;     if (kt + 1 < nk) G_STORE(cur ^ 1);
;     if (kt + 2 < nk) G_LOAD(kt + 2);
;     const bf16_t* a_s = sbase + cur * G_STAGE + (wr * 64 + l15) * GLD + quad * 8;
;     const bf16_t* b_s = sbase + cur * G_STAGE + 128 * GLD + (wc * 128 + l15) * GLD + quad * 8;
;     __builtin_amdgcn_s_setprio(1);
;     bf16x8 af[4];
; #pragma unroll
;     for (int m = 0; m < 4; ++m) af[m] = *(const bf16x8*)(a_s + m * 16 * GLD);
; #pragma unroll
;     for (int nh = 0; nh < 4; ++nh) {
;       bf16x8 bfr[2];
; #pragma unroll
;       for (int n2 = 0; n2 < 2; ++n2) bfr[n2] = *(const bf16x8*)(b_s + (nh * 2 + n2) * 16 * GLD);
; #pragma unroll
;       for (int m = 0; m < 4; ++m)
; #pragma unroll
;         for (int n2 = 0; n2 < 2; ++n2) acc[m][nh * 2 + n2] = __builtin_amdgcn_mfma_f32_16x16x32_bf16(bfr[n2], af[m], acc[m][nh * 2 + n2], 0, 0, 0);
;     }
;     __builtin_amdgcn_s_setprio(0);
;     __syncthreads();
;   }
.LBB0_647:
	s_and_b32 s3, s51, 1
	s_waitcnt vmcnt(0)
	s_xor_b32 s52, s3, 1
	s_mulk_i32 s52, 0x7800
	v_add_u32_e32 v176, s52, v155
	ds_write_b128 v176, v[0:3]
	ds_write_b128 v176, v[4:7] offset:5120
	ds_write_b128 v176, v[8:11] offset:10240
	ds_write_b128 v176, v[12:15] offset:15360
	ds_write_b128 v176, v[16:19] offset:20480
	ds_write_b128 v176, v[20:23] offset:25600
	global_load_dwordx4 v[0:3], v[162:163], off sc1
	v_lshl_add_u64 v[168:169], v[162:163], 0, s[10:11]
	global_load_dwordx4 v[4:7], v[168:169], off sc1
	global_load_dwordx4 v[8:11], v[160:161], off sc1
	v_lshl_add_u64 v[170:171], v[160:161], 0, s[12:13]
	global_load_dwordx4 v[12:15], v[170:171], off sc1
	v_lshl_add_u64 v[172:173], v[160:161], 0, s[14:15]
	global_load_dwordx4 v[16:19], v[172:173], off sc1
	v_lshl_add_u64 v[174:175], v[160:161], 0, s[16:17]
	global_load_dwordx4 v[20:23], v[174:175], off sc1
	s_add_i32 s51, s51, 1
	s_mulk_i32 s3, 0x7800
	v_add3_u32 v188, s3, v166, v167
	s_setprio 1
	v_add3_u32 v192, s3, v165, v167
	ds_read_b128 v[168:171], v192 offset:10240
	ds_read_b128 v[172:175], v192 offset:11520
	ds_read_b128 v[176:179], v188
	ds_read_b128 v[180:183], v188 offset:1280
	ds_read_b128 v[184:187], v188 offset:2560
	ds_read_b128 v[188:191], v188 offset:3840
	s_waitcnt lgkmcnt(3)
	v_mfma_f32_16x16x32_bf16 v[148:151], v[168:171], v[176:179], v[148:151]
	v_mfma_f32_16x16x32_bf16 v[144:147], v[172:175], v[176:179], v[144:147]
	s_waitcnt lgkmcnt(2)
	v_mfma_f32_16x16x32_bf16 v[132:135], v[168:171], v[180:183], v[132:135]
	v_mfma_f32_16x16x32_bf16 v[128:131], v[172:175], v[180:183], v[128:131]
	s_waitcnt lgkmcnt(1)
	v_mfma_f32_16x16x32_bf16 v[100:103], v[168:171], v[184:187], v[100:103]
	v_mfma_f32_16x16x32_bf16 v[92:95], v[172:175], v[184:187], v[92:95]
	s_waitcnt lgkmcnt(0)
	v_mfma_f32_16x16x32_bf16 v[68:71], v[168:171], v[188:191], v[68:71]
	ds_read_b128 v[168:171], v192 offset:12800
	v_mfma_f32_16x16x32_bf16 v[60:63], v[172:175], v[188:191], v[60:63]
	ds_read_b128 v[172:175], v192 offset:14080
	s_waitcnt lgkmcnt(1)
	v_mfma_f32_16x16x32_bf16 v[140:143], v[168:171], v[176:179], v[140:143]
	s_waitcnt lgkmcnt(0)
	v_mfma_f32_16x16x32_bf16 v[136:139], v[172:175], v[176:179], v[136:139]
	v_mfma_f32_16x16x32_bf16 v[116:119], v[168:171], v[180:183], v[116:119]
	v_mfma_f32_16x16x32_bf16 v[108:111], v[172:175], v[180:183], v[108:111]
	v_mfma_f32_16x16x32_bf16 v[84:87], v[168:171], v[184:187], v[84:87]
	v_mfma_f32_16x16x32_bf16 v[76:79], v[172:175], v[184:187], v[76:79]
	v_mfma_f32_16x16x32_bf16 v[52:55], v[168:171], v[188:191], v[52:55]
	ds_read_b128 v[168:171], v192 offset:15360
	v_mfma_f32_16x16x32_bf16 v[44:47], v[172:175], v[188:191], v[44:47]
	ds_read_b128 v[172:175], v192 offset:16640
	s_waitcnt lgkmcnt(1)
	v_mfma_f32_16x16x32_bf16 v[124:127], v[168:171], v[176:179], v[124:127]
	s_waitcnt lgkmcnt(0)
	v_mfma_f32_16x16x32_bf16 v[120:123], v[172:175], v[176:179], v[120:123]
	v_mfma_f32_16x16x32_bf16 v[96:99], v[168:171], v[180:183], v[96:99]
	v_mfma_f32_16x16x32_bf16 v[88:91], v[172:175], v[180:183], v[88:91]
	v_mfma_f32_16x16x32_bf16 v[64:67], v[168:171], v[184:187], v[64:67]
	v_mfma_f32_16x16x32_bf16 v[56:59], v[172:175], v[184:187], v[56:59]
	v_mfma_f32_16x16x32_bf16 v[36:39], v[168:171], v[188:191], v[36:39]
	ds_read_b128 v[168:171], v192 offset:17920
	v_mfma_f32_16x16x32_bf16 v[32:35], v[172:175], v[188:191], v[32:35]
	ds_read_b128 v[172:175], v192 offset:19200
	s_waitcnt lgkmcnt(1)
	v_mfma_f32_16x16x32_bf16 v[112:115], v[168:171], v[176:179], v[112:115]
	s_waitcnt lgkmcnt(0)
	v_mfma_f32_16x16x32_bf16 v[104:107], v[172:175], v[176:179], v[104:107]
	v_mfma_f32_16x16x32_bf16 v[80:83], v[168:171], v[180:183], v[80:83]
	v_mfma_f32_16x16x32_bf16 v[72:75], v[172:175], v[180:183], v[72:75]
	v_mfma_f32_16x16x32_bf16 v[48:51], v[168:171], v[184:187], v[48:51]
	v_mfma_f32_16x16x32_bf16 v[40:43], v[172:175], v[184:187], v[40:43]
	v_mfma_f32_16x16x32_bf16 v[28:31], v[168:171], v[188:191], v[28:31]
	v_mfma_f32_16x16x32_bf16 v[24:27], v[172:175], v[188:191], v[24:27]
	s_setprio 0
	v_lshl_add_u64 v[160:161], v[160:161], 0, s[20:21]
	s_cmp_eq_u32 s51, 30
	v_lshl_add_u64 v[162:163], v[162:163], 0, 64
	s_barrier
	s_cbranch_scc0 .LBB0_647
	s_waitcnt vmcnt(0)
	ds_write_b128 v155, v[0:3] offset:30720
	ds_write_b128 v155, v[4:7] offset:35840
	ds_write_b128 v155, v[8:11] offset:40960
	ds_write_b128 v155, v[12:15] offset:46080
	ds_write_b128 v155, v[16:19] offset:51200
	ds_write_b128 v155, v[20:23] offset:56320
	v_add_u32_e32 v155, v166, v167
	s_setprio 1
	v_add_u32_e32 v165, v165, v167
	ds_read_b128 v[160:163], v165 offset:10240
	ds_read_b128 v[166:169], v165 offset:11520
	ds_read_b128 v[170:173], v155
	ds_read_b128 v[174:177], v155 offset:1280
	ds_read_b128 v[178:181], v155 offset:2560
	ds_read_b128 v[182:185], v155 offset:3840
	s_waitcnt lgkmcnt(3)
	v_mfma_f32_16x16x32_bf16 v[148:151], v[160:163], v[170:173], v[148:151]
	v_mfma_f32_16x16x32_bf16 v[144:147], v[166:169], v[170:173], v[144:147]
	s_waitcnt lgkmcnt(2)
	v_mfma_f32_16x16x32_bf16 v[132:135], v[160:163], v[174:177], v[132:135]
	v_mfma_f32_16x16x32_bf16 v[128:131], v[166:169], v[174:177], v[128:131]
	s_waitcnt lgkmcnt(1)
	v_mfma_f32_16x16x32_bf16 v[100:103], v[160:163], v[178:181], v[100:103]
	v_mfma_f32_16x16x32_bf16 v[92:95], v[166:169], v[178:181], v[92:95]
	s_waitcnt lgkmcnt(0)
	v_mfma_f32_16x16x32_bf16 v[68:71], v[160:163], v[182:185], v[68:71]
	ds_read_b128 v[160:163], v165 offset:12800
	v_mfma_f32_16x16x32_bf16 v[60:63], v[166:169], v[182:185], v[60:63]
	ds_read_b128 v[166:169], v165 offset:14080
	s_waitcnt lgkmcnt(1)
	v_mfma_f32_16x16x32_bf16 v[186:189], v[160:163], v[170:173], v[140:143]
	s_waitcnt lgkmcnt(0)
; #define G_LOAD(kt_) do { \
;     if constexpr (AF32) { _Pragma("unroll") for (int i = 0; i < 4; ++i) ld16_sc1(ra[i], Af + (size_t)i * 32 * lda + (kt_) * 32); } \
;     else { _Pragma("unroll") for (int i = 0; i < 2; ++i) ld16_sc1(rab[i], Ab + (size_t)i * 64 * lda + (kt_) * 32); } \
;     _Pragma("unroll") for (int i = 0; i < 4; ++i) ld16_sc1(rb[i], Bp + (size_t)(kt_) * bstep + i * 2048); } while (0)
; template <bool AF32, class Epi>
; __device__ __forceinline__ void gemm_tile(unsigned char* smem, const void* Ap, int lda, const bf16_t* WT, int N, int K, const Epi& epi, int m0, int n0,
;                                           GPre& pr, bool preloaded, const void* nAp, int nn0, bool has_next) {
;     ...
;   for (int kt = 0; kt < nk; ++kt) {
;     const int cur = kt & 1;
;     if (kt + 1 < nk) G_STORE(cur ^ 1);
;     if (kt + 2 < nk) G_LOAD(kt + 2);
;     const bf16_t* a_s = sbase + cur * G_STAGE + (wr * 64 + l15) * GLD + quad * 8;
;     const bf16_t* b_s = sbase + cur * G_STAGE + 128 * GLD + (wc * 128 + l15) * GLD + quad * 8;
;     __builtin_amdgcn_s_setprio(1);
;     bf16x8 af[4];
; #pragma unroll
;     for (int m = 0; m < 4; ++m) af[m] = *(const bf16x8*)(a_s + m * 16 * GLD);
; #pragma unroll
;     for (int nh = 0; nh < 4; ++nh) {
;       bf16x8 bfr[2];
; #pragma unroll
;       for (int n2 = 0; n2 < 2; ++n2) bfr[n2] = *(const bf16x8*)(b_s + (nh * 2 + n2) * 16 * GLD);
; #pragma unroll
;       for (int m = 0; m < 4; ++m)
; #pragma unroll
;         for (int n2 = 0; n2 < 2; ++n2) acc[m][nh * 2 + n2] = __builtin_amdgcn_mfma_f32_16x16x32_bf16(bfr[n2], af[m], acc[m][nh * 2 + n2], 0, 0, 0);
;     }
;     __builtin_amdgcn_s_setprio(0);
;     __syncthreads();
;   }
;   if (has_next) {
;     const float* Af = (const float*)nAp + (size_t)(tid >> 3) * lda + (tid & 7) * 4;
;     const bf16_t* Ab = (const bf16_t*)nAp + (size_t)(tid >> 2) * lda + (tid & 3) * 8;
;     const bf16_t* Bp = WT + (size_t)nn0 * 32 + tid * 8;
;     G_LOAD(0);
;   }
	v_mfma_f32_16x16x32_bf16 v[136:139], v[166:169], v[170:173], v[136:139]
	v_mfma_f32_16x16x32_bf16 v[190:193], v[160:163], v[174:177], v[116:119]
	v_mfma_f32_16x16x32_bf16 v[194:197], v[166:169], v[174:177], v[108:111]
	v_mfma_f32_16x16x32_bf16 v[198:201], v[160:163], v[178:181], v[84:87]
	v_mfma_f32_16x16x32_bf16 v[202:205], v[166:169], v[178:181], v[76:79]
	v_mfma_f32_16x16x32_bf16 v[160:163], v[160:163], v[182:185], v[52:55]
	s_nop 2
	ds_read_b128 v[52:55], v165 offset:15360
	v_mfma_f32_16x16x32_bf16 v[166:169], v[166:169], v[182:185], v[44:47]
	s_nop 2
	ds_read_b128 v[44:47], v165 offset:16640
	s_waitcnt lgkmcnt(1)
	v_mfma_f32_16x16x32_bf16 v[124:127], v[52:55], v[170:173], v[124:127]
	s_waitcnt lgkmcnt(0)
	v_mfma_f32_16x16x32_bf16 v[120:123], v[44:47], v[170:173], v[120:123]
	v_mfma_f32_16x16x32_bf16 v[96:99], v[52:55], v[174:177], v[96:99]
	v_mfma_f32_16x16x32_bf16 v[88:91], v[44:47], v[174:177], v[88:91]
	v_mfma_f32_16x16x32_bf16 v[64:67], v[52:55], v[178:181], v[64:67]
	v_mfma_f32_16x16x32_bf16 v[56:59], v[44:47], v[178:181], v[56:59]
	v_mfma_f32_16x16x32_bf16 v[36:39], v[52:55], v[182:185], v[36:39]
	ds_read_b128 v[52:55], v165 offset:17920
	v_mfma_f32_16x16x32_bf16 v[32:35], v[44:47], v[182:185], v[32:35]
	ds_read_b128 v[44:47], v165 offset:19200
	s_waitcnt lgkmcnt(1)
	v_mfma_f32_16x16x32_bf16 v[28:31], v[52:55], v[182:185], v[28:31]
	s_waitcnt lgkmcnt(0)
	v_mfma_f32_16x16x32_bf16 v[24:27], v[44:47], v[182:185], v[24:27]
	v_mfma_f32_16x16x32_bf16 v[206:209], v[52:55], v[170:173], v[112:115]
	v_mfma_f32_16x16x32_bf16 v[170:173], v[44:47], v[170:173], v[104:107]
	v_mfma_f32_16x16x32_bf16 v[212:215], v[52:55], v[174:177], v[80:83]
	v_mfma_f32_16x16x32_bf16 v[174:177], v[44:47], v[174:177], v[72:75]
	v_mfma_f32_16x16x32_bf16 v[216:219], v[52:55], v[178:181], v[48:51]
	v_mfma_f32_16x16x32_bf16 v[178:181], v[44:47], v[178:181], v[40:43]
	s_setprio 0
	s_barrier
	s_setprio 1
	ds_read_b128 v[40:43], v165 offset:40960
	ds_read_b128 v[44:47], v165 offset:42240
	ds_read_b128 v[182:185], v155 offset:30720
	ds_read_b128 v[220:223], v155 offset:32000
	ds_read_b128 v[224:227], v155 offset:33280
	ds_read_b128 v[228:231], v155 offset:34560
	s_waitcnt lgkmcnt(3)
	v_mfma_f32_16x16x32_bf16 v[148:151], v[40:43], v[182:185], v[148:151]
	s_waitcnt lgkmcnt(2)
	v_mfma_f32_16x16x32_bf16 v[116:119], v[40:43], v[220:223], v[132:135]
	s_waitcnt lgkmcnt(1)
	v_mfma_f32_16x16x32_bf16 v[84:87], v[40:43], v[224:227], v[100:103]
	s_waitcnt lgkmcnt(0)
	v_mfma_f32_16x16x32_bf16 v[52:55], v[40:43], v[228:231], v[68:71]
	ds_read_b128 v[40:43], v165 offset:43520
	v_mfma_f32_16x16x32_bf16 v[48:51], v[44:47], v[228:231], v[60:63]
	s_nop 2
	ds_read_b128 v[60:63], v165 offset:44800
	v_mfma_f32_16x16x32_bf16 v[140:143], v[44:47], v[182:185], v[144:147]
	v_mfma_f32_16x16x32_bf16 v[108:111], v[44:47], v[220:223], v[128:131]
	v_mfma_f32_16x16x32_bf16 v[80:83], v[44:47], v[224:227], v[92:95]
	s_waitcnt lgkmcnt(1)
	v_mfma_f32_16x16x32_bf16 v[144:147], v[40:43], v[182:185], v[186:189]
	s_nop 0
	ds_read_b128 v[92:95], v165 offset:46080
	s_waitcnt lgkmcnt(1)
	v_mfma_f32_16x16x32_bf16 v[136:139], v[60:63], v[182:185], v[136:139]
	v_mfma_f32_16x16x32_bf16 v[112:115], v[40:43], v[220:223], v[190:193]
	v_mfma_f32_16x16x32_bf16 v[104:107], v[60:63], v[220:223], v[194:197]
	v_mfma_f32_16x16x32_bf16 v[76:79], v[40:43], v[224:227], v[198:201]
	v_mfma_f32_16x16x32_bf16 v[72:75], v[60:63], v[224:227], v[202:205]
	v_mfma_f32_16x16x32_bf16 v[44:47], v[40:43], v[228:231], v[160:163]
	v_mfma_f32_16x16x32_bf16 v[40:43], v[60:63], v[228:231], v[166:169]
	ds_read_b128 v[60:63], v165 offset:47360
	s_nop 0
	ds_read_b128 v[160:163], v165 offset:48640
	ds_read_b128 v[166:169], v165 offset:49920
	s_waitcnt lgkmcnt(3)
	v_mfma_f32_16x16x32_bf16 v[132:135], v[92:95], v[182:185], v[124:127]
	s_waitcnt lgkmcnt(2)
	v_mfma_f32_16x16x32_bf16 v[128:131], v[60:63], v[182:185], v[120:123]
	v_mfma_f32_16x16x32_bf16 v[100:103], v[92:95], v[220:223], v[96:99]
	v_mfma_f32_16x16x32_bf16 v[96:99], v[60:63], v[220:223], v[88:91]
	v_mfma_f32_16x16x32_bf16 v[68:71], v[92:95], v[224:227], v[64:67]
	v_mfma_f32_16x16x32_bf16 v[64:67], v[60:63], v[224:227], v[56:59]
	v_mfma_f32_16x16x32_bf16 v[36:39], v[92:95], v[228:231], v[36:39]
	v_mfma_f32_16x16x32_bf16 v[32:35], v[60:63], v[228:231], v[32:35]
	s_waitcnt lgkmcnt(1)
	v_mfma_f32_16x16x32_bf16 v[124:127], v[160:163], v[182:185], v[206:209]
	s_waitcnt lgkmcnt(0)
	v_mfma_f32_16x16x32_bf16 v[120:123], v[166:169], v[182:185], v[170:173]
	v_mfma_f32_16x16x32_bf16 v[92:95], v[160:163], v[220:223], v[212:215]
	v_mfma_f32_16x16x32_bf16 v[88:91], v[166:169], v[220:223], v[174:177]
	v_mfma_f32_16x16x32_bf16 v[60:63], v[160:163], v[224:227], v[216:219]
	v_mfma_f32_16x16x32_bf16 v[56:59], v[166:169], v[224:227], v[178:181]
	v_mfma_f32_16x16x32_bf16 v[28:31], v[160:163], v[228:231], v[28:31]
	v_mfma_f32_16x16x32_bf16 v[24:27], v[166:169], v[228:231], v[24:27]
	s_and_b64 vcc, exec, s[46:47]
	s_barrier
	s_cbranch_vccz .LBB0_635
	s_ashr_i32 s51, s50, 31
	s_lshl_b64 s[46:47], s[50:51], 18
	s_add_u32 s46, s2, s46
	s_addc_u32 s47, s33, s47
	s_lshl_b32 s50, s66, 8
	s_ashr_i32 s51, s50, 31
	v_lshl_add_u64 v[0:1], v[158:159], 1, s[46:47]
	s_lshl_b64 s[46:47], s[50:51], 6
	v_lshl_add_u64 v[4:5], v[0:1], 0, v[152:153]
	s_add_u32 s46, s56, s46
	s_addc_u32 s47, s57, s47
	global_load_dwordx4 v[0:3], v[4:5], off sc1
	v_lshl_add_u64 v[4:5], v[4:5], 0, s[10:11]
	global_load_dwordx4 v[4:7], v[4:5], off sc1
	v_lshl_add_u64 v[20:21], v[156:157], 1, s[46:47]
	global_load_dwordx4 v[8:11], v[20:21], off sc1
	v_lshl_add_u64 v[12:13], v[20:21], 0, s[12:13]
	global_load_dwordx4 v[12:15], v[12:13], off sc1
	v_lshl_add_u64 v[16:17], v[20:21], 0, s[14:15]
	global_load_dwordx4 v[16:19], v[16:17], off sc1
	v_lshl_add_u64 v[20:21], v[20:21], 0, s[16:17]
	global_load_dwordx4 v[20:23], v[20:21], off sc1
	s_branch .LBB0_635

; #define G_LOAD(kt_) do { \
;     if constexpr (AF32) { _Pragma("unroll") for (int i = 0; i < 4; ++i) ld16_sc1(ra[i], Af + (size_t)i * 32 * lda + (kt_) * 32); } \
;     else { _Pragma("unroll") for (int i = 0; i < 2; ++i) ld16_sc1(rab[i], Ab + (size_t)i * 64 * lda + (kt_) * 32); } \
;     _Pragma("unroll") for (int i = 0; i < 4; ++i) ld16_sc1(rb[i], Bp + (size_t)(kt_) * bstep + i * 2048); } while (0)
; template <bool AF32, class Epi>
; __device__ __forceinline__ void gemm_tile(unsigned char* smem, const void* Ap, int lda, const bf16_t* WT, int N, int K, const Epi& epi, int m0, int n0,
;                                           GPre& pr, bool preloaded, const void* nAp, int nn0, bool has_next) {
;     ...
;   if (!preloaded) G_LOAD(0);
;   G_STORE(0);
;   if (nk > 1) G_LOAD(1);
;   __syncthreads();
;   for (int kt = 0; kt < nk; ++kt) {
;     const int cur = kt & 1;
;     if (kt + 1 < nk) G_STORE(cur ^ 1);
;     if (kt + 2 < nk) G_LOAD(kt + 2);
;     const bf16_t* a_s = sbase + cur * G_STAGE + (wr * 64 + l15) * GLD + quad * 8;
;     const bf16_t* b_s = sbase + cur * G_STAGE + 128 * GLD + (wc * 128 + l15) * GLD + quad * 8;
;     __builtin_amdgcn_s_setprio(1);
;     bf16x8 af[4];
; #pragma unroll
;     for (int m = 0; m < 4; ++m) af[m] = *(const bf16x8*)(a_s + m * 16 * GLD);
; #pragma unroll
;     for (int nh = 0; nh < 4; ++nh) {
;       bf16x8 bfr[2];
; #pragma unroll
;       for (int n2 = 0; n2 < 2; ++n2) bfr[n2] = *(const bf16x8*)(b_s + (nh * 2 + n2) * 16 * GLD);
; #pragma unroll
;       for (int m = 0; m < 4; ++m)
; #pragma unroll
;         for (int n2 = 0; n2 < 2; ++n2) acc[m][nh * 2 + n2] = __builtin_amdgcn_mfma_f32_16x16x32_bf16(bfr[n2], af[m], acc[m][nh * 2 + n2], 0, 0, 0);
;     }
;     __builtin_amdgcn_s_setprio(0);
;     __syncthreads();
;   }
.LBB0_678:
	s_and_b32 s3, s49, 1
	s_waitcnt vmcnt(0)
	s_xor_b32 s50, s3, 1
	s_mulk_i32 s50, 0x7800
	v_cvt_pk_bf16_f32 v202, v44, v45
	v_mov_b32_e32 v205, v44
	v_mov_b32_e32 v44, v41
	v_lshl_add_u32 v171, v160, 1, s50
	v_cvt_pk_bf16_f32 v203, v46, v47
	v_mov_b32_e32 v204, v40
	v_mov_b32_e32 v206, v42
	v_mov_b32_e32 v207, v46
	v_mov_b32_e32 v46, v43
	v_cvt_pk_bf16_f32 v40, v40, v41
	v_cvt_pk_bf16_f32 v41, v42, v43
	v_cvt_pk_bf16_f32 v42, v36, v37
	v_cvt_pk_bf16_f32 v43, v38, v39
	v_mov_b32_e32 v208, v32
	v_mov_b32_e32 v209, v36
	v_mov_b32_e32 v36, v33
	v_mov_b32_e32 v212, v34
	v_mov_b32_e32 v213, v38
	v_mov_b32_e32 v38, v35
	v_cvt_pk_bf16_f32 v32, v32, v33
	v_cvt_pk_bf16_f32 v33, v34, v35
	v_pk_mul_f32 v[34:35], v[44:45], v[44:45]
	v_lshl_add_u32 v176, v162, 1, s50
	ds_write2st64_b64 v171, v[202:203], v[40:41] offset1:5
	ds_write2st64_b64 v171, v[42:43], v[32:33] offset0:10 offset1:15
	ds_write_b128 v176, v[0:3] offset:10240
	ds_write_b128 v176, v[4:7] offset:15360
	ds_write_b128 v176, v[8:11] offset:20480
	ds_write_b128 v176, v[12:15] offset:25600
	v_pk_fma_f32 v[0:1], v[204:205], v[204:205], v[34:35]
	v_pk_mul_f32 v[36:37], v[36:37], v[36:37]
	v_pk_fma_f32 v[0:1], v[206:207], v[206:207], v[0:1]
	v_pk_fma_f32 v[2:3], v[208:209], v[208:209], v[36:37]
	v_pk_fma_f32 v[202:203], v[46:47], v[46:47], v[0:1]
	global_load_dwordx4 v[44:47], v[166:167], off sc1
	v_lshl_add_u64 v[172:173], v[166:167], 0, s[14:15]
	v_pk_fma_f32 v[2:3], v[212:213], v[212:213], v[2:3]
	global_load_dwordx4 v[40:43], v[172:173], off sc1
	v_lshl_add_u64 v[174:175], v[166:167], 0, s[16:17]
	v_pk_fma_f32 v[204:205], v[38:39], v[38:39], v[2:3]
	global_load_dwordx4 v[36:39], v[174:175], off sc1
	v_lshl_add_u64 v[194:195], v[166:167], 0, s[18:19]
	global_load_dwordx4 v[32:35], v[194:195], off sc1
	global_load_dwordx4 v[0:3], v[164:165], off sc1
	v_lshl_add_u64 v[196:197], v[164:165], 0, s[20:21]
	global_load_dwordx4 v[4:7], v[196:197], off sc1
	v_lshl_add_u64 v[198:199], v[164:165], 0, s[22:23]
	global_load_dwordx4 v[8:11], v[198:199], off sc1
	v_lshl_add_u64 v[200:201], v[164:165], 0, s[24:25]
	global_load_dwordx4 v[12:15], v[200:201], off sc1
	s_add_i32 s49, s49, 1
	s_mulk_i32 s3, 0x7800
	v_pk_add_f32 v[184:185], v[184:185], v[202:203]
	v_pk_add_f32 v[180:181], v[180:181], v[204:205]
	v_add3_u32 v171, s3, v169, v170
	s_setprio 1
	v_add3_u32 v176, s3, v168, v170
	ds_read_b128 v[172:175], v176 offset:10240
	ds_read_b128 v[194:197], v176 offset:11520
	ds_read_b128 v[198:201], v171
	ds_read_b128 v[202:205], v171 offset:1280
	ds_read_b128 v[206:209], v171 offset:2560
	ds_read_b128 v[212:215], v171 offset:3840
	s_waitcnt lgkmcnt(3)
	v_mfma_f32_16x16x32_bf16 v[156:159], v[172:175], v[198:201], v[156:159]
	v_mfma_f32_16x16x32_bf16 v[152:155], v[194:197], v[198:201], v[152:155]
	s_waitcnt lgkmcnt(2)
	v_mfma_f32_16x16x32_bf16 v[140:143], v[172:175], v[202:205], v[140:143]
	v_mfma_f32_16x16x32_bf16 v[136:139], v[194:197], v[202:205], v[136:139]
	s_waitcnt lgkmcnt(1)
	v_mfma_f32_16x16x32_bf16 v[108:111], v[172:175], v[206:209], v[108:111]
	v_mfma_f32_16x16x32_bf16 v[100:103], v[194:197], v[206:209], v[100:103]
	s_waitcnt lgkmcnt(0)
	v_mfma_f32_16x16x32_bf16 v[76:79], v[172:175], v[212:215], v[76:79]
	ds_read_b128 v[172:175], v176 offset:12800
	v_mfma_f32_16x16x32_bf16 v[68:71], v[194:197], v[212:215], v[68:71]
	ds_read_b128 v[194:197], v176 offset:14080
	s_waitcnt lgkmcnt(1)
	v_mfma_f32_16x16x32_bf16 v[148:151], v[172:175], v[198:201], v[148:151]
	s_waitcnt lgkmcnt(0)
	v_mfma_f32_16x16x32_bf16 v[144:147], v[194:197], v[198:201], v[144:147]
	v_mfma_f32_16x16x32_bf16 v[124:127], v[172:175], v[202:205], v[124:127]
	v_mfma_f32_16x16x32_bf16 v[116:119], v[194:197], v[202:205], v[116:119]
	v_mfma_f32_16x16x32_bf16 v[92:95], v[172:175], v[206:209], v[92:95]
	v_mfma_f32_16x16x32_bf16 v[84:87], v[194:197], v[206:209], v[84:87]
	v_mfma_f32_16x16x32_bf16 v[60:63], v[172:175], v[212:215], v[60:63]
	ds_read_b128 v[172:175], v176 offset:15360
	v_mfma_f32_16x16x32_bf16 v[52:55], v[194:197], v[212:215], v[52:55]
	ds_read_b128 v[194:197], v176 offset:16640
	s_waitcnt lgkmcnt(1)
	v_mfma_f32_16x16x32_bf16 v[132:135], v[172:175], v[198:201], v[132:135]
	s_waitcnt lgkmcnt(0)
	v_mfma_f32_16x16x32_bf16 v[128:131], v[194:197], v[198:201], v[128:131]
	v_mfma_f32_16x16x32_bf16 v[104:107], v[172:175], v[202:205], v[104:107]
	v_mfma_f32_16x16x32_bf16 v[96:99], v[194:197], v[202:205], v[96:99]
	v_mfma_f32_16x16x32_bf16 v[72:75], v[172:175], v[206:209], v[72:75]
	v_mfma_f32_16x16x32_bf16 v[64:67], v[194:197], v[206:209], v[64:67]
	v_mfma_f32_16x16x32_bf16 v[28:31], v[172:175], v[212:215], v[28:31]
	ds_read_b128 v[172:175], v176 offset:17920
	v_mfma_f32_16x16x32_bf16 v[24:27], v[194:197], v[212:215], v[24:27]
	ds_read_b128 v[194:197], v176 offset:19200
	s_waitcnt lgkmcnt(1)
	v_mfma_f32_16x16x32_bf16 v[120:123], v[172:175], v[198:201], v[120:123]
	s_waitcnt lgkmcnt(0)
	v_mfma_f32_16x16x32_bf16 v[112:115], v[194:197], v[198:201], v[112:115]
	v_mfma_f32_16x16x32_bf16 v[88:91], v[172:175], v[202:205], v[88:91]
	v_mfma_f32_16x16x32_bf16 v[80:83], v[194:197], v[202:205], v[80:83]
	v_mfma_f32_16x16x32_bf16 v[56:59], v[172:175], v[206:209], v[56:59]
	v_mfma_f32_16x16x32_bf16 v[48:51], v[194:197], v[206:209], v[48:51]
	v_mfma_f32_16x16x32_bf16 v[20:23], v[172:175], v[212:215], v[20:23]
	v_mfma_f32_16x16x32_bf16 v[16:19], v[194:197], v[212:215], v[16:19]
	s_setprio 0
	v_lshl_add_u64 v[164:165], v[164:165], 0, s[36:37]
	s_cmp_eq_u32 s49, 30
	v_lshl_add_u64 v[166:167], v[166:167], 0, s[26:27]
	s_barrier
	s_cbranch_scc0 .LBB0_678
; #define G_LOAD(kt_) do { \
;     if constexpr (AF32) { _Pragma("unroll") for (int i = 0; i < 4; ++i) ld16_sc1(ra[i], Af + (size_t)i * 32 * lda + (kt_) * 32); } \
;     else { _Pragma("unroll") for (int i = 0; i < 2; ++i) ld16_sc1(rab[i], Ab + (size_t)i * 64 * lda + (kt_) * 32); } \
;     _Pragma("unroll") for (int i = 0; i < 4; ++i) ld16_sc1(rb[i], Bp + (size_t)(kt_) * bstep + i * 2048); } while (0)
; template <bool AF32, class Epi>
; __device__ __forceinline__ void gemm_tile(unsigned char* smem, const void* Ap, int lda, const bf16_t* WT, int N, int K, const Epi& epi, int m0, int n0,
;                                           GPre& pr, bool preloaded, const void* nAp, int nn0, bool has_next) {
;     ...
;     if (kt + 1 < nk) G_STORE(cur ^ 1);
;     if (kt + 2 < nk) G_LOAD(kt + 2);
;     const bf16_t* a_s = sbase + cur * G_STAGE + (wr * 64 + l15) * GLD + quad * 8;
;     const bf16_t* b_s = sbase + cur * G_STAGE + 128 * GLD + (wc * 128 + l15) * GLD + quad * 8;
;     __builtin_amdgcn_s_setprio(1);
;     bf16x8 af[4];
; #pragma unroll
;     for (int m = 0; m < 4; ++m) af[m] = *(const bf16x8*)(a_s + m * 16 * GLD);
; #pragma unroll
;     for (int nh = 0; nh < 4; ++nh) {
;       bf16x8 bfr[2];
; #pragma unroll
;       for (int n2 = 0; n2 < 2; ++n2) bfr[n2] = *(const bf16x8*)(b_s + (nh * 2 + n2) * 16 * GLD);
; #pragma unroll
;       for (int m = 0; m < 4; ++m)
; #pragma unroll
;         for (int n2 = 0; n2 < 2; ++n2) acc[m][nh * 2 + n2] = __builtin_amdgcn_mfma_f32_16x16x32_bf16(bfr[n2], af[m], acc[m][nh * 2 + n2], 0, 0, 0);
	s_waitcnt vmcnt(0)
	v_add_u32_e32 v176, v169, v170
	v_cvt_pk_bf16_f32 v164, v44, v45
	v_cvt_pk_bf16_f32 v165, v46, v47
	v_cvt_pk_bf16_f32 v166, v40, v41
	v_cvt_pk_bf16_f32 v167, v42, v43
	ds_write2st64_b64 v161, v[164:165], v[166:167] offset0:60 offset1:65
	v_cvt_pk_bf16_f32 v164, v36, v37
	v_cvt_pk_bf16_f32 v165, v38, v39
	v_cvt_pk_bf16_f32 v166, v32, v33
	v_cvt_pk_bf16_f32 v167, v34, v35
	ds_write2st64_b64 v161, v[164:165], v[166:167] offset0:70 offset1:75
	ds_write_b128 v163, v[0:3] offset:40960
	ds_write_b128 v163, v[4:7] offset:46080
	ds_write_b128 v163, v[8:11] offset:51200
	ds_write_b128 v163, v[12:15] offset:56320
	s_setprio 1
	v_add_u32_e32 v193, v168, v170
	ds_read_b128 v[160:163], v193 offset:10240
	ds_read_b128 v[164:167], v193 offset:11520
	ds_read_b128 v[168:171], v176
	ds_read_b128 v[172:175], v176 offset:1280
	ds_read_b128 v[194:197], v176 offset:2560
	ds_read_b128 v[198:201], v176 offset:3840
	s_waitcnt lgkmcnt(3)
	v_mfma_f32_16x16x32_bf16 v[156:159], v[160:163], v[168:171], v[156:159]
	v_mfma_f32_16x16x32_bf16 v[152:155], v[164:167], v[168:171], v[152:155]
	s_waitcnt lgkmcnt(2)
	v_mfma_f32_16x16x32_bf16 v[140:143], v[160:163], v[172:175], v[140:143]
	v_mfma_f32_16x16x32_bf16 v[136:139], v[164:167], v[172:175], v[136:139]
	s_waitcnt lgkmcnt(1)
	v_mfma_f32_16x16x32_bf16 v[108:111], v[160:163], v[194:197], v[108:111]
	v_mfma_f32_16x16x32_bf16 v[100:103], v[164:167], v[194:197], v[100:103]
	s_waitcnt lgkmcnt(0)
	v_mfma_f32_16x16x32_bf16 v[76:79], v[160:163], v[198:201], v[76:79]
	ds_read_b128 v[160:163], v193 offset:12800
	v_mfma_f32_16x16x32_bf16 v[68:71], v[164:167], v[198:201], v[68:71]
	ds_read_b128 v[164:167], v193 offset:14080
	s_waitcnt lgkmcnt(1)
	v_mfma_f32_16x16x32_bf16 v[148:151], v[160:163], v[168:171], v[148:151]
	s_waitcnt lgkmcnt(0)
	v_mfma_f32_16x16x32_bf16 v[144:147], v[164:167], v[168:171], v[144:147]
	v_mfma_f32_16x16x32_bf16 v[124:127], v[160:163], v[172:175], v[124:127]
	v_mfma_f32_16x16x32_bf16 v[116:119], v[164:167], v[172:175], v[116:119]
	v_mfma_f32_16x16x32_bf16 v[92:95], v[160:163], v[194:197], v[92:95]
	v_mfma_f32_16x16x32_bf16 v[84:87], v[164:167], v[194:197], v[84:87]
	v_mfma_f32_16x16x32_bf16 v[60:63], v[160:163], v[198:201], v[60:63]
	ds_read_b128 v[160:163], v193 offset:15360
	v_mfma_f32_16x16x32_bf16 v[52:55], v[164:167], v[198:201], v[52:55]
	ds_read_b128 v[164:167], v193 offset:16640
	s_waitcnt lgkmcnt(1)
	v_mfma_f32_16x16x32_bf16 v[220:223], v[160:163], v[194:197], v[72:75]
	s_nop 2
	ds_read_b128 v[72:75], v193 offset:19200
	s_waitcnt lgkmcnt(1)
	v_mfma_f32_16x16x32_bf16 v[224:227], v[164:167], v[194:197], v[64:67]
	s_nop 2
	ds_read_b128 v[64:67], v193 offset:17920
	s_waitcnt lgkmcnt(1)
	v_mfma_f32_16x16x32_bf16 v[112:115], v[72:75], v[168:171], v[112:115]
	v_mfma_f32_16x16x32_bf16 v[80:83], v[72:75], v[172:175], v[80:83]
	v_mfma_f32_16x16x32_bf16 v[48:51], v[72:75], v[194:197], v[48:51]
	v_mfma_f32_16x16x32_bf16 v[202:205], v[160:163], v[168:171], v[132:135]
	v_mfma_f32_16x16x32_bf16 v[206:209], v[164:167], v[168:171], v[128:131]
	v_mfma_f32_16x16x32_bf16 v[212:215], v[160:163], v[172:175], v[104:107]
	v_mfma_f32_16x16x32_bf16 v[216:219], v[164:167], v[172:175], v[96:99]
	v_mfma_f32_16x16x32_bf16 v[28:31], v[160:163], v[198:201], v[28:31]
	v_mfma_f32_16x16x32_bf16 v[24:27], v[164:167], v[198:201], v[24:27]
	s_waitcnt lgkmcnt(0)
	v_mfma_f32_16x16x32_bf16 v[228:231], v[64:67], v[168:171], v[120:123]
	v_mfma_f32_16x16x32_bf16 v[232:235], v[64:67], v[172:175], v[88:91]
	v_mfma_f32_16x16x32_bf16 v[236:239], v[64:67], v[194:197], v[56:59]
	v_mfma_f32_16x16x32_bf16 v[20:23], v[64:67], v[198:201], v[20:23]
	v_mfma_f32_16x16x32_bf16 v[16:19], v[72:75], v[198:201], v[16:19]
	s_setprio 0
	s_barrier
; #define G_LOAD(kt_) do { \
;     if constexpr (AF32) { _Pragma("unroll") for (int i = 0; i < 4; ++i) ld16_sc1(ra[i], Af + (size_t)i * 32 * lda + (kt_) * 32); } \
;     else { _Pragma("unroll") for (int i = 0; i < 2; ++i) ld16_sc1(rab[i], Ab + (size_t)i * 64 * lda + (kt_) * 32); } \
;     _Pragma("unroll") for (int i = 0; i < 4; ++i) ld16_sc1(rb[i], Bp + (size_t)(kt_) * bstep + i * 2048); } while (0)
; template <bool AF32, class Epi>
; __device__ __forceinline__ void gemm_tile(unsigned char* smem, const void* Ap, int lda, const bf16_t* WT, int N, int K, const Epi& epi, int m0, int n0,
;                                           GPre& pr, bool preloaded, const void* nAp, int nn0, bool has_next) {
;     ...
;   for (int kt = 0; kt < nk; ++kt) {
;     const int cur = kt & 1;
;     if (kt + 1 < nk) G_STORE(cur ^ 1);
;     if (kt + 2 < nk) G_LOAD(kt + 2);
;     const bf16_t* a_s = sbase + cur * G_STAGE + (wr * 64 + l15) * GLD + quad * 8;
;     const bf16_t* b_s = sbase + cur * G_STAGE + 128 * GLD + (wc * 128 + l15) * GLD + quad * 8;
;     __builtin_amdgcn_s_setprio(1);
;     bf16x8 af[4];
; #pragma unroll
;     for (int m = 0; m < 4; ++m) af[m] = *(const bf16x8*)(a_s + m * 16 * GLD);
; #pragma unroll
;     for (int nh = 0; nh < 4; ++nh) {
;       bf16x8 bfr[2];
; #pragma unroll
;       for (int n2 = 0; n2 < 2; ++n2) bfr[n2] = *(const bf16x8*)(b_s + (nh * 2 + n2) * 16 * GLD);
; #pragma unroll
;       for (int m = 0; m < 4; ++m)
; #pragma unroll
;         for (int n2 = 0; n2 < 2; ++n2) acc[m][nh * 2 + n2] = __builtin_amdgcn_mfma_f32_16x16x32_bf16(bfr[n2], af[m], acc[m][nh * 2 + n2], 0, 0, 0);
;     }
;     __builtin_amdgcn_s_setprio(0);
;     __syncthreads();
;   }
;   if (has_next) {
;     const float* Af = (const float*)nAp + (size_t)(tid >> 3) * lda + (tid & 7) * 4;
;     const bf16_t* Ab = (const bf16_t*)nAp + (size_t)(tid >> 2) * lda + (tid & 3) * 8;
;     const bf16_t* Bp = WT + (size_t)nn0 * 32 + tid * 8;
;     G_LOAD(0);
;   }
	s_setprio 1
	ds_read_b128 v[56:59], v193 offset:40960
	ds_read_b128 v[64:67], v193 offset:42240
	ds_read_b128 v[194:197], v176 offset:30720
	ds_read_b128 v[198:201], v176 offset:32000
	ds_read_b128 v[240:243], v176 offset:33280
	ds_read_b128 v[244:247], v176 offset:34560
	s_waitcnt lgkmcnt(3)
	v_mfma_f32_16x16x32_bf16 v[172:175], v[56:59], v[194:197], v[156:159]
	v_mfma_f32_16x16x32_bf16 v[168:171], v[64:67], v[194:197], v[152:155]
	s_waitcnt lgkmcnt(2)
	v_mfma_f32_16x16x32_bf16 v[140:143], v[56:59], v[198:201], v[140:143]
	v_mfma_f32_16x16x32_bf16 v[136:139], v[64:67], v[198:201], v[136:139]
	s_waitcnt lgkmcnt(1)
	v_mfma_f32_16x16x32_bf16 v[108:111], v[56:59], v[240:243], v[108:111]
	v_mfma_f32_16x16x32_bf16 v[104:107], v[64:67], v[240:243], v[100:103]
	s_waitcnt lgkmcnt(0)
	v_mfma_f32_16x16x32_bf16 v[76:79], v[56:59], v[244:247], v[76:79]
	ds_read_b128 v[56:59], v193 offset:43520
	v_mfma_f32_16x16x32_bf16 v[72:75], v[64:67], v[244:247], v[68:71]
	ds_read_b128 v[64:67], v193 offset:44800
	s_waitcnt lgkmcnt(1)
	v_mfma_f32_16x16x32_bf16 v[164:167], v[56:59], v[194:197], v[148:151]
	s_waitcnt lgkmcnt(0)
	v_mfma_f32_16x16x32_bf16 v[160:163], v[64:67], v[194:197], v[144:147]
	v_mfma_f32_16x16x32_bf16 v[132:135], v[56:59], v[198:201], v[124:127]
	v_mfma_f32_16x16x32_bf16 v[128:131], v[64:67], v[198:201], v[116:119]
	v_mfma_f32_16x16x32_bf16 v[100:103], v[56:59], v[240:243], v[92:95]
	v_mfma_f32_16x16x32_bf16 v[96:99], v[64:67], v[240:243], v[84:87]
	v_mfma_f32_16x16x32_bf16 v[68:71], v[56:59], v[244:247], v[60:63]
	ds_read_b128 v[56:59], v193 offset:46080
	v_mfma_f32_16x16x32_bf16 v[64:67], v[64:67], v[244:247], v[52:55]
	s_nop 2
	ds_read_b128 v[52:55], v193 offset:47360
	s_waitcnt lgkmcnt(1)
	v_mfma_f32_16x16x32_bf16 v[156:159], v[56:59], v[194:197], v[202:205]
	v_mfma_f32_16x16x32_bf16 v[124:127], v[56:59], v[198:201], v[212:215]
	v_mfma_f32_16x16x32_bf16 v[92:95], v[56:59], v[240:243], v[220:223]
	v_mfma_f32_16x16x32_bf16 v[60:63], v[56:59], v[244:247], v[28:31]
	s_nop 2
	ds_read_b128 v[28:31], v193 offset:48640
	s_waitcnt lgkmcnt(1)
	v_mfma_f32_16x16x32_bf16 v[56:59], v[52:55], v[244:247], v[24:27]
	s_nop 2
	ds_read_b128 v[24:27], v193 offset:49920
	v_mfma_f32_16x16x32_bf16 v[152:155], v[52:55], v[194:197], v[206:209]
	v_mfma_f32_16x16x32_bf16 v[120:123], v[52:55], v[198:201], v[216:219]
	v_mfma_f32_16x16x32_bf16 v[88:91], v[52:55], v[240:243], v[224:227]
	s_waitcnt lgkmcnt(1)
	v_mfma_f32_16x16x32_bf16 v[148:151], v[28:31], v[194:197], v[228:231]
	s_waitcnt lgkmcnt(0)
	v_mfma_f32_16x16x32_bf16 v[144:147], v[24:27], v[194:197], v[112:115]
	v_mfma_f32_16x16x32_bf16 v[116:119], v[28:31], v[198:201], v[232:235]
	v_mfma_f32_16x16x32_bf16 v[112:115], v[24:27], v[198:201], v[80:83]
	v_mfma_f32_16x16x32_bf16 v[84:87], v[28:31], v[240:243], v[236:239]
	v_mfma_f32_16x16x32_bf16 v[80:83], v[24:27], v[240:243], v[48:51]
	v_mfma_f32_16x16x32_bf16 v[52:55], v[28:31], v[244:247], v[20:23]
	v_mfma_f32_16x16x32_bf16 v[48:51], v[24:27], v[244:247], v[16:19]
	s_and_b64 vcc, exec, s[6:7]
	s_barrier
	s_cbranch_vccz .LBB0_681
	s_ashr_i32 s49, s48, 31
	s_lshl_b64 s[6:7], s[48:49], 19
	s_add_u32 s6, s10, s6
	s_addc_u32 s7, s11, s7
	s_lshl_b32 s48, s65, 8
	v_lshl_add_u64 v[0:1], v[186:187], 2, s[6:7]
	v_lshlrev_b32_e32 v176, 2, v188
	s_ashr_i32 s49, s48, 31
	v_lshl_add_u64 v[0:1], v[0:1], 0, v[176:177]
	s_lshl_b64 s[6:7], s[48:49], 6
	global_load_dwordx4 v[24:27], v[0:1], off sc1
	s_add_u32 s6, s2, s6
	v_lshl_add_u64 v[2:3], v[0:1], 0, s[14:15]
	global_load_dwordx4 v[28:31], v[2:3], off sc1
	s_addc_u32 s7, s33, s7
	v_lshl_add_u64 v[2:3], v[0:1], 0, s[16:17]
	global_load_dwordx4 v[16:19], v[2:3], off sc1
	v_lshl_add_u64 v[0:1], v[0:1], 0, s[18:19]
	global_load_dwordx4 v[20:23], v[0:1], off sc1
	v_lshl_add_u64 v[12:13], v[182:183], 1, s[6:7]
	global_load_dwordx4 v[0:3], v[12:13], off sc1
	v_lshl_add_u64 v[4:5], v[12:13], 0, s[20:21]
	global_load_dwordx4 v[4:7], v[4:5], off sc1
	v_lshl_add_u64 v[8:9], v[12:13], 0, s[22:23]
	global_load_dwordx4 v[8:11], v[8:9], off sc1
	v_lshl_add_u64 v[12:13], v[12:13], 0, s[24:25]
	global_load_dwordx4 v[12:15], v[12:13], off sc1
	s_branch .LBB0_682

; #define G_LOAD(kt_) do { \
;     if constexpr (AF32) { _Pragma("unroll") for (int i = 0; i < 4; ++i) ld16_sc1(ra[i], Af + (size_t)i * 32 * lda + (kt_) * 32); } \
;     else { _Pragma("unroll") for (int i = 0; i < 2; ++i) ld16_sc1(rab[i], Ab + (size_t)i * 64 * lda + (kt_) * 32); } \
;     _Pragma("unroll") for (int i = 0; i < 4; ++i) ld16_sc1(rb[i], Bp + (size_t)(kt_) * bstep + i * 2048); } while (0)
; template <bool AF32, class Epi>
; __device__ __forceinline__ void gemm_tile(unsigned char* smem, const void* Ap, int lda, const bf16_t* WT, int N, int K, const Epi& epi, int m0, int n0,
;                                           GPre& pr, bool preloaded, const void* nAp, int nn0, bool has_next) {
;     ...
;   if (!preloaded) G_LOAD(0);
;   G_STORE(0);
;   if (nk > 1) G_LOAD(1);
;   __syncthreads();
;   for (int kt = 0; kt < nk; ++kt) {
;     const int cur = kt & 1;
;     if (kt + 1 < nk) G_STORE(cur ^ 1);
;     if (kt + 2 < nk) G_LOAD(kt + 2);
;     const bf16_t* a_s = sbase + cur * G_STAGE + (wr * 64 + l15) * GLD + quad * 8;
;     const bf16_t* b_s = sbase + cur * G_STAGE + 128 * GLD + (wc * 128 + l15) * GLD + quad * 8;
;     __builtin_amdgcn_s_setprio(1);
;     bf16x8 af[4];
; #pragma unroll
;     for (int m = 0; m < 4; ++m) af[m] = *(const bf16x8*)(a_s + m * 16 * GLD);
; #pragma unroll
;     for (int nh = 0; nh < 4; ++nh) {
;       bf16x8 bfr[2];
; #pragma unroll
;       for (int n2 = 0; n2 < 2; ++n2) bfr[n2] = *(const bf16x8*)(b_s + (nh * 2 + n2) * 16 * GLD);
; #pragma unroll
;       for (int m = 0; m < 4; ++m)
; #pragma unroll
;         for (int n2 = 0; n2 < 2; ++n2) acc[m][nh * 2 + n2] = __builtin_amdgcn_mfma_f32_16x16x32_bf16(bfr[n2], af[m], acc[m][nh * 2 + n2], 0, 0, 0);
;     }
;     __builtin_amdgcn_s_setprio(0);
;     __syncthreads();
;   }
.LBB0_718:
	s_and_b32 s3, s50, 1
	s_waitcnt vmcnt(0)
	s_xor_b32 s51, s3, 1
	s_mulk_i32 s51, 0x7800
	v_add_u32_e32 v176, s51, v155
	ds_write_b128 v176, v[0:3]
	ds_write_b128 v176, v[4:7] offset:5120
	ds_write_b128 v176, v[8:11] offset:10240
	ds_write_b128 v176, v[12:15] offset:15360
	ds_write_b128 v176, v[16:19] offset:20480
	ds_write_b128 v176, v[20:23] offset:25600
	global_load_dwordx4 v[0:3], v[162:163], off sc1
	v_lshl_add_u64 v[168:169], v[162:163], 0, s[10:11]
	global_load_dwordx4 v[4:7], v[168:169], off sc1
	global_load_dwordx4 v[8:11], v[160:161], off sc1
	v_lshl_add_u64 v[170:171], v[160:161], 0, s[12:13]
	global_load_dwordx4 v[12:15], v[170:171], off sc1
	v_lshl_add_u64 v[172:173], v[160:161], 0, s[14:15]
	global_load_dwordx4 v[16:19], v[172:173], off sc1
	v_lshl_add_u64 v[174:175], v[160:161], 0, s[16:17]
	global_load_dwordx4 v[20:23], v[174:175], off sc1
	s_add_i32 s50, s50, 1
	s_mulk_i32 s3, 0x7800
	v_add3_u32 v188, s3, v166, v167
	s_setprio 1
	v_add3_u32 v192, s3, v165, v167
	ds_read_b128 v[168:171], v192 offset:10240
	ds_read_b128 v[172:175], v192 offset:11520
	ds_read_b128 v[176:179], v188
	ds_read_b128 v[180:183], v188 offset:1280
	ds_read_b128 v[184:187], v188 offset:2560
	ds_read_b128 v[188:191], v188 offset:3840
	s_waitcnt lgkmcnt(3)
	v_mfma_f32_16x16x32_bf16 v[148:151], v[168:171], v[176:179], v[148:151]
	v_mfma_f32_16x16x32_bf16 v[144:147], v[172:175], v[176:179], v[144:147]
	s_waitcnt lgkmcnt(2)
	v_mfma_f32_16x16x32_bf16 v[132:135], v[168:171], v[180:183], v[132:135]
	v_mfma_f32_16x16x32_bf16 v[128:131], v[172:175], v[180:183], v[128:131]
	s_waitcnt lgkmcnt(1)
	v_mfma_f32_16x16x32_bf16 v[100:103], v[168:171], v[184:187], v[100:103]
	v_mfma_f32_16x16x32_bf16 v[92:95], v[172:175], v[184:187], v[92:95]
	s_waitcnt lgkmcnt(0)
	v_mfma_f32_16x16x32_bf16 v[68:71], v[168:171], v[188:191], v[68:71]
	ds_read_b128 v[168:171], v192 offset:12800
	v_mfma_f32_16x16x32_bf16 v[60:63], v[172:175], v[188:191], v[60:63]
	ds_read_b128 v[172:175], v192 offset:14080
	s_waitcnt lgkmcnt(1)
	v_mfma_f32_16x16x32_bf16 v[140:143], v[168:171], v[176:179], v[140:143]
	s_waitcnt lgkmcnt(0)
	v_mfma_f32_16x16x32_bf16 v[136:139], v[172:175], v[176:179], v[136:139]
	v_mfma_f32_16x16x32_bf16 v[116:119], v[168:171], v[180:183], v[116:119]
	v_mfma_f32_16x16x32_bf16 v[108:111], v[172:175], v[180:183], v[108:111]
	v_mfma_f32_16x16x32_bf16 v[84:87], v[168:171], v[184:187], v[84:87]
	v_mfma_f32_16x16x32_bf16 v[76:79], v[172:175], v[184:187], v[76:79]
	v_mfma_f32_16x16x32_bf16 v[52:55], v[168:171], v[188:191], v[52:55]
	ds_read_b128 v[168:171], v192 offset:15360
	v_mfma_f32_16x16x32_bf16 v[44:47], v[172:175], v[188:191], v[44:47]
	ds_read_b128 v[172:175], v192 offset:16640
	s_waitcnt lgkmcnt(1)
	v_mfma_f32_16x16x32_bf16 v[124:127], v[168:171], v[176:179], v[124:127]
	s_waitcnt lgkmcnt(0)
	v_mfma_f32_16x16x32_bf16 v[120:123], v[172:175], v[176:179], v[120:123]
	v_mfma_f32_16x16x32_bf16 v[96:99], v[168:171], v[180:183], v[96:99]
	v_mfma_f32_16x16x32_bf16 v[88:91], v[172:175], v[180:183], v[88:91]
	v_mfma_f32_16x16x32_bf16 v[64:67], v[168:171], v[184:187], v[64:67]
	v_mfma_f32_16x16x32_bf16 v[56:59], v[172:175], v[184:187], v[56:59]
	v_mfma_f32_16x16x32_bf16 v[36:39], v[168:171], v[188:191], v[36:39]
	ds_read_b128 v[168:171], v192 offset:17920
	v_mfma_f32_16x16x32_bf16 v[32:35], v[172:175], v[188:191], v[32:35]
	ds_read_b128 v[172:175], v192 offset:19200
	s_waitcnt lgkmcnt(1)
	v_mfma_f32_16x16x32_bf16 v[112:115], v[168:171], v[176:179], v[112:115]
	s_waitcnt lgkmcnt(0)
	v_mfma_f32_16x16x32_bf16 v[104:107], v[172:175], v[176:179], v[104:107]
	v_mfma_f32_16x16x32_bf16 v[80:83], v[168:171], v[180:183], v[80:83]
	v_mfma_f32_16x16x32_bf16 v[72:75], v[172:175], v[180:183], v[72:75]
	v_mfma_f32_16x16x32_bf16 v[48:51], v[168:171], v[184:187], v[48:51]
	v_mfma_f32_16x16x32_bf16 v[40:43], v[172:175], v[184:187], v[40:43]
	v_mfma_f32_16x16x32_bf16 v[28:31], v[168:171], v[188:191], v[28:31]
	v_mfma_f32_16x16x32_bf16 v[24:27], v[172:175], v[188:191], v[24:27]
	s_setprio 0
	v_lshl_add_u64 v[160:161], v[160:161], 0, s[20:21]
	s_cmpk_eq_i32 s50, 0x56
	v_lshl_add_u64 v[162:163], v[162:163], 0, 64
	s_barrier
	s_cbranch_scc0 .LBB0_718
	s_waitcnt vmcnt(0)
	ds_write_b128 v155, v[0:3] offset:30720
	ds_write_b128 v155, v[4:7] offset:35840
	ds_write_b128 v155, v[8:11] offset:40960
	ds_write_b128 v155, v[12:15] offset:46080
	ds_write_b128 v155, v[16:19] offset:51200
	ds_write_b128 v155, v[20:23] offset:56320
	v_add_u32_e32 v155, v166, v167
	s_setprio 1
	v_add_u32_e32 v165, v165, v167
	ds_read_b128 v[160:163], v165 offset:10240
	ds_read_b128 v[166:169], v165 offset:11520
	ds_read_b128 v[170:173], v155
	ds_read_b128 v[174:177], v155 offset:1280
	ds_read_b128 v[178:181], v155 offset:2560
	ds_read_b128 v[182:185], v155 offset:3840
	s_waitcnt lgkmcnt(3)
	v_mfma_f32_16x16x32_bf16 v[148:151], v[160:163], v[170:173], v[148:151]
	v_mfma_f32_16x16x32_bf16 v[144:147], v[166:169], v[170:173], v[144:147]
	s_waitcnt lgkmcnt(2)
	v_mfma_f32_16x16x32_bf16 v[132:135], v[160:163], v[174:177], v[132:135]
	v_mfma_f32_16x16x32_bf16 v[128:131], v[166:169], v[174:177], v[128:131]
	s_waitcnt lgkmcnt(1)
	v_mfma_f32_16x16x32_bf16 v[100:103], v[160:163], v[178:181], v[100:103]
	v_mfma_f32_16x16x32_bf16 v[92:95], v[166:169], v[178:181], v[92:95]
	s_waitcnt lgkmcnt(0)
	v_mfma_f32_16x16x32_bf16 v[68:71], v[160:163], v[182:185], v[68:71]
	ds_read_b128 v[160:163], v165 offset:12800
	v_mfma_f32_16x16x32_bf16 v[60:63], v[166:169], v[182:185], v[60:63]
	ds_read_b128 v[166:169], v165 offset:14080
	s_waitcnt lgkmcnt(1)
	v_mfma_f32_16x16x32_bf16 v[186:189], v[160:163], v[170:173], v[140:143]
	s_waitcnt lgkmcnt(0)
; #define G_LOAD(kt_) do { \
;     if constexpr (AF32) { _Pragma("unroll") for (int i = 0; i < 4; ++i) ld16_sc1(ra[i], Af + (size_t)i * 32 * lda + (kt_) * 32); } \
;     else { _Pragma("unroll") for (int i = 0; i < 2; ++i) ld16_sc1(rab[i], Ab + (size_t)i * 64 * lda + (kt_) * 32); } \
;     _Pragma("unroll") for (int i = 0; i < 4; ++i) ld16_sc1(rb[i], Bp + (size_t)(kt_) * bstep + i * 2048); } while (0)
; template <bool AF32, class Epi>
; __device__ __forceinline__ void gemm_tile(unsigned char* smem, const void* Ap, int lda, const bf16_t* WT, int N, int K, const Epi& epi, int m0, int n0,
;                                           GPre& pr, bool preloaded, const void* nAp, int nn0, bool has_next) {
;     ...
;   for (int kt = 0; kt < nk; ++kt) {
;     const int cur = kt & 1;
;     if (kt + 1 < nk) G_STORE(cur ^ 1);
;     if (kt + 2 < nk) G_LOAD(kt + 2);
;     const bf16_t* a_s = sbase + cur * G_STAGE + (wr * 64 + l15) * GLD + quad * 8;
;     const bf16_t* b_s = sbase + cur * G_STAGE + 128 * GLD + (wc * 128 + l15) * GLD + quad * 8;
;     __builtin_amdgcn_s_setprio(1);
;     bf16x8 af[4];
; #pragma unroll
;     for (int m = 0; m < 4; ++m) af[m] = *(const bf16x8*)(a_s + m * 16 * GLD);
; #pragma unroll
;     for (int nh = 0; nh < 4; ++nh) {
;       bf16x8 bfr[2];
; #pragma unroll
;       for (int n2 = 0; n2 < 2; ++n2) bfr[n2] = *(const bf16x8*)(b_s + (nh * 2 + n2) * 16 * GLD);
; #pragma unroll
;       for (int m = 0; m < 4; ++m)
; #pragma unroll
;         for (int n2 = 0; n2 < 2; ++n2) acc[m][nh * 2 + n2] = __builtin_amdgcn_mfma_f32_16x16x32_bf16(bfr[n2], af[m], acc[m][nh * 2 + n2], 0, 0, 0);
;     }
;     __builtin_amdgcn_s_setprio(0);
;     __syncthreads();
;   }
;   if (has_next) {
;     const float* Af = (const float*)nAp + (size_t)(tid >> 3) * lda + (tid & 7) * 4;
;     const bf16_t* Ab = (const bf16_t*)nAp + (size_t)(tid >> 2) * lda + (tid & 3) * 8;
;     const bf16_t* Bp = WT + (size_t)nn0 * 32 + tid * 8;
;     G_LOAD(0);
;   }
	v_mfma_f32_16x16x32_bf16 v[136:139], v[166:169], v[170:173], v[136:139]
	v_mfma_f32_16x16x32_bf16 v[190:193], v[160:163], v[174:177], v[116:119]
	v_mfma_f32_16x16x32_bf16 v[194:197], v[166:169], v[174:177], v[108:111]
	v_mfma_f32_16x16x32_bf16 v[198:201], v[160:163], v[178:181], v[84:87]
	v_mfma_f32_16x16x32_bf16 v[202:205], v[166:169], v[178:181], v[76:79]
	v_mfma_f32_16x16x32_bf16 v[160:163], v[160:163], v[182:185], v[52:55]
	s_nop 2
	ds_read_b128 v[52:55], v165 offset:15360
	v_mfma_f32_16x16x32_bf16 v[166:169], v[166:169], v[182:185], v[44:47]
	s_nop 2
	ds_read_b128 v[44:47], v165 offset:16640
	s_waitcnt lgkmcnt(1)
	v_mfma_f32_16x16x32_bf16 v[124:127], v[52:55], v[170:173], v[124:127]
	s_waitcnt lgkmcnt(0)
	v_mfma_f32_16x16x32_bf16 v[120:123], v[44:47], v[170:173], v[120:123]
	v_mfma_f32_16x16x32_bf16 v[96:99], v[52:55], v[174:177], v[96:99]
	v_mfma_f32_16x16x32_bf16 v[88:91], v[44:47], v[174:177], v[88:91]
	v_mfma_f32_16x16x32_bf16 v[64:67], v[52:55], v[178:181], v[64:67]
	v_mfma_f32_16x16x32_bf16 v[56:59], v[44:47], v[178:181], v[56:59]
	v_mfma_f32_16x16x32_bf16 v[36:39], v[52:55], v[182:185], v[36:39]
	ds_read_b128 v[52:55], v165 offset:17920
	v_mfma_f32_16x16x32_bf16 v[32:35], v[44:47], v[182:185], v[32:35]
	ds_read_b128 v[44:47], v165 offset:19200
	s_waitcnt lgkmcnt(1)
	v_mfma_f32_16x16x32_bf16 v[28:31], v[52:55], v[182:185], v[28:31]
	s_waitcnt lgkmcnt(0)
	v_mfma_f32_16x16x32_bf16 v[24:27], v[44:47], v[182:185], v[24:27]
	v_mfma_f32_16x16x32_bf16 v[206:209], v[52:55], v[170:173], v[112:115]
	v_mfma_f32_16x16x32_bf16 v[170:173], v[44:47], v[170:173], v[104:107]
	v_mfma_f32_16x16x32_bf16 v[212:215], v[52:55], v[174:177], v[80:83]
	v_mfma_f32_16x16x32_bf16 v[174:177], v[44:47], v[174:177], v[72:75]
	v_mfma_f32_16x16x32_bf16 v[216:219], v[52:55], v[178:181], v[48:51]
	v_mfma_f32_16x16x32_bf16 v[178:181], v[44:47], v[178:181], v[40:43]
	s_setprio 0
	s_barrier
	s_setprio 1
	ds_read_b128 v[40:43], v165 offset:40960
	ds_read_b128 v[44:47], v165 offset:42240
	ds_read_b128 v[182:185], v155 offset:30720
	ds_read_b128 v[220:223], v155 offset:32000
	ds_read_b128 v[224:227], v155 offset:33280
	ds_read_b128 v[228:231], v155 offset:34560
	s_waitcnt lgkmcnt(3)
	v_mfma_f32_16x16x32_bf16 v[148:151], v[40:43], v[182:185], v[148:151]
	s_waitcnt lgkmcnt(2)
	v_mfma_f32_16x16x32_bf16 v[116:119], v[40:43], v[220:223], v[132:135]
	s_waitcnt lgkmcnt(1)
	v_mfma_f32_16x16x32_bf16 v[84:87], v[40:43], v[224:227], v[100:103]
	s_waitcnt lgkmcnt(0)
	v_mfma_f32_16x16x32_bf16 v[52:55], v[40:43], v[228:231], v[68:71]
	ds_read_b128 v[40:43], v165 offset:43520
	v_mfma_f32_16x16x32_bf16 v[48:51], v[44:47], v[228:231], v[60:63]
	s_nop 2
	ds_read_b128 v[60:63], v165 offset:44800
	v_mfma_f32_16x16x32_bf16 v[140:143], v[44:47], v[182:185], v[144:147]
	v_mfma_f32_16x16x32_bf16 v[108:111], v[44:47], v[220:223], v[128:131]
	v_mfma_f32_16x16x32_bf16 v[80:83], v[44:47], v[224:227], v[92:95]
	s_waitcnt lgkmcnt(1)
	v_mfma_f32_16x16x32_bf16 v[144:147], v[40:43], v[182:185], v[186:189]
	s_nop 0
	ds_read_b128 v[92:95], v165 offset:46080
	s_waitcnt lgkmcnt(1)
	v_mfma_f32_16x16x32_bf16 v[136:139], v[60:63], v[182:185], v[136:139]
	v_mfma_f32_16x16x32_bf16 v[112:115], v[40:43], v[220:223], v[190:193]
	v_mfma_f32_16x16x32_bf16 v[104:107], v[60:63], v[220:223], v[194:197]
	v_mfma_f32_16x16x32_bf16 v[76:79], v[40:43], v[224:227], v[198:201]
	v_mfma_f32_16x16x32_bf16 v[72:75], v[60:63], v[224:227], v[202:205]
	v_mfma_f32_16x16x32_bf16 v[44:47], v[40:43], v[228:231], v[160:163]
	v_mfma_f32_16x16x32_bf16 v[40:43], v[60:63], v[228:231], v[166:169]
	ds_read_b128 v[60:63], v165 offset:47360
	s_nop 0
	ds_read_b128 v[160:163], v165 offset:48640
	ds_read_b128 v[166:169], v165 offset:49920
	s_waitcnt lgkmcnt(3)
	v_mfma_f32_16x16x32_bf16 v[132:135], v[92:95], v[182:185], v[124:127]
	s_waitcnt lgkmcnt(2)
	v_mfma_f32_16x16x32_bf16 v[128:131], v[60:63], v[182:185], v[120:123]
	v_mfma_f32_16x16x32_bf16 v[100:103], v[92:95], v[220:223], v[96:99]
	v_mfma_f32_16x16x32_bf16 v[96:99], v[60:63], v[220:223], v[88:91]
	v_mfma_f32_16x16x32_bf16 v[68:71], v[92:95], v[224:227], v[64:67]
	v_mfma_f32_16x16x32_bf16 v[64:67], v[60:63], v[224:227], v[56:59]
	v_mfma_f32_16x16x32_bf16 v[36:39], v[92:95], v[228:231], v[36:39]
	v_mfma_f32_16x16x32_bf16 v[32:35], v[60:63], v[228:231], v[32:35]
	s_waitcnt lgkmcnt(1)
	v_mfma_f32_16x16x32_bf16 v[124:127], v[160:163], v[182:185], v[206:209]
	s_waitcnt lgkmcnt(0)
	v_mfma_f32_16x16x32_bf16 v[120:123], v[166:169], v[182:185], v[170:173]
	v_mfma_f32_16x16x32_bf16 v[92:95], v[160:163], v[220:223], v[212:215]
	v_mfma_f32_16x16x32_bf16 v[88:91], v[166:169], v[220:223], v[174:177]
	v_mfma_f32_16x16x32_bf16 v[60:63], v[160:163], v[224:227], v[216:219]
	v_mfma_f32_16x16x32_bf16 v[56:59], v[166:169], v[224:227], v[178:181]
	v_mfma_f32_16x16x32_bf16 v[28:31], v[160:163], v[228:231], v[28:31]
	v_mfma_f32_16x16x32_bf16 v[24:27], v[166:169], v[228:231], v[24:27]
	s_and_b64 vcc, exec, s[46:47]
	s_barrier
	s_cbranch_vccz .LBB0_706
	s_mul_i32 s46, s67, 0xb0000
	s_mul_hi_i32 s3, s67, 0xb0000
	s_add_u32 s46, s2, s46
	s_addc_u32 s47, s33, s3
	s_lshl_b32 s50, s66, 8
	s_ashr_i32 s51, s50, 31
	v_lshl_add_u64 v[0:1], v[158:159], 1, s[46:47]
	s_lshl_b64 s[46:47], s[50:51], 6
	v_lshl_add_u64 v[4:5], v[0:1], 0, v[152:153]
	s_add_u32 s46, s54, s46
	s_addc_u32 s47, s55, s47
	global_load_dwordx4 v[0:3], v[4:5], off sc1
	v_lshl_add_u64 v[4:5], v[4:5], 0, s[10:11]
	global_load_dwordx4 v[4:7], v[4:5], off sc1
	v_lshl_add_u64 v[20:21], v[156:157], 1, s[46:47]
	global_load_dwordx4 v[8:11], v[20:21], off sc1
	v_lshl_add_u64 v[12:13], v[20:21], 0, s[12:13]
	global_load_dwordx4 v[12:15], v[12:13], off sc1
	v_lshl_add_u64 v[16:17], v[20:21], 0, s[14:15]
	global_load_dwordx4 v[16:19], v[16:17], off sc1
	v_lshl_add_u64 v[20:21], v[20:21], 0, s[16:17]
	global_load_dwordx4 v[20:23], v[20:21], off sc1
	s_branch .LBB0_706
